# first K-loop iteration peeled for the five compute-bound GEMMs: first MFMA of each accumulator takes C=0, the 128 v_mov of the tile header are gone
# speedup vs baseline: 1.0073x; 1.0032x over previous
; #define PG8_STAGE(bufoff, gbase, voff) do { _Pragma("unroll") for (int _i = 0; _i < 2; ++_i) \
;         __builtin_amdgcn_global_load_lds((const unsigned*)((const char*)(gbase) + (voff)[_i]), (LAS unsigned*)(lds + (bufoff) + ldsw + _i * 8192), 16, 0, 0); } while (0)
; #define PG8_LDA(dst, b, h) do { _Pragma("unroll") for (int m = 0; m < 4; ++m) _Pragma("unroll") for (int k = 0; k < 2; ++k) dst[m][k] = *(const LAS h16x8*)(lds + PG8_SA(b, h) + aoff + m * 2048 + k * 1024); } while (0)
; #define PG8_LDB(dst, b, h) do { _Pragma("unroll") for (int n = 0; n < 2; ++n) _Pragma("unroll") for (int k = 0; k < 2; ++k) dst[n][k] = *(const LAS h16x8*)(lds + PG8_SB(b, h) + boff + n * 2048 + k * 1024); } while (0)
; #define PG8_MMA(ai, bj, At, Bt_) do { __builtin_amdgcn_s_setprio(1); _Pragma("unroll") for (int m = 0; m < 4; ++m) _Pragma("unroll") for (int n = 0; n < 2; ++n) _Pragma("unroll") for (int k = 0; k < 2; ++k) \
;         acc[ai][bj][m][n] = __builtin_amdgcn_mfma_f32_16x16x32_f16(Bt_[n][k], At[m][k], acc[ai][bj][m][n], 0, 0, 0); __builtin_amdgcn_s_setprio(0); } while (0)
; #define PG8_WAIT_V(n) asm volatile("s_waitcnt vmcnt(" #n ")" ::: "memory")
; #define PG8_WAIT_L(n) asm volatile("s_waitcnt lgkmcnt(" #n ")" ::: "memory")
; #define PG8_BAR __builtin_amdgcn_s_barrier()
; #define PG8_SCHED __builtin_amdgcn_sched_barrier(0)
; template <class Epi, class AMap>
; __device__ __forceinline__ void gemm_phase(LAS unsigned char* lds, const AMap am, const int lda, const h16* Bt, const int ldb, const int M, const int N, const int K, const Epi& E) {
;     ...
; #pragma unroll
;             for (int m = 0; m < 4; ++m)
; #pragma unroll
;                 for (int n = 0; n < 2; ++n) acc[a][b][m][n] = (f32x4){0.f, 0.f, 0.f, 0.f};
;     ...
;             PG8_LDB(B0, 0, 0); PG8_SCHED; PG8_LDA(At, 0, 0); PG8_STAGE(PG8_SA(1, 1), a1 + hstepA, voffA);
;             PG8_WAIT_L(8); PG8_BAR; PG8_WAIT_L(0); PG8_MMA(0, 0, At, B0); PG8_BAR; PG8_SCHED;
;             PG8_LDB(B1, 0, 1); PG8_STAGE(PG8_SB(0, 0), b2, voffB);
;             PG8_BAR; PG8_WAIT_L(0); PG8_MMA(0, 1, At, B1); PG8_BAR;
;             PG8_LDA(At, 0, 1); PG8_STAGE(PG8_SA(0, 0), a2, voffA);
;             PG8_BAR; PG8_WAIT_L(0); PG8_MMA(1, 0, At, B0); PG8_BAR; PG8_SCHED;
;             PG8_STAGE(PG8_SB(0, 1), b2 + hstepB, voffB);
;             PG8_WAIT_V(6); PG8_BAR; PG8_MMA(1, 1, At, B1); PG8_BAR;
.LBB0_60:
	s_add_u32 s20, s26, 0x100
	s_addc_u32 s21, s27, 0
	s_mov_b32 s29, -2
	s_add_u32 s26, s22, 0x100
	s_addc_u32 s27, s23, 0
	s_add_i32 s51, 0, 0x10000
	v_add_u32_e32 v144, s51, v147
	ds_read_b128 v[140:143], v144
	ds_read_b128 v[150:153], v144 offset:1024
	ds_read_b128 v[154:157], v144 offset:2048
	ds_read_b128 v[158:161], v144 offset:3072
	s_cmpk_eq_i32 s29, 0x52
	s_cselect_b32 s45, s1, s27
	s_cselect_b32 s44, s0, s26
	s_cselect_b32 s43, s41, s21
	s_cselect_b32 s42, s40, s20
	v_lshl_add_u64 v[144:145], s[22:23], 0, v[136:137]
	s_add_i32 m0, s63, 0xc000
	ds_read_b128 v[162:165], v149
	ds_read_b128 v[166:169], v149 offset:1024
	ds_read_b128 v[170:173], v149 offset:2048
	ds_read_b128 v[174:177], v149 offset:3072
	ds_read_b128 v[178:181], v149 offset:4096
	ds_read_b128 v[182:185], v149 offset:5120
	ds_read_b128 v[186:189], v149 offset:6144
	ds_read_b128 v[190:193], v149 offset:7168
	global_load_lds_dwordx4 v[144:145], off
	v_lshl_add_u64 v[144:145], s[22:23], 0, v[138:139]
	s_add_i32 m0, s63, 0xe000
	s_nop 0
	global_load_lds_dwordx4 v[144:145], off
	s_waitcnt lgkmcnt(11)
	s_add_i32 s60, 0, 0x14000
	v_add_u32_e32 v144, s60, v147
	s_add_i32 s22, s51, s48
	ds_read_b128 v[194:197], v144
	ds_read_b128 v[198:201], v144 offset:1024
	ds_read_b128 v[202:205], v144 offset:2048
	ds_read_b128 v[220:223], v144 offset:3072
	s_waitcnt vmcnt(8) lgkmcnt(0)
	s_barrier
	v_mfma_f32_16x16x32_f16 v[126:129], v[140:143], v[162:165], 0
	v_mfma_f32_16x16x32_f16 v[122:125], v[154:157], v[162:165], 0
	v_mfma_f32_16x16x32_f16 v[110:113], v[140:143], v[170:173], 0
	v_mfma_f32_16x16x32_f16 v[106:109], v[154:157], v[170:173], 0
	v_mfma_f32_16x16x32_f16 v[94:97], v[140:143], v[178:181], 0
	v_mfma_f32_16x16x32_f16 v[90:93], v[154:157], v[178:181], 0
	v_mfma_f32_16x16x32_f16 v[78:81], v[140:143], v[186:189], 0
	v_mfma_f32_16x16x32_f16 v[74:77], v[154:157], v[186:189], 0
	v_mfma_f32_16x16x32_f16 v[126:129], v[150:153], v[166:169], v[126:129]
	v_mfma_f32_16x16x32_f16 v[122:125], v[158:161], v[166:169], v[122:125]
	v_mfma_f32_16x16x32_f16 v[110:113], v[150:153], v[174:177], v[110:113]
	v_mfma_f32_16x16x32_f16 v[106:109], v[158:161], v[174:177], v[106:109]
	v_mfma_f32_16x16x32_f16 v[94:97], v[150:153], v[182:185], v[94:97]
	v_mfma_f32_16x16x32_f16 v[90:93], v[158:161], v[182:185], v[90:93]
	v_mfma_f32_16x16x32_f16 v[78:81], v[150:153], v[190:193], v[78:81]
	v_mfma_f32_16x16x32_f16 v[74:77], v[158:161], v[190:193], v[74:77]
	v_mfma_f32_16x16x32_f16 v[118:121], v[194:197], v[162:165], 0
	v_mfma_f32_16x16x32_f16 v[114:117], v[202:205], v[162:165], 0
	v_mfma_f32_16x16x32_f16 v[102:105], v[194:197], v[170:173], 0
	v_mfma_f32_16x16x32_f16 v[98:101], v[202:205], v[170:173], 0
	v_mfma_f32_16x16x32_f16 v[86:89], v[194:197], v[178:181], 0
	v_mfma_f32_16x16x32_f16 v[82:85], v[202:205], v[178:181], 0
	v_mfma_f32_16x16x32_f16 v[70:73], v[194:197], v[186:189], 0
	v_mfma_f32_16x16x32_f16 v[66:69], v[202:205], v[186:189], 0
	v_mfma_f32_16x16x32_f16 v[118:121], v[198:201], v[166:169], v[118:121]
	v_mfma_f32_16x16x32_f16 v[114:117], v[220:223], v[166:169], v[114:117]
	v_mfma_f32_16x16x32_f16 v[102:105], v[198:201], v[174:177], v[102:105]
	v_mfma_f32_16x16x32_f16 v[98:101], v[220:223], v[174:177], v[98:101]
	v_mfma_f32_16x16x32_f16 v[86:89], v[198:201], v[182:185], v[86:89]
	v_mfma_f32_16x16x32_f16 v[82:85], v[220:223], v[182:185], v[82:85]
	v_mfma_f32_16x16x32_f16 v[70:73], v[198:201], v[190:193], v[70:73]
	v_mfma_f32_16x16x32_f16 v[66:69], v[220:223], v[190:193], v[66:69]
	s_barrier
	v_lshl_add_u64 v[144:145], s[42:43], 0, v[0:1]
	s_mov_b32 m0, s22
	v_lshl_add_u64 v[206:207], s[42:43], 0, v[134:135]
	global_load_lds_dwordx4 v[144:145], off
	s_add_i32 m0, s22, 0x2000
	s_nop 0
	global_load_lds_dwordx4 v[206:207], off
	s_mov_b32 m0, s63
	v_lshl_add_u64 v[212:213], s[44:45], 0, v[130:131]
	ds_read_b128 v[162:165], v149 offset:16384
	ds_read_b128 v[166:169], v149 offset:17408
	ds_read_b128 v[170:173], v149 offset:18432
	ds_read_b128 v[174:177], v149 offset:19456
	ds_read_b128 v[178:181], v149 offset:20480
	ds_read_b128 v[182:185], v149 offset:21504
	ds_read_b128 v[186:189], v149 offset:22528
	ds_read_b128 v[190:193], v149 offset:23552
	global_load_lds_dwordx4 v[212:213], off
	v_lshl_add_u64 v[214:215], s[44:45], 0, v[132:133]
	s_mov_b32 m0, s64
	s_nop 0
	global_load_lds_dwordx4 v[214:215], off
	s_add_u32 s22, s42, 0x158000
	s_addc_u32 s23, s43, 0
	s_add_i32 s51, s60, s48
	v_lshl_add_u64 v[232:233], s[22:23], 0, v[0:1]
	s_mov_b32 m0, s51
	s_nop 0
	global_load_lds_dwordx4 v[232:233], off
	v_lshl_add_u64 v[232:233], s[22:23], 0, v[134:135]
	s_add_i32 m0, s51, 0x2000
	s_nop 0
	global_load_lds_dwordx4 v[232:233], off
	s_waitcnt vmcnt(8) lgkmcnt(0)
	s_barrier
; #define PG8_STAGE(bufoff, gbase, voff) do { _Pragma("unroll") for (int _i = 0; _i < 2; ++_i) \
;         __builtin_amdgcn_global_load_lds((const unsigned*)((const char*)(gbase) + (voff)[_i]), (LAS unsigned*)(lds + (bufoff) + ldsw + _i * 8192), 16, 0, 0); } while (0)
; #define PG8_LDA(dst, b, h) do { _Pragma("unroll") for (int m = 0; m < 4; ++m) _Pragma("unroll") for (int k = 0; k < 2; ++k) dst[m][k] = *(const LAS h16x8*)(lds + PG8_SA(b, h) + aoff + m * 2048 + k * 1024); } while (0)
; #define PG8_LDB(dst, b, h) do { _Pragma("unroll") for (int n = 0; n < 2; ++n) _Pragma("unroll") for (int k = 0; k < 2; ++k) dst[n][k] = *(const LAS h16x8*)(lds + PG8_SB(b, h) + boff + n * 2048 + k * 1024); } while (0)
; #define PG8_MMA(ai, bj, At, Bt_) do { __builtin_amdgcn_s_setprio(1); _Pragma("unroll") for (int m = 0; m < 4; ++m) _Pragma("unroll") for (int n = 0; n < 2; ++n) _Pragma("unroll") for (int k = 0; k < 2; ++k) \
;         acc[ai][bj][m][n] = __builtin_amdgcn_mfma_f32_16x16x32_f16(Bt_[n][k], At[m][k], acc[ai][bj][m][n], 0, 0, 0); __builtin_amdgcn_s_setprio(0); } while (0)
; #define PG8_WAIT_V(n) asm volatile("s_waitcnt vmcnt(" #n ")" ::: "memory")
; template <class Epi, class AMap>
; __device__ __forceinline__ void gemm_phase(LAS unsigned char* lds, const AMap am, const int lda, const h16* Bt, const int ldb, const int M, const int N, const int K, const Epi& E) {
;     ...
;             PG8_WAIT_L(8); PG8_BAR; PG8_WAIT_L(0); PG8_MMA(0, 0, At, B0); PG8_BAR; PG8_SCHED;
;             PG8_LDB(B1, 0, 1); PG8_STAGE(PG8_SB(0, 0), b2, voffB);
;             PG8_BAR; PG8_WAIT_L(0); PG8_MMA(0, 1, At, B1); PG8_BAR;
;             PG8_LDA(At, 0, 1); PG8_STAGE(PG8_SA(0, 0), a2, voffA);
;             PG8_BAR; PG8_WAIT_L(0); PG8_MMA(1, 0, At, B0); PG8_BAR; PG8_SCHED;
;             PG8_STAGE(PG8_SB(0, 1), b2 + hstepB, voffB);
;             PG8_WAIT_V(6); PG8_BAR; PG8_MMA(1, 1, At, B1); PG8_BAR;
;             PG8_LDB(B0, 1, 0); PG8_SCHED; PG8_LDA(At, 1, 0); PG8_STAGE(PG8_SA(0, 1), a2 + hstepA, voffA);
;             PG8_WAIT_L(8); PG8_BAR; PG8_WAIT_L(0); PG8_MMA(0, 0, At, B0); PG8_BAR; PG8_SCHED;
;             PG8_LDB(B1, 1, 1); PG8_STAGE(PG8_SB(1, 0), b3, voffB);
;             PG8_BAR; PG8_WAIT_L(0); PG8_MMA(0, 1, At, B1); PG8_BAR;
;             PG8_LDA(At, 1, 1); PG8_STAGE(PG8_SA(1, 0), a3, voffA);
;             PG8_BAR; PG8_WAIT_L(0); PG8_MMA(1, 0, At, B0); PG8_BAR; PG8_SCHED;
	v_mfma_f32_16x16x32_f16 v[62:65], v[140:143], v[162:165], 0
	v_mfma_f32_16x16x32_f16 v[58:61], v[154:157], v[162:165], 0
	v_mfma_f32_16x16x32_f16 v[46:49], v[140:143], v[170:173], 0
	v_mfma_f32_16x16x32_f16 v[42:45], v[154:157], v[170:173], 0
	v_mfma_f32_16x16x32_f16 v[30:33], v[140:143], v[178:181], 0
	v_mfma_f32_16x16x32_f16 v[26:29], v[154:157], v[178:181], 0
	v_mfma_f32_16x16x32_f16 v[14:17], v[140:143], v[186:189], 0
	v_mfma_f32_16x16x32_f16 v[10:13], v[154:157], v[186:189], 0
	v_mfma_f32_16x16x32_f16 v[62:65], v[150:153], v[166:169], v[62:65]
	v_mfma_f32_16x16x32_f16 v[58:61], v[158:161], v[166:169], v[58:61]
	v_mfma_f32_16x16x32_f16 v[46:49], v[150:153], v[174:177], v[46:49]
	v_mfma_f32_16x16x32_f16 v[42:45], v[158:161], v[174:177], v[42:45]
	v_mfma_f32_16x16x32_f16 v[30:33], v[150:153], v[182:185], v[30:33]
	v_mfma_f32_16x16x32_f16 v[26:29], v[158:161], v[182:185], v[26:29]
	v_mfma_f32_16x16x32_f16 v[14:17], v[150:153], v[190:193], v[14:17]
	v_mfma_f32_16x16x32_f16 v[10:13], v[158:161], v[190:193], v[10:13]
	v_mfma_f32_16x16x32_f16 v[54:57], v[194:197], v[162:165], 0
	v_mfma_f32_16x16x32_f16 v[50:53], v[202:205], v[162:165], 0
	v_mfma_f32_16x16x32_f16 v[38:41], v[194:197], v[170:173], 0
	v_mfma_f32_16x16x32_f16 v[34:37], v[202:205], v[170:173], 0
	v_mfma_f32_16x16x32_f16 v[22:25], v[194:197], v[178:181], 0
	v_mfma_f32_16x16x32_f16 v[18:21], v[202:205], v[178:181], 0
	v_mfma_f32_16x16x32_f16 v[6:9], v[194:197], v[186:189], 0
	v_mfma_f32_16x16x32_f16 v[2:5], v[202:205], v[186:189], 0
	v_mfma_f32_16x16x32_f16 v[54:57], v[198:201], v[166:169], v[54:57]
	v_mfma_f32_16x16x32_f16 v[50:53], v[220:223], v[166:169], v[50:53]
	v_mfma_f32_16x16x32_f16 v[38:41], v[198:201], v[174:177], v[38:41]
	v_mfma_f32_16x16x32_f16 v[34:37], v[220:223], v[174:177], v[34:37]
	v_mfma_f32_16x16x32_f16 v[22:25], v[198:201], v[182:185], v[22:25]
	v_mfma_f32_16x16x32_f16 v[18:21], v[220:223], v[182:185], v[18:21]
	v_mfma_f32_16x16x32_f16 v[6:9], v[198:201], v[190:193], v[6:9]
	v_mfma_f32_16x16x32_f16 v[2:5], v[220:223], v[190:193], v[2:5]
	s_barrier
	s_add_i32 s51, 0, 0x18000
	v_add_u32_e32 v234, s51, v147
	ds_read_b128 v[140:143], v234
	ds_read_b128 v[150:153], v234 offset:1024
	ds_read_b128 v[154:157], v234 offset:2048
	ds_read_b128 v[158:161], v234 offset:3072
	s_add_u32 s22, s44, 0x158000
	s_addc_u32 s23, s45, 0
	s_mov_b32 m0, s65
	v_lshl_add_u64 v[232:233], s[22:23], 0, v[130:131]
	ds_read_b128 v[162:165], v149 offset:32768
	ds_read_b128 v[166:169], v149 offset:33792
	ds_read_b128 v[170:173], v149 offset:34816
	ds_read_b128 v[174:177], v149 offset:35840
	ds_read_b128 v[178:181], v149 offset:36864
	ds_read_b128 v[182:185], v149 offset:37888
	ds_read_b128 v[186:189], v149 offset:38912
	ds_read_b128 v[190:193], v149 offset:39936
	global_load_lds_dwordx4 v[232:233], off
	v_lshl_add_u64 v[232:233], s[22:23], 0, v[132:133]
	s_mov_b32 m0, s68
	s_nop 0
	global_load_lds_dwordx4 v[232:233], off
	s_waitcnt lgkmcnt(11)
	s_add_i32 s44, 0, 0x1c000
	s_add_i32 s22, s51, s48
	v_add_u32_e32 v216, s44, v147
	v_lshl_add_u64 v[144:145], v[144:145], 0, s[92:93]
	s_mov_b32 m0, s22
	ds_read_b128 v[194:197], v216
	ds_read_b128 v[198:201], v216 offset:1024
	ds_read_b128 v[202:205], v216 offset:2048
	ds_read_b128 v[220:223], v216 offset:3072
	s_waitcnt vmcnt(8) lgkmcnt(0)
	s_barrier
	v_mfma_f32_16x16x32_f16 v[126:129], v[140:143], v[162:165], v[126:129]
	v_mfma_f32_16x16x32_f16 v[122:125], v[154:157], v[162:165], v[122:125]
	v_mfma_f32_16x16x32_f16 v[110:113], v[140:143], v[170:173], v[110:113]
	v_mfma_f32_16x16x32_f16 v[106:109], v[154:157], v[170:173], v[106:109]
	v_mfma_f32_16x16x32_f16 v[94:97], v[140:143], v[178:181], v[94:97]
	v_mfma_f32_16x16x32_f16 v[90:93], v[154:157], v[178:181], v[90:93]
	v_mfma_f32_16x16x32_f16 v[78:81], v[140:143], v[186:189], v[78:81]
	v_mfma_f32_16x16x32_f16 v[74:77], v[154:157], v[186:189], v[74:77]
	v_mfma_f32_16x16x32_f16 v[126:129], v[150:153], v[166:169], v[126:129]
	v_mfma_f32_16x16x32_f16 v[122:125], v[158:161], v[166:169], v[122:125]
	v_mfma_f32_16x16x32_f16 v[110:113], v[150:153], v[174:177], v[110:113]
	v_mfma_f32_16x16x32_f16 v[106:109], v[158:161], v[174:177], v[106:109]
	v_mfma_f32_16x16x32_f16 v[94:97], v[150:153], v[182:185], v[94:97]
	v_mfma_f32_16x16x32_f16 v[90:93], v[158:161], v[182:185], v[90:93]
	v_mfma_f32_16x16x32_f16 v[78:81], v[150:153], v[190:193], v[78:81]
	v_mfma_f32_16x16x32_f16 v[74:77], v[158:161], v[190:193], v[74:77]
	v_mfma_f32_16x16x32_f16 v[118:121], v[194:197], v[162:165], v[118:121]
	v_mfma_f32_16x16x32_f16 v[114:117], v[202:205], v[162:165], v[114:117]
	v_mfma_f32_16x16x32_f16 v[102:105], v[194:197], v[170:173], v[102:105]
	v_mfma_f32_16x16x32_f16 v[98:101], v[202:205], v[170:173], v[98:101]
	v_mfma_f32_16x16x32_f16 v[86:89], v[194:197], v[178:181], v[86:89]
	v_mfma_f32_16x16x32_f16 v[82:85], v[202:205], v[178:181], v[82:85]
	v_mfma_f32_16x16x32_f16 v[70:73], v[194:197], v[186:189], v[70:73]
	v_mfma_f32_16x16x32_f16 v[66:69], v[202:205], v[186:189], v[66:69]
	v_mfma_f32_16x16x32_f16 v[118:121], v[198:201], v[166:169], v[118:121]
	v_mfma_f32_16x16x32_f16 v[114:117], v[220:223], v[166:169], v[114:117]
	v_mfma_f32_16x16x32_f16 v[102:105], v[198:201], v[174:177], v[102:105]
	v_mfma_f32_16x16x32_f16 v[98:101], v[220:223], v[174:177], v[98:101]
	v_mfma_f32_16x16x32_f16 v[86:89], v[198:201], v[182:185], v[86:89]
	v_mfma_f32_16x16x32_f16 v[82:85], v[220:223], v[182:185], v[82:85]
	v_mfma_f32_16x16x32_f16 v[70:73], v[198:201], v[190:193], v[70:73]
	v_mfma_f32_16x16x32_f16 v[66:69], v[220:223], v[190:193], v[66:69]
	s_barrier
; #define PG8_STAGE(bufoff, gbase, voff) do { _Pragma("unroll") for (int _i = 0; _i < 2; ++_i) \
;         __builtin_amdgcn_global_load_lds((const unsigned*)((const char*)(gbase) + (voff)[_i]), (LAS unsigned*)(lds + (bufoff) + ldsw + _i * 8192), 16, 0, 0); } while (0)
; #define PG8_LDA(dst, b, h) do { _Pragma("unroll") for (int m = 0; m < 4; ++m) _Pragma("unroll") for (int k = 0; k < 2; ++k) dst[m][k] = *(const LAS h16x8*)(lds + PG8_SA(b, h) + aoff + m * 2048 + k * 1024); } while (0)
; #define PG8_MMA(ai, bj, At, Bt_) do { __builtin_amdgcn_s_setprio(1); _Pragma("unroll") for (int m = 0; m < 4; ++m) _Pragma("unroll") for (int n = 0; n < 2; ++n) _Pragma("unroll") for (int k = 0; k < 2; ++k) \
;         acc[ai][bj][m][n] = __builtin_amdgcn_mfma_f32_16x16x32_f16(Bt_[n][k], At[m][k], acc[ai][bj][m][n], 0, 0, 0); __builtin_amdgcn_s_setprio(0); } while (0)
; #define PG8_WAIT_V(n) asm volatile("s_waitcnt vmcnt(" #n ")" ::: "memory")
; #define PG8_WAIT_L(n) asm volatile("s_waitcnt lgkmcnt(" #n ")" ::: "memory")
; #define PG8_BAR __builtin_amdgcn_s_barrier()
; #define PG8_SCHED __builtin_amdgcn_sched_barrier(0)
; template <class Epi, class AMap>
; __device__ __forceinline__ void gemm_phase(LAS unsigned char* lds, const AMap am, const int lda, const h16* Bt, const int ldb, const int M, const int N, const int K, const Epi& E) {
;     ...
;             PG8_LDA(At, 1, 1); PG8_STAGE(PG8_SA(1, 0), a3, voffA);
;             PG8_BAR; PG8_WAIT_L(0); PG8_MMA(1, 0, At, B0); PG8_BAR; PG8_SCHED;
;             PG8_STAGE(PG8_SB(1, 1), b3 + hstepB, voffB);
;             PG8_WAIT_V(6); PG8_BAR; PG8_MMA(1, 1, At, B1); PG8_BAR;
	global_load_lds_dwordx4 v[144:145], off
	v_lshl_add_u64 v[144:145], v[206:207], 0, s[92:93]
	s_add_i32 m0, s22, 0x2000
	s_nop 0
	global_load_lds_dwordx4 v[144:145], off
	s_mov_b32 m0, s69
	v_lshl_add_u64 v[144:145], v[212:213], 0, s[92:93]
	ds_read_b128 v[162:165], v149 offset:49152
	ds_read_b128 v[166:169], v149 offset:50176
	ds_read_b128 v[170:173], v149 offset:51200
	ds_read_b128 v[174:177], v149 offset:52224
	ds_read_b128 v[178:181], v149 offset:53248
	ds_read_b128 v[182:185], v149 offset:54272
	ds_read_b128 v[186:189], v149 offset:55296
	ds_read_b128 v[190:193], v149 offset:56320
	global_load_lds_dwordx4 v[144:145], off
	v_lshl_add_u64 v[144:145], v[214:215], 0, s[92:93]
	s_mov_b32 m0, s70
	s_nop 0
	global_load_lds_dwordx4 v[144:145], off
	s_add_u32 s22, s42, 0x158080
	s_addc_u32 s23, s43, 0
	s_add_i32 s42, s44, s48
	v_lshl_add_u64 v[232:233], s[22:23], 0, v[0:1]
	s_mov_b32 m0, s42
	s_nop 0
	global_load_lds_dwordx4 v[232:233], off
	v_lshl_add_u64 v[232:233], s[22:23], 0, v[134:135]
	s_add_i32 m0, s42, 0x2000
	s_nop 0
	global_load_lds_dwordx4 v[232:233], off
	s_add_i32 s29, s29, 2
	s_add_u32 s20, s20, 0x100
	s_addc_u32 s21, s21, 0
	s_cmpk_gt_u32 s29, 0x53
	s_mov_b64 s[22:23], s[26:27]
	s_waitcnt vmcnt(8) lgkmcnt(0)
	s_barrier
	v_mfma_f32_16x16x32_f16 v[62:65], v[140:143], v[162:165], v[62:65]
	v_mfma_f32_16x16x32_f16 v[58:61], v[154:157], v[162:165], v[58:61]
	v_mfma_f32_16x16x32_f16 v[46:49], v[140:143], v[170:173], v[46:49]
	v_mfma_f32_16x16x32_f16 v[42:45], v[154:157], v[170:173], v[42:45]
	v_mfma_f32_16x16x32_f16 v[30:33], v[140:143], v[178:181], v[30:33]
	v_mfma_f32_16x16x32_f16 v[26:29], v[154:157], v[178:181], v[26:29]
	v_mfma_f32_16x16x32_f16 v[14:17], v[140:143], v[186:189], v[14:17]
	v_mfma_f32_16x16x32_f16 v[10:13], v[154:157], v[186:189], v[10:13]
	v_mfma_f32_16x16x32_f16 v[62:65], v[150:153], v[166:169], v[62:65]
	v_mfma_f32_16x16x32_f16 v[58:61], v[158:161], v[166:169], v[58:61]
	v_mfma_f32_16x16x32_f16 v[46:49], v[150:153], v[174:177], v[46:49]
	v_mfma_f32_16x16x32_f16 v[42:45], v[158:161], v[174:177], v[42:45]
	v_mfma_f32_16x16x32_f16 v[30:33], v[150:153], v[182:185], v[30:33]
	v_mfma_f32_16x16x32_f16 v[26:29], v[158:161], v[182:185], v[26:29]
	v_mfma_f32_16x16x32_f16 v[14:17], v[150:153], v[190:193], v[14:17]
	v_mfma_f32_16x16x32_f16 v[10:13], v[158:161], v[190:193], v[10:13]
	v_mfma_f32_16x16x32_f16 v[54:57], v[194:197], v[162:165], v[54:57]
	v_mfma_f32_16x16x32_f16 v[50:53], v[202:205], v[162:165], v[50:53]
	v_mfma_f32_16x16x32_f16 v[38:41], v[194:197], v[170:173], v[38:41]
	v_mfma_f32_16x16x32_f16 v[34:37], v[202:205], v[170:173], v[34:37]
	v_mfma_f32_16x16x32_f16 v[22:25], v[194:197], v[178:181], v[22:25]
	v_mfma_f32_16x16x32_f16 v[18:21], v[202:205], v[178:181], v[18:21]
	v_mfma_f32_16x16x32_f16 v[6:9], v[194:197], v[186:189], v[6:9]
	v_mfma_f32_16x16x32_f16 v[2:5], v[202:205], v[186:189], v[2:5]
	v_mfma_f32_16x16x32_f16 v[54:57], v[198:201], v[166:169], v[54:57]
	v_mfma_f32_16x16x32_f16 v[50:53], v[220:223], v[166:169], v[50:53]
	v_mfma_f32_16x16x32_f16 v[38:41], v[198:201], v[174:177], v[38:41]
	v_mfma_f32_16x16x32_f16 v[34:37], v[220:223], v[174:177], v[34:37]
	v_mfma_f32_16x16x32_f16 v[22:25], v[198:201], v[182:185], v[22:25]
	v_mfma_f32_16x16x32_f16 v[18:21], v[220:223], v[182:185], v[18:21]
	v_mfma_f32_16x16x32_f16 v[6:9], v[198:201], v[190:193], v[6:9]
	v_mfma_f32_16x16x32_f16 v[2:5], v[220:223], v[190:193], v[2:5]
	s_barrier
	s_cbranch_scc1 .Lg4x_61
.LBB0_61:
	s_add_u32 s26, s22, 0x100
	s_addc_u32 s27, s23, 0
	s_add_i32 s51, 0, 0x10000
	v_add_u32_e32 v144, s51, v147
	ds_read_b128 v[140:143], v144
	ds_read_b128 v[150:153], v144 offset:1024
	ds_read_b128 v[154:157], v144 offset:2048
	ds_read_b128 v[158:161], v144 offset:3072
	s_cmpk_eq_i32 s29, 0x52
	s_cselect_b32 s45, s1, s27
	s_cselect_b32 s44, s0, s26
	s_cselect_b32 s43, s41, s21
	s_cselect_b32 s42, s40, s20
	v_lshl_add_u64 v[144:145], s[22:23], 0, v[136:137]
	s_add_i32 m0, s63, 0xc000
	ds_read_b128 v[162:165], v149
	ds_read_b128 v[166:169], v149 offset:1024
	ds_read_b128 v[170:173], v149 offset:2048
	ds_read_b128 v[174:177], v149 offset:3072
	ds_read_b128 v[178:181], v149 offset:4096
	ds_read_b128 v[182:185], v149 offset:5120
	ds_read_b128 v[186:189], v149 offset:6144
	ds_read_b128 v[190:193], v149 offset:7168
	global_load_lds_dwordx4 v[144:145], off
	v_lshl_add_u64 v[144:145], s[22:23], 0, v[138:139]
	s_add_i32 m0, s63, 0xe000
	s_nop 0
	global_load_lds_dwordx4 v[144:145], off
	s_waitcnt lgkmcnt(11)
	s_add_i32 s60, 0, 0x14000
	v_add_u32_e32 v144, s60, v147
	s_add_i32 s22, s51, s48
	ds_read_b128 v[194:197], v144
	ds_read_b128 v[198:201], v144 offset:1024
	ds_read_b128 v[202:205], v144 offset:2048
	ds_read_b128 v[220:223], v144 offset:3072
	s_waitcnt vmcnt(8) lgkmcnt(0)
	s_barrier
; #define PG8_STAGE(bufoff, gbase, voff) do { _Pragma("unroll") for (int _i = 0; _i < 2; ++_i) \
;         __builtin_amdgcn_global_load_lds((const unsigned*)((const char*)(gbase) + (voff)[_i]), (LAS unsigned*)(lds + (bufoff) + ldsw + _i * 8192), 16, 0, 0); } while (0)
; #define PG8_LDA(dst, b, h) do { _Pragma("unroll") for (int m = 0; m < 4; ++m) _Pragma("unroll") for (int k = 0; k < 2; ++k) dst[m][k] = *(const LAS h16x8*)(lds + PG8_SA(b, h) + aoff + m * 2048 + k * 1024); } while (0)
; #define PG8_LDB(dst, b, h) do { _Pragma("unroll") for (int n = 0; n < 2; ++n) _Pragma("unroll") for (int k = 0; k < 2; ++k) dst[n][k] = *(const LAS h16x8*)(lds + PG8_SB(b, h) + boff + n * 2048 + k * 1024); } while (0)
; #define PG8_MMA(ai, bj, At, Bt_) do { __builtin_amdgcn_s_setprio(1); _Pragma("unroll") for (int m = 0; m < 4; ++m) _Pragma("unroll") for (int n = 0; n < 2; ++n) _Pragma("unroll") for (int k = 0; k < 2; ++k) \
;         acc[ai][bj][m][n] = __builtin_amdgcn_mfma_f32_16x16x32_f16(Bt_[n][k], At[m][k], acc[ai][bj][m][n], 0, 0, 0); __builtin_amdgcn_s_setprio(0); } while (0)
; #define PG8_WAIT_V(n) asm volatile("s_waitcnt vmcnt(" #n ")" ::: "memory")
; #define PG8_WAIT_L(n) asm volatile("s_waitcnt lgkmcnt(" #n ")" ::: "memory")
; #define PG8_BAR __builtin_amdgcn_s_barrier()
; #define PG8_SCHED __builtin_amdgcn_sched_barrier(0)
; template <class Epi, class AMap>
; __device__ __forceinline__ void gemm_phase(LAS unsigned char* lds, const AMap am, const int lda, const h16* Bt, const int ldb, const int M, const int N, const int K, const Epi& E) {
;     ...
;             PG8_LDB(B0, 0, 0); PG8_SCHED; PG8_LDA(At, 0, 0); PG8_STAGE(PG8_SA(1, 1), a1 + hstepA, voffA);
;             PG8_WAIT_L(8); PG8_BAR; PG8_WAIT_L(0); PG8_MMA(0, 0, At, B0); PG8_BAR; PG8_SCHED;
;             PG8_LDB(B1, 0, 1); PG8_STAGE(PG8_SB(0, 0), b2, voffB);
;             PG8_BAR; PG8_WAIT_L(0); PG8_MMA(0, 1, At, B1); PG8_BAR;
;             PG8_LDA(At, 0, 1); PG8_STAGE(PG8_SA(0, 0), a2, voffA);
;             PG8_BAR; PG8_WAIT_L(0); PG8_MMA(1, 0, At, B0); PG8_BAR; PG8_SCHED;
;             PG8_STAGE(PG8_SB(0, 1), b2 + hstepB, voffB);
;             PG8_WAIT_V(6); PG8_BAR; PG8_MMA(1, 1, At, B1); PG8_BAR;
	v_mfma_f32_16x16x32_f16 v[126:129], v[140:143], v[162:165], v[126:129]
	v_mfma_f32_16x16x32_f16 v[122:125], v[154:157], v[162:165], v[122:125]
	v_mfma_f32_16x16x32_f16 v[110:113], v[140:143], v[170:173], v[110:113]
	v_mfma_f32_16x16x32_f16 v[106:109], v[154:157], v[170:173], v[106:109]
	v_mfma_f32_16x16x32_f16 v[94:97], v[140:143], v[178:181], v[94:97]
	v_mfma_f32_16x16x32_f16 v[90:93], v[154:157], v[178:181], v[90:93]
	v_mfma_f32_16x16x32_f16 v[78:81], v[140:143], v[186:189], v[78:81]
	v_mfma_f32_16x16x32_f16 v[74:77], v[154:157], v[186:189], v[74:77]
	v_mfma_f32_16x16x32_f16 v[126:129], v[150:153], v[166:169], v[126:129]
	v_mfma_f32_16x16x32_f16 v[122:125], v[158:161], v[166:169], v[122:125]
	v_mfma_f32_16x16x32_f16 v[110:113], v[150:153], v[174:177], v[110:113]
	v_mfma_f32_16x16x32_f16 v[106:109], v[158:161], v[174:177], v[106:109]
	v_mfma_f32_16x16x32_f16 v[94:97], v[150:153], v[182:185], v[94:97]
	v_mfma_f32_16x16x32_f16 v[90:93], v[158:161], v[182:185], v[90:93]
	v_mfma_f32_16x16x32_f16 v[78:81], v[150:153], v[190:193], v[78:81]
	v_mfma_f32_16x16x32_f16 v[74:77], v[158:161], v[190:193], v[74:77]
	v_mfma_f32_16x16x32_f16 v[118:121], v[194:197], v[162:165], v[118:121]
	v_mfma_f32_16x16x32_f16 v[114:117], v[202:205], v[162:165], v[114:117]
	v_mfma_f32_16x16x32_f16 v[102:105], v[194:197], v[170:173], v[102:105]
	v_mfma_f32_16x16x32_f16 v[98:101], v[202:205], v[170:173], v[98:101]
	v_mfma_f32_16x16x32_f16 v[86:89], v[194:197], v[178:181], v[86:89]
	v_mfma_f32_16x16x32_f16 v[82:85], v[202:205], v[178:181], v[82:85]
	v_mfma_f32_16x16x32_f16 v[70:73], v[194:197], v[186:189], v[70:73]
	v_mfma_f32_16x16x32_f16 v[66:69], v[202:205], v[186:189], v[66:69]
	v_mfma_f32_16x16x32_f16 v[118:121], v[198:201], v[166:169], v[118:121]
	v_mfma_f32_16x16x32_f16 v[114:117], v[220:223], v[166:169], v[114:117]
	v_mfma_f32_16x16x32_f16 v[102:105], v[198:201], v[174:177], v[102:105]
	v_mfma_f32_16x16x32_f16 v[98:101], v[220:223], v[174:177], v[98:101]
	v_mfma_f32_16x16x32_f16 v[86:89], v[198:201], v[182:185], v[86:89]
	v_mfma_f32_16x16x32_f16 v[82:85], v[220:223], v[182:185], v[82:85]
	v_mfma_f32_16x16x32_f16 v[70:73], v[198:201], v[190:193], v[70:73]
	v_mfma_f32_16x16x32_f16 v[66:69], v[220:223], v[190:193], v[66:69]
	s_barrier
	v_lshl_add_u64 v[144:145], s[42:43], 0, v[0:1]
	s_mov_b32 m0, s22
	v_lshl_add_u64 v[206:207], s[42:43], 0, v[134:135]
	global_load_lds_dwordx4 v[144:145], off
	s_add_i32 m0, s22, 0x2000
	s_nop 0
	global_load_lds_dwordx4 v[206:207], off
	s_mov_b32 m0, s63
	v_lshl_add_u64 v[212:213], s[44:45], 0, v[130:131]
	ds_read_b128 v[162:165], v149 offset:16384
	ds_read_b128 v[166:169], v149 offset:17408
	ds_read_b128 v[170:173], v149 offset:18432
	ds_read_b128 v[174:177], v149 offset:19456
	ds_read_b128 v[178:181], v149 offset:20480
	ds_read_b128 v[182:185], v149 offset:21504
	ds_read_b128 v[186:189], v149 offset:22528
	ds_read_b128 v[190:193], v149 offset:23552
	global_load_lds_dwordx4 v[212:213], off
	v_lshl_add_u64 v[214:215], s[44:45], 0, v[132:133]
	s_mov_b32 m0, s64
	s_nop 0
	global_load_lds_dwordx4 v[214:215], off
	s_add_u32 s22, s42, 0x158000
	s_addc_u32 s23, s43, 0
	s_add_i32 s51, s60, s48
	v_lshl_add_u64 v[232:233], s[22:23], 0, v[0:1]
	s_mov_b32 m0, s51
	s_nop 0
	global_load_lds_dwordx4 v[232:233], off
	v_lshl_add_u64 v[232:233], s[22:23], 0, v[134:135]
	s_add_i32 m0, s51, 0x2000
	s_nop 0
	global_load_lds_dwordx4 v[232:233], off
	s_waitcnt vmcnt(8) lgkmcnt(0)
	s_barrier
	v_mfma_f32_16x16x32_f16 v[62:65], v[140:143], v[162:165], v[62:65]
	v_mfma_f32_16x16x32_f16 v[58:61], v[154:157], v[162:165], v[58:61]
	v_mfma_f32_16x16x32_f16 v[46:49], v[140:143], v[170:173], v[46:49]
	v_mfma_f32_16x16x32_f16 v[42:45], v[154:157], v[170:173], v[42:45]
	v_mfma_f32_16x16x32_f16 v[30:33], v[140:143], v[178:181], v[30:33]
	v_mfma_f32_16x16x32_f16 v[26:29], v[154:157], v[178:181], v[26:29]
	v_mfma_f32_16x16x32_f16 v[14:17], v[140:143], v[186:189], v[14:17]
	v_mfma_f32_16x16x32_f16 v[10:13], v[154:157], v[186:189], v[10:13]
	v_mfma_f32_16x16x32_f16 v[62:65], v[150:153], v[166:169], v[62:65]
	v_mfma_f32_16x16x32_f16 v[58:61], v[158:161], v[166:169], v[58:61]
	v_mfma_f32_16x16x32_f16 v[46:49], v[150:153], v[174:177], v[46:49]
	v_mfma_f32_16x16x32_f16 v[42:45], v[158:161], v[174:177], v[42:45]
	v_mfma_f32_16x16x32_f16 v[30:33], v[150:153], v[182:185], v[30:33]
	v_mfma_f32_16x16x32_f16 v[26:29], v[158:161], v[182:185], v[26:29]
	v_mfma_f32_16x16x32_f16 v[14:17], v[150:153], v[190:193], v[14:17]
	v_mfma_f32_16x16x32_f16 v[10:13], v[158:161], v[190:193], v[10:13]
	v_mfma_f32_16x16x32_f16 v[54:57], v[194:197], v[162:165], v[54:57]
	v_mfma_f32_16x16x32_f16 v[50:53], v[202:205], v[162:165], v[50:53]
	v_mfma_f32_16x16x32_f16 v[38:41], v[194:197], v[170:173], v[38:41]
	v_mfma_f32_16x16x32_f16 v[34:37], v[202:205], v[170:173], v[34:37]
	v_mfma_f32_16x16x32_f16 v[22:25], v[194:197], v[178:181], v[22:25]
	v_mfma_f32_16x16x32_f16 v[18:21], v[202:205], v[178:181], v[18:21]
	v_mfma_f32_16x16x32_f16 v[6:9], v[194:197], v[186:189], v[6:9]
	v_mfma_f32_16x16x32_f16 v[2:5], v[202:205], v[186:189], v[2:5]
	v_mfma_f32_16x16x32_f16 v[54:57], v[198:201], v[166:169], v[54:57]
	v_mfma_f32_16x16x32_f16 v[50:53], v[220:223], v[166:169], v[50:53]
	v_mfma_f32_16x16x32_f16 v[38:41], v[198:201], v[174:177], v[38:41]
	v_mfma_f32_16x16x32_f16 v[34:37], v[220:223], v[174:177], v[34:37]
	v_mfma_f32_16x16x32_f16 v[22:25], v[198:201], v[182:185], v[22:25]
	v_mfma_f32_16x16x32_f16 v[18:21], v[220:223], v[182:185], v[18:21]
	v_mfma_f32_16x16x32_f16 v[6:9], v[198:201], v[190:193], v[6:9]
	v_mfma_f32_16x16x32_f16 v[2:5], v[220:223], v[190:193], v[2:5]
	s_barrier
; #define PG8_STAGE(bufoff, gbase, voff) do { _Pragma("unroll") for (int _i = 0; _i < 2; ++_i) \
;         __builtin_amdgcn_global_load_lds((const unsigned*)((const char*)(gbase) + (voff)[_i]), (LAS unsigned*)(lds + (bufoff) + ldsw + _i * 8192), 16, 0, 0); } while (0)
; #define PG8_LDA(dst, b, h) do { _Pragma("unroll") for (int m = 0; m < 4; ++m) _Pragma("unroll") for (int k = 0; k < 2; ++k) dst[m][k] = *(const LAS h16x8*)(lds + PG8_SA(b, h) + aoff + m * 2048 + k * 1024); } while (0)
; #define PG8_LDB(dst, b, h) do { _Pragma("unroll") for (int n = 0; n < 2; ++n) _Pragma("unroll") for (int k = 0; k < 2; ++k) dst[n][k] = *(const LAS h16x8*)(lds + PG8_SB(b, h) + boff + n * 2048 + k * 1024); } while (0)
; #define PG8_MMA(ai, bj, At, Bt_) do { __builtin_amdgcn_s_setprio(1); _Pragma("unroll") for (int m = 0; m < 4; ++m) _Pragma("unroll") for (int n = 0; n < 2; ++n) _Pragma("unroll") for (int k = 0; k < 2; ++k) \
;         acc[ai][bj][m][n] = __builtin_amdgcn_mfma_f32_16x16x32_f16(Bt_[n][k], At[m][k], acc[ai][bj][m][n], 0, 0, 0); __builtin_amdgcn_s_setprio(0); } while (0)
; #define PG8_WAIT_V(n) asm volatile("s_waitcnt vmcnt(" #n ")" ::: "memory")
; #define PG8_WAIT_L(n) asm volatile("s_waitcnt lgkmcnt(" #n ")" ::: "memory")
; #define PG8_BAR __builtin_amdgcn_s_barrier()
; #define PG8_SCHED __builtin_amdgcn_sched_barrier(0)
; template <class Epi, class AMap>
; __device__ __forceinline__ void gemm_phase(LAS unsigned char* lds, const AMap am, const int lda, const h16* Bt, const int ldb, const int M, const int N, const int K, const Epi& E) {
;     ...
;             PG8_LDB(B0, 1, 0); PG8_SCHED; PG8_LDA(At, 1, 0); PG8_STAGE(PG8_SA(0, 1), a2 + hstepA, voffA);
;             PG8_WAIT_L(8); PG8_BAR; PG8_WAIT_L(0); PG8_MMA(0, 0, At, B0); PG8_BAR; PG8_SCHED;
;             PG8_LDB(B1, 1, 1); PG8_STAGE(PG8_SB(1, 0), b3, voffB);
;             PG8_BAR; PG8_WAIT_L(0); PG8_MMA(0, 1, At, B1); PG8_BAR;
;             PG8_LDA(At, 1, 1); PG8_STAGE(PG8_SA(1, 0), a3, voffA);
;             PG8_BAR; PG8_WAIT_L(0); PG8_MMA(1, 0, At, B0); PG8_BAR; PG8_SCHED;
;             PG8_STAGE(PG8_SB(1, 1), b3 + hstepB, voffB);
;             PG8_WAIT_V(6); PG8_BAR; PG8_MMA(1, 1, At, B1); PG8_BAR;
	s_add_i32 s51, 0, 0x18000
	v_add_u32_e32 v234, s51, v147
	ds_read_b128 v[140:143], v234
	ds_read_b128 v[150:153], v234 offset:1024
	ds_read_b128 v[154:157], v234 offset:2048
	ds_read_b128 v[158:161], v234 offset:3072
	s_add_u32 s22, s44, 0x158000
	s_addc_u32 s23, s45, 0
	s_mov_b32 m0, s65
	v_lshl_add_u64 v[232:233], s[22:23], 0, v[130:131]
	ds_read_b128 v[162:165], v149 offset:32768
	ds_read_b128 v[166:169], v149 offset:33792
	ds_read_b128 v[170:173], v149 offset:34816
	ds_read_b128 v[174:177], v149 offset:35840
	ds_read_b128 v[178:181], v149 offset:36864
	ds_read_b128 v[182:185], v149 offset:37888
	ds_read_b128 v[186:189], v149 offset:38912
	ds_read_b128 v[190:193], v149 offset:39936
	global_load_lds_dwordx4 v[232:233], off
	v_lshl_add_u64 v[232:233], s[22:23], 0, v[132:133]
	s_mov_b32 m0, s68
	s_nop 0
	global_load_lds_dwordx4 v[232:233], off
	s_waitcnt lgkmcnt(11)
	s_add_i32 s44, 0, 0x1c000
	s_add_i32 s22, s51, s48
	v_add_u32_e32 v216, s44, v147
	v_lshl_add_u64 v[144:145], v[144:145], 0, s[92:93]
	s_mov_b32 m0, s22
	ds_read_b128 v[194:197], v216
	ds_read_b128 v[198:201], v216 offset:1024
	ds_read_b128 v[202:205], v216 offset:2048
	ds_read_b128 v[220:223], v216 offset:3072
	s_waitcnt vmcnt(8) lgkmcnt(0)
	s_barrier
	v_mfma_f32_16x16x32_f16 v[126:129], v[140:143], v[162:165], v[126:129]
	v_mfma_f32_16x16x32_f16 v[122:125], v[154:157], v[162:165], v[122:125]
	v_mfma_f32_16x16x32_f16 v[110:113], v[140:143], v[170:173], v[110:113]
	v_mfma_f32_16x16x32_f16 v[106:109], v[154:157], v[170:173], v[106:109]
	v_mfma_f32_16x16x32_f16 v[94:97], v[140:143], v[178:181], v[94:97]
	v_mfma_f32_16x16x32_f16 v[90:93], v[154:157], v[178:181], v[90:93]
	v_mfma_f32_16x16x32_f16 v[78:81], v[140:143], v[186:189], v[78:81]
	v_mfma_f32_16x16x32_f16 v[74:77], v[154:157], v[186:189], v[74:77]
	v_mfma_f32_16x16x32_f16 v[126:129], v[150:153], v[166:169], v[126:129]
	v_mfma_f32_16x16x32_f16 v[122:125], v[158:161], v[166:169], v[122:125]
	v_mfma_f32_16x16x32_f16 v[110:113], v[150:153], v[174:177], v[110:113]
	v_mfma_f32_16x16x32_f16 v[106:109], v[158:161], v[174:177], v[106:109]
	v_mfma_f32_16x16x32_f16 v[94:97], v[150:153], v[182:185], v[94:97]
	v_mfma_f32_16x16x32_f16 v[90:93], v[158:161], v[182:185], v[90:93]
	v_mfma_f32_16x16x32_f16 v[78:81], v[150:153], v[190:193], v[78:81]
	v_mfma_f32_16x16x32_f16 v[74:77], v[158:161], v[190:193], v[74:77]
	v_mfma_f32_16x16x32_f16 v[118:121], v[194:197], v[162:165], v[118:121]
	v_mfma_f32_16x16x32_f16 v[114:117], v[202:205], v[162:165], v[114:117]
	v_mfma_f32_16x16x32_f16 v[102:105], v[194:197], v[170:173], v[102:105]
	v_mfma_f32_16x16x32_f16 v[98:101], v[202:205], v[170:173], v[98:101]
	v_mfma_f32_16x16x32_f16 v[86:89], v[194:197], v[178:181], v[86:89]
	v_mfma_f32_16x16x32_f16 v[82:85], v[202:205], v[178:181], v[82:85]
	v_mfma_f32_16x16x32_f16 v[70:73], v[194:197], v[186:189], v[70:73]
	v_mfma_f32_16x16x32_f16 v[66:69], v[202:205], v[186:189], v[66:69]
	v_mfma_f32_16x16x32_f16 v[118:121], v[198:201], v[166:169], v[118:121]
	v_mfma_f32_16x16x32_f16 v[114:117], v[220:223], v[166:169], v[114:117]
	v_mfma_f32_16x16x32_f16 v[102:105], v[198:201], v[174:177], v[102:105]
	v_mfma_f32_16x16x32_f16 v[98:101], v[220:223], v[174:177], v[98:101]
	v_mfma_f32_16x16x32_f16 v[86:89], v[198:201], v[182:185], v[86:89]
	v_mfma_f32_16x16x32_f16 v[82:85], v[220:223], v[182:185], v[82:85]
	v_mfma_f32_16x16x32_f16 v[70:73], v[198:201], v[190:193], v[70:73]
	v_mfma_f32_16x16x32_f16 v[66:69], v[220:223], v[190:193], v[66:69]
	s_barrier
	global_load_lds_dwordx4 v[144:145], off
	v_lshl_add_u64 v[144:145], v[206:207], 0, s[92:93]
	s_add_i32 m0, s22, 0x2000
	s_nop 0
	global_load_lds_dwordx4 v[144:145], off
	s_mov_b32 m0, s69
	v_lshl_add_u64 v[144:145], v[212:213], 0, s[92:93]
	ds_read_b128 v[162:165], v149 offset:49152
	ds_read_b128 v[166:169], v149 offset:50176
	ds_read_b128 v[170:173], v149 offset:51200
	ds_read_b128 v[174:177], v149 offset:52224
	ds_read_b128 v[178:181], v149 offset:53248
	ds_read_b128 v[182:185], v149 offset:54272
	ds_read_b128 v[186:189], v149 offset:55296
	ds_read_b128 v[190:193], v149 offset:56320
	global_load_lds_dwordx4 v[144:145], off
	v_lshl_add_u64 v[144:145], v[214:215], 0, s[92:93]
	s_mov_b32 m0, s70
	s_nop 0
	global_load_lds_dwordx4 v[144:145], off
	s_add_u32 s22, s42, 0x158080
	s_addc_u32 s23, s43, 0
	s_add_i32 s42, s44, s48
	v_lshl_add_u64 v[232:233], s[22:23], 0, v[0:1]
	s_mov_b32 m0, s42
	s_nop 0
	global_load_lds_dwordx4 v[232:233], off
	v_lshl_add_u64 v[232:233], s[22:23], 0, v[134:135]
	s_add_i32 m0, s42, 0x2000
	s_nop 0
	global_load_lds_dwordx4 v[232:233], off
	s_add_i32 s29, s29, 2
	s_add_u32 s20, s20, 0x100
	s_addc_u32 s21, s21, 0
	s_cmpk_gt_u32 s29, 0x53
	s_mov_b64 s[22:23], s[26:27]
	s_waitcnt vmcnt(8) lgkmcnt(0)
	s_barrier
	v_mfma_f32_16x16x32_f16 v[62:65], v[140:143], v[162:165], v[62:65]
	v_mfma_f32_16x16x32_f16 v[58:61], v[154:157], v[162:165], v[58:61]
	v_mfma_f32_16x16x32_f16 v[46:49], v[140:143], v[170:173], v[46:49]
	v_mfma_f32_16x16x32_f16 v[42:45], v[154:157], v[170:173], v[42:45]
	v_mfma_f32_16x16x32_f16 v[30:33], v[140:143], v[178:181], v[30:33]
	v_mfma_f32_16x16x32_f16 v[26:29], v[154:157], v[178:181], v[26:29]
	v_mfma_f32_16x16x32_f16 v[14:17], v[140:143], v[186:189], v[14:17]
	v_mfma_f32_16x16x32_f16 v[10:13], v[154:157], v[186:189], v[10:13]
	v_mfma_f32_16x16x32_f16 v[62:65], v[150:153], v[166:169], v[62:65]
	v_mfma_f32_16x16x32_f16 v[58:61], v[158:161], v[166:169], v[58:61]
	v_mfma_f32_16x16x32_f16 v[46:49], v[150:153], v[174:177], v[46:49]
	v_mfma_f32_16x16x32_f16 v[42:45], v[158:161], v[174:177], v[42:45]
	v_mfma_f32_16x16x32_f16 v[30:33], v[150:153], v[182:185], v[30:33]
	v_mfma_f32_16x16x32_f16 v[26:29], v[158:161], v[182:185], v[26:29]
	v_mfma_f32_16x16x32_f16 v[14:17], v[150:153], v[190:193], v[14:17]
	v_mfma_f32_16x16x32_f16 v[10:13], v[158:161], v[190:193], v[10:13]
	v_mfma_f32_16x16x32_f16 v[54:57], v[194:197], v[162:165], v[54:57]
	v_mfma_f32_16x16x32_f16 v[50:53], v[202:205], v[162:165], v[50:53]
	v_mfma_f32_16x16x32_f16 v[38:41], v[194:197], v[170:173], v[38:41]
	v_mfma_f32_16x16x32_f16 v[34:37], v[202:205], v[170:173], v[34:37]
	v_mfma_f32_16x16x32_f16 v[22:25], v[194:197], v[178:181], v[22:25]
	v_mfma_f32_16x16x32_f16 v[18:21], v[202:205], v[178:181], v[18:21]
	v_mfma_f32_16x16x32_f16 v[6:9], v[194:197], v[186:189], v[6:9]
	v_mfma_f32_16x16x32_f16 v[2:5], v[202:205], v[186:189], v[2:5]
	v_mfma_f32_16x16x32_f16 v[54:57], v[198:201], v[166:169], v[54:57]
	v_mfma_f32_16x16x32_f16 v[50:53], v[220:223], v[166:169], v[50:53]
	v_mfma_f32_16x16x32_f16 v[38:41], v[198:201], v[174:177], v[38:41]
	v_mfma_f32_16x16x32_f16 v[34:37], v[220:223], v[174:177], v[34:37]
	v_mfma_f32_16x16x32_f16 v[22:25], v[198:201], v[182:185], v[22:25]
	v_mfma_f32_16x16x32_f16 v[18:21], v[220:223], v[182:185], v[18:21]
	v_mfma_f32_16x16x32_f16 v[6:9], v[198:201], v[190:193], v[6:9]
	v_mfma_f32_16x16x32_f16 v[2:5], v[220:223], v[190:193], v[2:5]
	s_barrier
	s_cbranch_scc0 .LBB0_61
.Lg4x_61:
	s_cmpk_gt_u32 s46, 0xff
	s_cbranch_scc1 .Lgx0
	s_barrier

; #define PG8_STAGE(bufoff, gbase, voff) do { _Pragma("unroll") for (int _i = 0; _i < 2; ++_i) \
;         __builtin_amdgcn_global_load_lds((const unsigned*)((const char*)(gbase) + (voff)[_i]), (LAS unsigned*)(lds + (bufoff) + ldsw + _i * 8192), 16, 0, 0); } while (0)
; #define PG8_LDA(dst, b, h) do { _Pragma("unroll") for (int m = 0; m < 4; ++m) _Pragma("unroll") for (int k = 0; k < 2; ++k) dst[m][k] = *(const LAS h16x8*)(lds + PG8_SA(b, h) + aoff + m * 2048 + k * 1024); } while (0)
; #define PG8_LDB(dst, b, h) do { _Pragma("unroll") for (int n = 0; n < 2; ++n) _Pragma("unroll") for (int k = 0; k < 2; ++k) dst[n][k] = *(const LAS h16x8*)(lds + PG8_SB(b, h) + boff + n * 2048 + k * 1024); } while (0)
; #define PG8_WAIT_V(n) asm volatile("s_waitcnt vmcnt(" #n ")" ::: "memory")
; #define PG8_WAIT_L(n) asm volatile("s_waitcnt lgkmcnt(" #n ")" ::: "memory")
; #define PG8_BAR __builtin_amdgcn_s_barrier()
; #define PG8_SCHED __builtin_amdgcn_sched_barrier(0)
; template <class Epi, class AMap>
; __device__ __forceinline__ void gemm_phase(LAS unsigned char* lds, const AMap am, const int lda, const h16* Bt, const int ldb, const int M, const int N, const int K, const Epi& E) {
;     ...
;         const bool has_next = S.next(ui + 1, nxt);
;         const char* nA = has_next ? am(nxt.pn) + (size_t)nxt.pm * tstepA : cA; const char* nB = has_next ? (const char*)Bt + (size_t)nxt.pn * tstepB : cB;
; #pragma unroll 1
;         for (int t = 0; t < nt; t += 2) {
;             const bool last = (t == nt - 2);
;             const char* a1 = cA + (size_t)(t + 1) * kstep;
;             const char* a2 = last ? nA : cA + (size_t)(t + 2) * kstep; const char* b2 = last ? nB : cB + (size_t)(t + 2) * kstep;
;             const char* a3 = a2 + kstep; const char* b3 = b2 + kstep;
;             PG8_LDB(B0, 0, 0); PG8_SCHED; PG8_LDA(At, 0, 0); PG8_STAGE(PG8_SA(1, 1), a1 + hstepA, voffA);
;             PG8_WAIT_L(8); PG8_BAR; PG8_WAIT_L(0); PG8_MMA(0, 0, At, B0); PG8_BAR; PG8_SCHED;
;             PG8_LDB(B1, 0, 1); PG8_STAGE(PG8_SB(0, 0), b2, voffB);
;             PG8_BAR; PG8_WAIT_L(0); PG8_MMA(0, 1, At, B1); PG8_BAR;
;             PG8_LDA(At, 0, 1); PG8_STAGE(PG8_SA(0, 0), a2, voffA);
;             PG8_BAR; PG8_WAIT_L(0); PG8_MMA(1, 0, At, B0); PG8_BAR; PG8_SCHED;
;             PG8_STAGE(PG8_SB(0, 1), b2 + hstepB, voffB);
;             PG8_WAIT_V(6); PG8_BAR; PG8_MMA(1, 1, At, B1); PG8_BAR;
.LBB0_91:
	s_ashr_i32 s69, s68, 31
	s_lshl_b64 s[20:21], s[68:69], 20
	v_mov_b64_e32 v[2:3], 0xac0
	s_add_u32 s96, s94, s20
	v_cmp_lt_i64_e32 vcc, s[76:77], v[2:3]
	s_addc_u32 s97, s95, s21
	s_and_b64 s[20:21], vcc, exec
	s_cselect_b32 s69, s97, s27
	s_cselect_b32 s29, s96, s26
	s_ashr_i32 s73, s72, 31
	s_lshl_b64 s[20:21], s[72:73], 20
	s_add_u32 s76, s63, s20
	s_addc_u32 s77, s80, s21
	s_and_b64 s[20:21], vcc, exec
	s_cselect_b32 s73, s77, s49
	s_cselect_b32 s20, s76, s48
	s_add_u32 vcc_lo, s26, 0x80080
	s_addc_u32 vcc_hi, s27, 0
	s_add_u32 s21, s48, 0x100
	s_addc_u32 s66, s49, 0
	s_mov_b32 s60, -2
	s_add_u32 s0, vcc_lo, 0xfff80080
	s_addc_u32 s1, vcc_hi, -1
	s_add_i32 s67, 0, 0x10000
	v_add_u32_e32 v226, s67, v169
	ds_read_b128 v[66:69], v226
	ds_read_b128 v[70:73], v226 offset:1024
	ds_read_b128 v[74:77], v226 offset:2048
	ds_read_b128 v[78:81], v226 offset:3072
	s_cmp_eq_u32 s60, 28
	s_cselect_b32 s27, s69, s1
	s_cselect_b32 s26, s29, s0
	s_cselect_b32 s49, s73, s66
	s_cselect_b32 s48, s20, s21
	v_lshl_add_u64 v[192:193], vcc, 0, v[172:173]
	s_add_i32 m0, s81, 0xc000
	ds_read_b128 v[90:93], v195
	ds_read_b128 v[94:97], v195 offset:1024
	ds_read_b128 v[98:101], v195 offset:2048
	ds_read_b128 v[102:105], v195 offset:3072
	ds_read_b128 v[176:179], v195 offset:4096
	ds_read_b128 v[180:183], v195 offset:5120
	ds_read_b128 v[184:187], v195 offset:6144
	ds_read_b128 v[188:191], v195 offset:7168
	global_load_lds_dwordx4 v[192:193], off
	v_lshl_add_u64 v[192:193], vcc, 0, v[174:175]
	s_add_i32 m0, s81, 0xe000
	s_nop 0
	global_load_lds_dwordx4 v[192:193], off
	s_waitcnt lgkmcnt(11)
	s_add_i32 s65, 0, 0x14000
	v_add_u32_e32 v192, s65, v169
	s_add_i32 s0, s67, s64
	ds_read_b128 v[196:199], v192
	ds_read_b128 v[200:203], v192 offset:1024
	ds_read_b128 v[204:207], v192 offset:2048
	ds_read_b128 v[220:223], v192 offset:3072
	s_waitcnt vmcnt(8) lgkmcnt(0)
	s_barrier
	v_mfma_f32_16x16x32_f16 v[158:161], v[66:69], v[90:93], 0
	v_mfma_f32_16x16x32_f16 v[154:157], v[74:77], v[90:93], 0
	v_mfma_f32_16x16x32_f16 v[142:145], v[66:69], v[98:101], 0
	v_mfma_f32_16x16x32_f16 v[134:137], v[74:77], v[98:101], 0
	v_mfma_f32_16x16x32_f16 v[126:129], v[66:69], v[176:179], 0
	v_mfma_f32_16x16x32_f16 v[118:121], v[74:77], v[176:179], 0
	v_mfma_f32_16x16x32_f16 v[110:113], v[66:69], v[184:187], 0
	v_mfma_f32_16x16x32_f16 v[106:109], v[74:77], v[184:187], 0
	v_mfma_f32_16x16x32_f16 v[158:161], v[70:73], v[94:97], v[158:161]
	v_mfma_f32_16x16x32_f16 v[154:157], v[78:81], v[94:97], v[154:157]
	v_mfma_f32_16x16x32_f16 v[142:145], v[70:73], v[102:105], v[142:145]
	v_mfma_f32_16x16x32_f16 v[134:137], v[78:81], v[102:105], v[134:137]
	v_mfma_f32_16x16x32_f16 v[126:129], v[70:73], v[180:183], v[126:129]
	v_mfma_f32_16x16x32_f16 v[118:121], v[78:81], v[180:183], v[118:121]
	v_mfma_f32_16x16x32_f16 v[110:113], v[70:73], v[188:191], v[110:113]
	v_mfma_f32_16x16x32_f16 v[106:109], v[78:81], v[188:191], v[106:109]
	v_mfma_f32_16x16x32_f16 v[150:153], v[196:199], v[90:93], 0
	v_mfma_f32_16x16x32_f16 v[146:149], v[204:207], v[90:93], 0
	v_mfma_f32_16x16x32_f16 v[150:153], v[200:203], v[94:97], v[150:153]
	v_mfma_f32_16x16x32_f16 v[146:149], v[220:223], v[94:97], v[146:149]
	v_mfma_f32_16x16x32_f16 v[138:141], v[196:199], v[98:101], 0
	v_mfma_f32_16x16x32_f16 v[130:133], v[204:207], v[98:101], 0
	v_mfma_f32_16x16x32_f16 v[114:117], v[204:207], v[176:179], 0
	v_mfma_f32_16x16x32_f16 v[86:89], v[196:199], v[184:187], 0
	v_mfma_f32_16x16x32_f16 v[82:85], v[204:207], v[184:187], 0
	v_mfma_f32_16x16x32_f16 v[138:141], v[200:203], v[102:105], v[138:141]
	v_mfma_f32_16x16x32_f16 v[130:133], v[220:223], v[102:105], v[130:133]
	v_mfma_f32_16x16x32_f16 v[122:125], v[196:199], v[176:179], 0
	v_mfma_f32_16x16x32_f16 v[114:117], v[220:223], v[180:183], v[114:117]
	v_mfma_f32_16x16x32_f16 v[86:89], v[200:203], v[188:191], v[86:89]
	v_mfma_f32_16x16x32_f16 v[82:85], v[220:223], v[188:191], v[82:85]
	v_mfma_f32_16x16x32_f16 v[122:125], v[200:203], v[180:183], v[122:125]
	s_barrier
	v_lshl_add_u64 v[192:193], s[48:49], 0, v[0:1]
	s_mov_b32 m0, s0
	v_lshl_add_u64 v[212:213], s[48:49], 0, v[162:163]
	global_load_lds_dwordx4 v[192:193], off
	s_add_i32 m0, s0, 0x2000
	s_nop 0
	global_load_lds_dwordx4 v[212:213], off
	s_mov_b32 m0, s81
	v_lshl_add_u64 v[214:215], s[26:27], 0, v[166:167]
	ds_read_b128 v[90:93], v195 offset:16384
	ds_read_b128 v[94:97], v195 offset:17408
	ds_read_b128 v[98:101], v195 offset:18432
	ds_read_b128 v[102:105], v195 offset:19456
	ds_read_b128 v[176:179], v195 offset:20480
	ds_read_b128 v[180:183], v195 offset:21504
	ds_read_b128 v[184:187], v195 offset:22528
	ds_read_b128 v[188:191], v195 offset:23552
	global_load_lds_dwordx4 v[214:215], off
	v_lshl_add_u64 v[216:217], s[26:27], 0, v[164:165]
	s_mov_b32 m0, s82
	s_nop 0
	global_load_lds_dwordx4 v[216:217], off
	s_add_u32 s0, s48, 0x80000
	s_addc_u32 s1, s49, 0
	s_add_i32 s65, s65, s64
	v_lshl_add_u64 v[224:225], s[0:1], 0, v[0:1]
	s_mov_b32 m0, s65
	s_nop 0
	global_load_lds_dwordx4 v[224:225], off
	v_lshl_add_u64 v[224:225], s[0:1], 0, v[162:163]
	s_add_i32 m0, s65, 0x2000
	s_nop 0
	global_load_lds_dwordx4 v[224:225], off
	s_waitcnt vmcnt(8) lgkmcnt(0)
	s_barrier
; #define PG8_STAGE(bufoff, gbase, voff) do { _Pragma("unroll") for (int _i = 0; _i < 2; ++_i) \
;         __builtin_amdgcn_global_load_lds((const unsigned*)((const char*)(gbase) + (voff)[_i]), (LAS unsigned*)(lds + (bufoff) + ldsw + _i * 8192), 16, 0, 0); } while (0)
; #define PG8_LDA(dst, b, h) do { _Pragma("unroll") for (int m = 0; m < 4; ++m) _Pragma("unroll") for (int k = 0; k < 2; ++k) dst[m][k] = *(const LAS h16x8*)(lds + PG8_SA(b, h) + aoff + m * 2048 + k * 1024); } while (0)
; #define PG8_LDB(dst, b, h) do { _Pragma("unroll") for (int n = 0; n < 2; ++n) _Pragma("unroll") for (int k = 0; k < 2; ++k) dst[n][k] = *(const LAS h16x8*)(lds + PG8_SB(b, h) + boff + n * 2048 + k * 1024); } while (0)
; #define PG8_MMA(ai, bj, At, Bt_) do { __builtin_amdgcn_s_setprio(1); _Pragma("unroll") for (int m = 0; m < 4; ++m) _Pragma("unroll") for (int n = 0; n < 2; ++n) _Pragma("unroll") for (int k = 0; k < 2; ++k) \
;         acc[ai][bj][m][n] = __builtin_amdgcn_mfma_f32_16x16x32_f16(Bt_[n][k], At[m][k], acc[ai][bj][m][n], 0, 0, 0); __builtin_amdgcn_s_setprio(0); } while (0)
; #define PG8_WAIT_V(n) asm volatile("s_waitcnt vmcnt(" #n ")" ::: "memory")
; #define PG8_WAIT_L(n) asm volatile("s_waitcnt lgkmcnt(" #n ")" ::: "memory")
; #define PG8_BAR __builtin_amdgcn_s_barrier()
; #define PG8_SCHED __builtin_amdgcn_sched_barrier(0)
; template <class Epi, class AMap>
; __device__ __forceinline__ void gemm_phase(LAS unsigned char* lds, const AMap am, const int lda, const h16* Bt, const int ldb, const int M, const int N, const int K, const Epi& E) {
;     ...
;             PG8_WAIT_V(6); PG8_BAR; PG8_MMA(1, 1, At, B1); PG8_BAR;
;             PG8_LDB(B0, 1, 0); PG8_SCHED; PG8_LDA(At, 1, 0); PG8_STAGE(PG8_SA(0, 1), a2 + hstepA, voffA);
;             PG8_WAIT_L(8); PG8_BAR; PG8_WAIT_L(0); PG8_MMA(0, 0, At, B0); PG8_BAR; PG8_SCHED;
;             PG8_LDB(B1, 1, 1); PG8_STAGE(PG8_SB(1, 0), b3, voffB);
;             PG8_BAR; PG8_WAIT_L(0); PG8_MMA(0, 1, At, B1); PG8_BAR;
;             PG8_LDA(At, 1, 1); PG8_STAGE(PG8_SA(1, 0), a3, voffA);
;             PG8_BAR; PG8_WAIT_L(0); PG8_MMA(1, 0, At, B0); PG8_BAR; PG8_SCHED;
	v_mfma_f32_16x16x32_f16 v[62:65], v[66:69], v[90:93], 0
	v_mfma_f32_16x16x32_f16 v[58:61], v[74:77], v[90:93], 0
	v_mfma_f32_16x16x32_f16 v[46:49], v[66:69], v[98:101], 0
	v_mfma_f32_16x16x32_f16 v[38:41], v[74:77], v[98:101], 0
	v_mfma_f32_16x16x32_f16 v[30:33], v[66:69], v[176:179], 0
	v_mfma_f32_16x16x32_f16 v[22:25], v[74:77], v[176:179], 0
	v_mfma_f32_16x16x32_f16 v[14:17], v[66:69], v[184:187], 0
	v_mfma_f32_16x16x32_f16 v[10:13], v[74:77], v[184:187], 0
	v_mfma_f32_16x16x32_f16 v[62:65], v[70:73], v[94:97], v[62:65]
	v_mfma_f32_16x16x32_f16 v[58:61], v[78:81], v[94:97], v[58:61]
	v_mfma_f32_16x16x32_f16 v[46:49], v[70:73], v[102:105], v[46:49]
	v_mfma_f32_16x16x32_f16 v[38:41], v[78:81], v[102:105], v[38:41]
	v_mfma_f32_16x16x32_f16 v[30:33], v[70:73], v[180:183], v[30:33]
	v_mfma_f32_16x16x32_f16 v[22:25], v[78:81], v[180:183], v[22:25]
	v_mfma_f32_16x16x32_f16 v[14:17], v[70:73], v[188:191], v[14:17]
	v_mfma_f32_16x16x32_f16 v[10:13], v[78:81], v[188:191], v[10:13]
	v_mfma_f32_16x16x32_f16 v[54:57], v[196:199], v[90:93], 0
	v_mfma_f32_16x16x32_f16 v[50:53], v[204:207], v[90:93], 0
	v_mfma_f32_16x16x32_f16 v[42:45], v[196:199], v[98:101], 0
	v_mfma_f32_16x16x32_f16 v[34:37], v[204:207], v[98:101], 0
	v_mfma_f32_16x16x32_f16 v[26:29], v[196:199], v[176:179], 0
	v_mfma_f32_16x16x32_f16 v[18:21], v[204:207], v[176:179], 0
	v_mfma_f32_16x16x32_f16 v[6:9], v[196:199], v[184:187], 0
	v_mfma_f32_16x16x32_f16 v[2:5], v[204:207], v[184:187], 0
	v_mfma_f32_16x16x32_f16 v[54:57], v[200:203], v[94:97], v[54:57]
	v_mfma_f32_16x16x32_f16 v[50:53], v[220:223], v[94:97], v[50:53]
	v_mfma_f32_16x16x32_f16 v[42:45], v[200:203], v[102:105], v[42:45]
	v_mfma_f32_16x16x32_f16 v[34:37], v[220:223], v[102:105], v[34:37]
	v_mfma_f32_16x16x32_f16 v[26:29], v[200:203], v[180:183], v[26:29]
	v_mfma_f32_16x16x32_f16 v[18:21], v[220:223], v[180:183], v[18:21]
	v_mfma_f32_16x16x32_f16 v[6:9], v[200:203], v[188:191], v[6:9]
	v_mfma_f32_16x16x32_f16 v[2:5], v[220:223], v[188:191], v[2:5]
	s_barrier
	s_add_i32 s65, 0, 0x18000
	v_add_u32_e32 v226, s65, v169
	ds_read_b128 v[66:69], v226
	ds_read_b128 v[70:73], v226 offset:1024
	ds_read_b128 v[74:77], v226 offset:2048
	ds_read_b128 v[78:81], v226 offset:3072
	s_add_u32 s0, s26, 0x80000
	s_addc_u32 s1, s27, 0
	s_mov_b32 m0, s83
	v_lshl_add_u64 v[224:225], s[0:1], 0, v[166:167]
	ds_read_b128 v[90:93], v195 offset:32768
	ds_read_b128 v[94:97], v195 offset:33792
	ds_read_b128 v[98:101], v195 offset:34816
	ds_read_b128 v[102:105], v195 offset:35840
	ds_read_b128 v[176:179], v195 offset:36864
	ds_read_b128 v[180:183], v195 offset:37888
	ds_read_b128 v[184:187], v195 offset:38912
	ds_read_b128 v[188:191], v195 offset:39936
	global_load_lds_dwordx4 v[224:225], off
	v_lshl_add_u64 v[224:225], s[0:1], 0, v[164:165]
	s_mov_b32 m0, s50
	s_nop 0
	global_load_lds_dwordx4 v[224:225], off
	s_waitcnt lgkmcnt(11)
	s_add_i32 s26, 0, 0x1c000
	v_add_u32_e32 v226, s26, v169
	s_add_i32 s0, s65, s64
	ds_read_b128 v[196:199], v226
	ds_read_b128 v[200:203], v226 offset:1024
	ds_read_b128 v[204:207], v226 offset:2048
	ds_read_b128 v[220:223], v226 offset:3072
	s_waitcnt vmcnt(8) lgkmcnt(0)
	s_barrier
	v_mfma_f32_16x16x32_f16 v[158:161], v[66:69], v[90:93], v[158:161]
	v_mfma_f32_16x16x32_f16 v[158:161], v[70:73], v[94:97], v[158:161]
	v_mfma_f32_16x16x32_f16 v[154:157], v[74:77], v[90:93], v[154:157]
	v_mfma_f32_16x16x32_f16 v[154:157], v[78:81], v[94:97], v[154:157]
	v_mfma_f32_16x16x32_f16 v[142:145], v[66:69], v[98:101], v[142:145]
	v_mfma_f32_16x16x32_f16 v[134:137], v[74:77], v[98:101], v[134:137]
	v_mfma_f32_16x16x32_f16 v[126:129], v[66:69], v[176:179], v[126:129]
	v_mfma_f32_16x16x32_f16 v[118:121], v[74:77], v[176:179], v[118:121]
	v_mfma_f32_16x16x32_f16 v[110:113], v[66:69], v[184:187], v[110:113]
	v_mfma_f32_16x16x32_f16 v[106:109], v[74:77], v[184:187], v[106:109]
	v_mfma_f32_16x16x32_f16 v[142:145], v[70:73], v[102:105], v[142:145]
	v_mfma_f32_16x16x32_f16 v[134:137], v[78:81], v[102:105], v[134:137]
	v_mfma_f32_16x16x32_f16 v[126:129], v[70:73], v[180:183], v[126:129]
	v_mfma_f32_16x16x32_f16 v[118:121], v[78:81], v[180:183], v[118:121]
	v_mfma_f32_16x16x32_f16 v[110:113], v[70:73], v[188:191], v[110:113]
	v_mfma_f32_16x16x32_f16 v[106:109], v[78:81], v[188:191], v[106:109]
	v_mfma_f32_16x16x32_f16 v[146:149], v[204:207], v[90:93], v[146:149]
	v_mfma_f32_16x16x32_f16 v[150:153], v[196:199], v[90:93], v[150:153]
	v_mfma_f32_16x16x32_f16 v[146:149], v[220:223], v[94:97], v[146:149]
	v_mfma_f32_16x16x32_f16 v[138:141], v[196:199], v[98:101], v[138:141]
	v_mfma_f32_16x16x32_f16 v[150:153], v[200:203], v[94:97], v[150:153]
	v_mfma_f32_16x16x32_f16 v[138:141], v[200:203], v[102:105], v[138:141]
	v_mfma_f32_16x16x32_f16 v[130:133], v[204:207], v[98:101], v[130:133]
	v_mfma_f32_16x16x32_f16 v[130:133], v[220:223], v[102:105], v[130:133]
	v_mfma_f32_16x16x32_f16 v[122:125], v[196:199], v[176:179], v[122:125]
	v_mfma_f32_16x16x32_f16 v[122:125], v[200:203], v[180:183], v[122:125]
	v_mfma_f32_16x16x32_f16 v[114:117], v[204:207], v[176:179], v[114:117]
	v_mfma_f32_16x16x32_f16 v[86:89], v[196:199], v[184:187], v[86:89]
	v_mfma_f32_16x16x32_f16 v[82:85], v[204:207], v[184:187], v[82:85]
	v_mfma_f32_16x16x32_f16 v[114:117], v[220:223], v[180:183], v[114:117]
	v_mfma_f32_16x16x32_f16 v[86:89], v[200:203], v[188:191], v[86:89]
	v_mfma_f32_16x16x32_f16 v[82:85], v[220:223], v[188:191], v[82:85]
	s_barrier
; #define PG8_STAGE(bufoff, gbase, voff) do { _Pragma("unroll") for (int _i = 0; _i < 2; ++_i) \
;         __builtin_amdgcn_global_load_lds((const unsigned*)((const char*)(gbase) + (voff)[_i]), (LAS unsigned*)(lds + (bufoff) + ldsw + _i * 8192), 16, 0, 0); } while (0)
; #define PG8_LDA(dst, b, h) do { _Pragma("unroll") for (int m = 0; m < 4; ++m) _Pragma("unroll") for (int k = 0; k < 2; ++k) dst[m][k] = *(const LAS h16x8*)(lds + PG8_SA(b, h) + aoff + m * 2048 + k * 1024); } while (0)
; #define PG8_LDB(dst, b, h) do { _Pragma("unroll") for (int n = 0; n < 2; ++n) _Pragma("unroll") for (int k = 0; k < 2; ++k) dst[n][k] = *(const LAS h16x8*)(lds + PG8_SB(b, h) + boff + n * 2048 + k * 1024); } while (0)
; #define PG8_MMA(ai, bj, At, Bt_) do { __builtin_amdgcn_s_setprio(1); _Pragma("unroll") for (int m = 0; m < 4; ++m) _Pragma("unroll") for (int n = 0; n < 2; ++n) _Pragma("unroll") for (int k = 0; k < 2; ++k) \
;         acc[ai][bj][m][n] = __builtin_amdgcn_mfma_f32_16x16x32_f16(Bt_[n][k], At[m][k], acc[ai][bj][m][n], 0, 0, 0); __builtin_amdgcn_s_setprio(0); } while (0)
; #define PG8_WAIT_V(n) asm volatile("s_waitcnt vmcnt(" #n ")" ::: "memory")
; #define PG8_WAIT_L(n) asm volatile("s_waitcnt lgkmcnt(" #n ")" ::: "memory")
; #define PG8_BAR __builtin_amdgcn_s_barrier()
; #define PG8_SCHED __builtin_amdgcn_sched_barrier(0)
; template <class Epi, class AMap>
; __device__ __forceinline__ void gemm_phase(LAS unsigned char* lds, const AMap am, const int lda, const h16* Bt, const int ldb, const int M, const int N, const int K, const Epi& E) {
;     ...
;         for (int t = 0; t < nt; t += 2) {
;             const bool last = (t == nt - 2);
;             const char* a1 = cA + (size_t)(t + 1) * kstep;
;             const char* a2 = last ? nA : cA + (size_t)(t + 2) * kstep; const char* b2 = last ? nB : cB + (size_t)(t + 2) * kstep;
;             const char* a3 = a2 + kstep; const char* b3 = b2 + kstep;
;             PG8_LDB(B0, 0, 0); PG8_SCHED; PG8_LDA(At, 0, 0); PG8_STAGE(PG8_SA(1, 1), a1 + hstepA, voffA);
;             PG8_WAIT_L(8); PG8_BAR; PG8_WAIT_L(0); PG8_MMA(0, 0, At, B0); PG8_BAR; PG8_SCHED;
;     ...
;             PG8_LDA(At, 1, 1); PG8_STAGE(PG8_SA(1, 0), a3, voffA);
;             PG8_BAR; PG8_WAIT_L(0); PG8_MMA(1, 0, At, B0); PG8_BAR; PG8_SCHED;
;             PG8_STAGE(PG8_SB(1, 1), b3 + hstepB, voffB);
;             PG8_WAIT_V(6); PG8_BAR; PG8_MMA(1, 1, At, B1); PG8_BAR;
	v_lshl_add_u64 v[224:225], v[192:193], 0, s[92:93]
	s_mov_b32 m0, s0
	s_nop 0
	global_load_lds_dwordx4 v[224:225], off
	v_lshl_add_u64 v[224:225], v[212:213], 0, s[92:93]
	s_add_i32 m0, s0, 0x2000
	s_nop 0
	global_load_lds_dwordx4 v[224:225], off
	s_mov_b32 m0, s89
	v_lshl_add_u64 v[192:193], v[214:215], 0, s[92:93]
	ds_read_b128 v[90:93], v195 offset:49152
	ds_read_b128 v[94:97], v195 offset:50176
	ds_read_b128 v[98:101], v195 offset:51200
	ds_read_b128 v[102:105], v195 offset:52224
	ds_read_b128 v[176:179], v195 offset:53248
	ds_read_b128 v[180:183], v195 offset:54272
	ds_read_b128 v[184:187], v195 offset:55296
	ds_read_b128 v[188:191], v195 offset:56320
	global_load_lds_dwordx4 v[192:193], off
	v_lshl_add_u64 v[192:193], v[216:217], 0, s[92:93]
	s_mov_b32 m0, s35
	s_nop 0
	global_load_lds_dwordx4 v[192:193], off
	s_add_u32 s0, s48, 0x80080
	s_addc_u32 s1, s49, 0
	s_add_i32 s26, s26, s64
	v_lshl_add_u64 v[224:225], s[0:1], 0, v[0:1]
	s_mov_b32 m0, s26
	s_nop 0
	global_load_lds_dwordx4 v[224:225], off
	v_lshl_add_u64 v[224:225], s[0:1], 0, v[162:163]
	s_add_i32 m0, s26, 0x2000
	s_nop 0
	global_load_lds_dwordx4 v[224:225], off
	s_add_i32 s60, s60, 2
	s_add_u32 vcc_lo, vcc_lo, 0x100
	s_addc_u32 vcc_hi, vcc_hi, 0
	s_add_u32 s21, s21, 0x100
	s_addc_u32 s66, s66, 0
	s_cmp_gt_u32 s60, 29
	s_waitcnt vmcnt(8) lgkmcnt(0)
	s_barrier
	v_mfma_f32_16x16x32_f16 v[62:65], v[66:69], v[90:93], v[62:65]
	v_mfma_f32_16x16x32_f16 v[58:61], v[74:77], v[90:93], v[58:61]
	v_mfma_f32_16x16x32_f16 v[46:49], v[66:69], v[98:101], v[46:49]
	v_mfma_f32_16x16x32_f16 v[38:41], v[74:77], v[98:101], v[38:41]
	v_mfma_f32_16x16x32_f16 v[30:33], v[66:69], v[176:179], v[30:33]
	v_mfma_f32_16x16x32_f16 v[22:25], v[74:77], v[176:179], v[22:25]
	v_mfma_f32_16x16x32_f16 v[14:17], v[66:69], v[184:187], v[14:17]
	v_mfma_f32_16x16x32_f16 v[10:13], v[74:77], v[184:187], v[10:13]
	v_mfma_f32_16x16x32_f16 v[62:65], v[70:73], v[94:97], v[62:65]
	v_mfma_f32_16x16x32_f16 v[58:61], v[78:81], v[94:97], v[58:61]
	v_mfma_f32_16x16x32_f16 v[46:49], v[70:73], v[102:105], v[46:49]
	v_mfma_f32_16x16x32_f16 v[38:41], v[78:81], v[102:105], v[38:41]
	v_mfma_f32_16x16x32_f16 v[30:33], v[70:73], v[180:183], v[30:33]
	v_mfma_f32_16x16x32_f16 v[22:25], v[78:81], v[180:183], v[22:25]
	v_mfma_f32_16x16x32_f16 v[14:17], v[70:73], v[188:191], v[14:17]
	v_mfma_f32_16x16x32_f16 v[10:13], v[78:81], v[188:191], v[10:13]
	v_mfma_f32_16x16x32_f16 v[54:57], v[196:199], v[90:93], v[54:57]
	v_mfma_f32_16x16x32_f16 v[50:53], v[204:207], v[90:93], v[50:53]
	v_mfma_f32_16x16x32_f16 v[42:45], v[196:199], v[98:101], v[42:45]
	v_mfma_f32_16x16x32_f16 v[34:37], v[204:207], v[98:101], v[34:37]
	v_mfma_f32_16x16x32_f16 v[26:29], v[196:199], v[176:179], v[26:29]
	v_mfma_f32_16x16x32_f16 v[18:21], v[204:207], v[176:179], v[18:21]
	v_mfma_f32_16x16x32_f16 v[6:9], v[196:199], v[184:187], v[6:9]
	v_mfma_f32_16x16x32_f16 v[2:5], v[204:207], v[184:187], v[2:5]
	v_mfma_f32_16x16x32_f16 v[54:57], v[200:203], v[94:97], v[54:57]
	v_mfma_f32_16x16x32_f16 v[50:53], v[220:223], v[94:97], v[50:53]
	v_mfma_f32_16x16x32_f16 v[42:45], v[200:203], v[102:105], v[42:45]
	v_mfma_f32_16x16x32_f16 v[34:37], v[220:223], v[102:105], v[34:37]
	v_mfma_f32_16x16x32_f16 v[26:29], v[200:203], v[180:183], v[26:29]
	v_mfma_f32_16x16x32_f16 v[18:21], v[220:223], v[180:183], v[18:21]
	v_mfma_f32_16x16x32_f16 v[6:9], v[200:203], v[188:191], v[6:9]
	v_mfma_f32_16x16x32_f16 v[2:5], v[220:223], v[188:191], v[2:5]
	s_barrier
	s_cbranch_scc1 .Lg4x_92
.LBB0_92:
	s_add_u32 s0, vcc_lo, 0xfff80080
	s_addc_u32 s1, vcc_hi, -1
	s_add_i32 s67, 0, 0x10000
	v_add_u32_e32 v226, s67, v169
	ds_read_b128 v[66:69], v226
	ds_read_b128 v[70:73], v226 offset:1024
	ds_read_b128 v[74:77], v226 offset:2048
	ds_read_b128 v[78:81], v226 offset:3072
	s_cmp_eq_u32 s60, 28
	s_cselect_b32 s27, s69, s1
	s_cselect_b32 s26, s29, s0
	s_cselect_b32 s49, s73, s66
	s_cselect_b32 s48, s20, s21
	v_lshl_add_u64 v[192:193], vcc, 0, v[172:173]
	s_add_i32 m0, s81, 0xc000
	ds_read_b128 v[90:93], v195
	ds_read_b128 v[94:97], v195 offset:1024
	ds_read_b128 v[98:101], v195 offset:2048
	ds_read_b128 v[102:105], v195 offset:3072
	ds_read_b128 v[176:179], v195 offset:4096
	ds_read_b128 v[180:183], v195 offset:5120
	ds_read_b128 v[184:187], v195 offset:6144
	ds_read_b128 v[188:191], v195 offset:7168
	global_load_lds_dwordx4 v[192:193], off
	v_lshl_add_u64 v[192:193], vcc, 0, v[174:175]
	s_add_i32 m0, s81, 0xe000
	s_nop 0
	global_load_lds_dwordx4 v[192:193], off
	s_waitcnt lgkmcnt(11)
	s_add_i32 s65, 0, 0x14000
	v_add_u32_e32 v192, s65, v169
	s_add_i32 s0, s67, s64
	ds_read_b128 v[196:199], v192
	ds_read_b128 v[200:203], v192 offset:1024
	ds_read_b128 v[204:207], v192 offset:2048
	ds_read_b128 v[220:223], v192 offset:3072
	s_waitcnt vmcnt(8) lgkmcnt(0)
	s_barrier
; #define PG8_STAGE(bufoff, gbase, voff) do { _Pragma("unroll") for (int _i = 0; _i < 2; ++_i) \
;         __builtin_amdgcn_global_load_lds((const unsigned*)((const char*)(gbase) + (voff)[_i]), (LAS unsigned*)(lds + (bufoff) + ldsw + _i * 8192), 16, 0, 0); } while (0)
; #define PG8_LDA(dst, b, h) do { _Pragma("unroll") for (int m = 0; m < 4; ++m) _Pragma("unroll") for (int k = 0; k < 2; ++k) dst[m][k] = *(const LAS h16x8*)(lds + PG8_SA(b, h) + aoff + m * 2048 + k * 1024); } while (0)
; #define PG8_LDB(dst, b, h) do { _Pragma("unroll") for (int n = 0; n < 2; ++n) _Pragma("unroll") for (int k = 0; k < 2; ++k) dst[n][k] = *(const LAS h16x8*)(lds + PG8_SB(b, h) + boff + n * 2048 + k * 1024); } while (0)
; #define PG8_MMA(ai, bj, At, Bt_) do { __builtin_amdgcn_s_setprio(1); _Pragma("unroll") for (int m = 0; m < 4; ++m) _Pragma("unroll") for (int n = 0; n < 2; ++n) _Pragma("unroll") for (int k = 0; k < 2; ++k) \
;         acc[ai][bj][m][n] = __builtin_amdgcn_mfma_f32_16x16x32_f16(Bt_[n][k], At[m][k], acc[ai][bj][m][n], 0, 0, 0); __builtin_amdgcn_s_setprio(0); } while (0)
; #define PG8_WAIT_V(n) asm volatile("s_waitcnt vmcnt(" #n ")" ::: "memory")
; #define PG8_WAIT_L(n) asm volatile("s_waitcnt lgkmcnt(" #n ")" ::: "memory")
; #define PG8_BAR __builtin_amdgcn_s_barrier()
; #define PG8_SCHED __builtin_amdgcn_sched_barrier(0)
; template <class Epi, class AMap>
; __device__ __forceinline__ void gemm_phase(LAS unsigned char* lds, const AMap am, const int lda, const h16* Bt, const int ldb, const int M, const int N, const int K, const Epi& E) {
;     ...
;             PG8_LDB(B0, 0, 0); PG8_SCHED; PG8_LDA(At, 0, 0); PG8_STAGE(PG8_SA(1, 1), a1 + hstepA, voffA);
;             PG8_WAIT_L(8); PG8_BAR; PG8_WAIT_L(0); PG8_MMA(0, 0, At, B0); PG8_BAR; PG8_SCHED;
;             PG8_LDB(B1, 0, 1); PG8_STAGE(PG8_SB(0, 0), b2, voffB);
;             PG8_BAR; PG8_WAIT_L(0); PG8_MMA(0, 1, At, B1); PG8_BAR;
;             PG8_LDA(At, 0, 1); PG8_STAGE(PG8_SA(0, 0), a2, voffA);
;             PG8_BAR; PG8_WAIT_L(0); PG8_MMA(1, 0, At, B0); PG8_BAR; PG8_SCHED;
;             PG8_STAGE(PG8_SB(0, 1), b2 + hstepB, voffB);
;             PG8_WAIT_V(6); PG8_BAR; PG8_MMA(1, 1, At, B1); PG8_BAR;
	v_mfma_f32_16x16x32_f16 v[158:161], v[66:69], v[90:93], v[158:161]
	v_mfma_f32_16x16x32_f16 v[154:157], v[74:77], v[90:93], v[154:157]
	v_mfma_f32_16x16x32_f16 v[142:145], v[66:69], v[98:101], v[142:145]
	v_mfma_f32_16x16x32_f16 v[134:137], v[74:77], v[98:101], v[134:137]
	v_mfma_f32_16x16x32_f16 v[126:129], v[66:69], v[176:179], v[126:129]
	v_mfma_f32_16x16x32_f16 v[118:121], v[74:77], v[176:179], v[118:121]
	v_mfma_f32_16x16x32_f16 v[110:113], v[66:69], v[184:187], v[110:113]
	v_mfma_f32_16x16x32_f16 v[106:109], v[74:77], v[184:187], v[106:109]
	v_mfma_f32_16x16x32_f16 v[158:161], v[70:73], v[94:97], v[158:161]
	v_mfma_f32_16x16x32_f16 v[154:157], v[78:81], v[94:97], v[154:157]
	v_mfma_f32_16x16x32_f16 v[142:145], v[70:73], v[102:105], v[142:145]
	v_mfma_f32_16x16x32_f16 v[134:137], v[78:81], v[102:105], v[134:137]
	v_mfma_f32_16x16x32_f16 v[126:129], v[70:73], v[180:183], v[126:129]
	v_mfma_f32_16x16x32_f16 v[118:121], v[78:81], v[180:183], v[118:121]
	v_mfma_f32_16x16x32_f16 v[110:113], v[70:73], v[188:191], v[110:113]
	v_mfma_f32_16x16x32_f16 v[106:109], v[78:81], v[188:191], v[106:109]
	v_mfma_f32_16x16x32_f16 v[150:153], v[196:199], v[90:93], v[150:153]
	v_mfma_f32_16x16x32_f16 v[146:149], v[204:207], v[90:93], v[146:149]
	v_mfma_f32_16x16x32_f16 v[150:153], v[200:203], v[94:97], v[150:153]
	v_mfma_f32_16x16x32_f16 v[146:149], v[220:223], v[94:97], v[146:149]
	v_mfma_f32_16x16x32_f16 v[138:141], v[196:199], v[98:101], v[138:141]
	v_mfma_f32_16x16x32_f16 v[130:133], v[204:207], v[98:101], v[130:133]
	v_mfma_f32_16x16x32_f16 v[114:117], v[204:207], v[176:179], v[114:117]
	v_mfma_f32_16x16x32_f16 v[86:89], v[196:199], v[184:187], v[86:89]
	v_mfma_f32_16x16x32_f16 v[82:85], v[204:207], v[184:187], v[82:85]
	v_mfma_f32_16x16x32_f16 v[138:141], v[200:203], v[102:105], v[138:141]
	v_mfma_f32_16x16x32_f16 v[130:133], v[220:223], v[102:105], v[130:133]
	v_mfma_f32_16x16x32_f16 v[122:125], v[196:199], v[176:179], v[122:125]
	v_mfma_f32_16x16x32_f16 v[114:117], v[220:223], v[180:183], v[114:117]
	v_mfma_f32_16x16x32_f16 v[86:89], v[200:203], v[188:191], v[86:89]
	v_mfma_f32_16x16x32_f16 v[82:85], v[220:223], v[188:191], v[82:85]
	v_mfma_f32_16x16x32_f16 v[122:125], v[200:203], v[180:183], v[122:125]
	s_barrier
	v_lshl_add_u64 v[192:193], s[48:49], 0, v[0:1]
	s_mov_b32 m0, s0
	v_lshl_add_u64 v[212:213], s[48:49], 0, v[162:163]
	global_load_lds_dwordx4 v[192:193], off
	s_add_i32 m0, s0, 0x2000
	s_nop 0
	global_load_lds_dwordx4 v[212:213], off
	s_mov_b32 m0, s81
	v_lshl_add_u64 v[214:215], s[26:27], 0, v[166:167]
	ds_read_b128 v[90:93], v195 offset:16384
	ds_read_b128 v[94:97], v195 offset:17408
	ds_read_b128 v[98:101], v195 offset:18432
	ds_read_b128 v[102:105], v195 offset:19456
	ds_read_b128 v[176:179], v195 offset:20480
	ds_read_b128 v[180:183], v195 offset:21504
	ds_read_b128 v[184:187], v195 offset:22528
	ds_read_b128 v[188:191], v195 offset:23552
	global_load_lds_dwordx4 v[214:215], off
	v_lshl_add_u64 v[216:217], s[26:27], 0, v[164:165]
	s_mov_b32 m0, s82
	s_nop 0
	global_load_lds_dwordx4 v[216:217], off
	s_add_u32 s0, s48, 0x80000
	s_addc_u32 s1, s49, 0
	s_add_i32 s65, s65, s64
	v_lshl_add_u64 v[224:225], s[0:1], 0, v[0:1]
	s_mov_b32 m0, s65
	s_nop 0
	global_load_lds_dwordx4 v[224:225], off
	v_lshl_add_u64 v[224:225], s[0:1], 0, v[162:163]
	s_add_i32 m0, s65, 0x2000
	s_nop 0
	global_load_lds_dwordx4 v[224:225], off
	s_waitcnt vmcnt(8) lgkmcnt(0)
	s_barrier
	v_mfma_f32_16x16x32_f16 v[62:65], v[66:69], v[90:93], v[62:65]
	v_mfma_f32_16x16x32_f16 v[58:61], v[74:77], v[90:93], v[58:61]
	v_mfma_f32_16x16x32_f16 v[46:49], v[66:69], v[98:101], v[46:49]
	v_mfma_f32_16x16x32_f16 v[38:41], v[74:77], v[98:101], v[38:41]
	v_mfma_f32_16x16x32_f16 v[30:33], v[66:69], v[176:179], v[30:33]
	v_mfma_f32_16x16x32_f16 v[22:25], v[74:77], v[176:179], v[22:25]
	v_mfma_f32_16x16x32_f16 v[14:17], v[66:69], v[184:187], v[14:17]
	v_mfma_f32_16x16x32_f16 v[10:13], v[74:77], v[184:187], v[10:13]
	v_mfma_f32_16x16x32_f16 v[62:65], v[70:73], v[94:97], v[62:65]
	v_mfma_f32_16x16x32_f16 v[58:61], v[78:81], v[94:97], v[58:61]
	v_mfma_f32_16x16x32_f16 v[46:49], v[70:73], v[102:105], v[46:49]
	v_mfma_f32_16x16x32_f16 v[38:41], v[78:81], v[102:105], v[38:41]
	v_mfma_f32_16x16x32_f16 v[30:33], v[70:73], v[180:183], v[30:33]
	v_mfma_f32_16x16x32_f16 v[22:25], v[78:81], v[180:183], v[22:25]
	v_mfma_f32_16x16x32_f16 v[14:17], v[70:73], v[188:191], v[14:17]
	v_mfma_f32_16x16x32_f16 v[10:13], v[78:81], v[188:191], v[10:13]
	v_mfma_f32_16x16x32_f16 v[54:57], v[196:199], v[90:93], v[54:57]
	v_mfma_f32_16x16x32_f16 v[50:53], v[204:207], v[90:93], v[50:53]
	v_mfma_f32_16x16x32_f16 v[42:45], v[196:199], v[98:101], v[42:45]
	v_mfma_f32_16x16x32_f16 v[34:37], v[204:207], v[98:101], v[34:37]
	v_mfma_f32_16x16x32_f16 v[26:29], v[196:199], v[176:179], v[26:29]
	v_mfma_f32_16x16x32_f16 v[18:21], v[204:207], v[176:179], v[18:21]
	v_mfma_f32_16x16x32_f16 v[6:9], v[196:199], v[184:187], v[6:9]
	v_mfma_f32_16x16x32_f16 v[2:5], v[204:207], v[184:187], v[2:5]
	v_mfma_f32_16x16x32_f16 v[54:57], v[200:203], v[94:97], v[54:57]
	v_mfma_f32_16x16x32_f16 v[50:53], v[220:223], v[94:97], v[50:53]
	v_mfma_f32_16x16x32_f16 v[42:45], v[200:203], v[102:105], v[42:45]
	v_mfma_f32_16x16x32_f16 v[34:37], v[220:223], v[102:105], v[34:37]
	v_mfma_f32_16x16x32_f16 v[26:29], v[200:203], v[180:183], v[26:29]
	v_mfma_f32_16x16x32_f16 v[18:21], v[220:223], v[180:183], v[18:21]
	v_mfma_f32_16x16x32_f16 v[6:9], v[200:203], v[188:191], v[6:9]
	v_mfma_f32_16x16x32_f16 v[2:5], v[220:223], v[188:191], v[2:5]
	s_barrier
; #define PG8_STAGE(bufoff, gbase, voff) do { _Pragma("unroll") for (int _i = 0; _i < 2; ++_i) \
;         __builtin_amdgcn_global_load_lds((const unsigned*)((const char*)(gbase) + (voff)[_i]), (LAS unsigned*)(lds + (bufoff) + ldsw + _i * 8192), 16, 0, 0); } while (0)
; #define PG8_LDA(dst, b, h) do { _Pragma("unroll") for (int m = 0; m < 4; ++m) _Pragma("unroll") for (int k = 0; k < 2; ++k) dst[m][k] = *(const LAS h16x8*)(lds + PG8_SA(b, h) + aoff + m * 2048 + k * 1024); } while (0)
; #define PG8_LDB(dst, b, h) do { _Pragma("unroll") for (int n = 0; n < 2; ++n) _Pragma("unroll") for (int k = 0; k < 2; ++k) dst[n][k] = *(const LAS h16x8*)(lds + PG8_SB(b, h) + boff + n * 2048 + k * 1024); } while (0)
; #define PG8_MMA(ai, bj, At, Bt_) do { __builtin_amdgcn_s_setprio(1); _Pragma("unroll") for (int m = 0; m < 4; ++m) _Pragma("unroll") for (int n = 0; n < 2; ++n) _Pragma("unroll") for (int k = 0; k < 2; ++k) \
;         acc[ai][bj][m][n] = __builtin_amdgcn_mfma_f32_16x16x32_f16(Bt_[n][k], At[m][k], acc[ai][bj][m][n], 0, 0, 0); __builtin_amdgcn_s_setprio(0); } while (0)
; #define PG8_WAIT_V(n) asm volatile("s_waitcnt vmcnt(" #n ")" ::: "memory")
; #define PG8_WAIT_L(n) asm volatile("s_waitcnt lgkmcnt(" #n ")" ::: "memory")
; #define PG8_BAR __builtin_amdgcn_s_barrier()
; #define PG8_SCHED __builtin_amdgcn_sched_barrier(0)
; template <class Epi, class AMap>
; __device__ __forceinline__ void gemm_phase(LAS unsigned char* lds, const AMap am, const int lda, const h16* Bt, const int ldb, const int M, const int N, const int K, const Epi& E) {
;     ...
;             PG8_LDB(B0, 1, 0); PG8_SCHED; PG8_LDA(At, 1, 0); PG8_STAGE(PG8_SA(0, 1), a2 + hstepA, voffA);
;             PG8_WAIT_L(8); PG8_BAR; PG8_WAIT_L(0); PG8_MMA(0, 0, At, B0); PG8_BAR; PG8_SCHED;
;             PG8_LDB(B1, 1, 1); PG8_STAGE(PG8_SB(1, 0), b3, voffB);
;             PG8_BAR; PG8_WAIT_L(0); PG8_MMA(0, 1, At, B1); PG8_BAR;
;             PG8_LDA(At, 1, 1); PG8_STAGE(PG8_SA(1, 0), a3, voffA);
;             PG8_BAR; PG8_WAIT_L(0); PG8_MMA(1, 0, At, B0); PG8_BAR; PG8_SCHED;
;             PG8_STAGE(PG8_SB(1, 1), b3 + hstepB, voffB);
;             PG8_WAIT_V(6); PG8_BAR; PG8_MMA(1, 1, At, B1); PG8_BAR;
	s_add_i32 s65, 0, 0x18000
	v_add_u32_e32 v226, s65, v169
	ds_read_b128 v[66:69], v226
	ds_read_b128 v[70:73], v226 offset:1024
	ds_read_b128 v[74:77], v226 offset:2048
	ds_read_b128 v[78:81], v226 offset:3072
	s_add_u32 s0, s26, 0x80000
	s_addc_u32 s1, s27, 0
	s_mov_b32 m0, s83
	v_lshl_add_u64 v[224:225], s[0:1], 0, v[166:167]
	ds_read_b128 v[90:93], v195 offset:32768
	ds_read_b128 v[94:97], v195 offset:33792
	ds_read_b128 v[98:101], v195 offset:34816
	ds_read_b128 v[102:105], v195 offset:35840
	ds_read_b128 v[176:179], v195 offset:36864
	ds_read_b128 v[180:183], v195 offset:37888
	ds_read_b128 v[184:187], v195 offset:38912
	ds_read_b128 v[188:191], v195 offset:39936
	global_load_lds_dwordx4 v[224:225], off
	v_lshl_add_u64 v[224:225], s[0:1], 0, v[164:165]
	s_mov_b32 m0, s50
	s_nop 0
	global_load_lds_dwordx4 v[224:225], off
	s_waitcnt lgkmcnt(11)
	s_add_i32 s26, 0, 0x1c000
	v_add_u32_e32 v226, s26, v169
	s_add_i32 s0, s65, s64
	ds_read_b128 v[196:199], v226
	ds_read_b128 v[200:203], v226 offset:1024
	ds_read_b128 v[204:207], v226 offset:2048
	ds_read_b128 v[220:223], v226 offset:3072
	s_waitcnt vmcnt(8) lgkmcnt(0)
	s_barrier
	v_mfma_f32_16x16x32_f16 v[158:161], v[66:69], v[90:93], v[158:161]
	v_mfma_f32_16x16x32_f16 v[158:161], v[70:73], v[94:97], v[158:161]
	v_mfma_f32_16x16x32_f16 v[154:157], v[74:77], v[90:93], v[154:157]
	v_mfma_f32_16x16x32_f16 v[154:157], v[78:81], v[94:97], v[154:157]
	v_mfma_f32_16x16x32_f16 v[142:145], v[66:69], v[98:101], v[142:145]
	v_mfma_f32_16x16x32_f16 v[134:137], v[74:77], v[98:101], v[134:137]
	v_mfma_f32_16x16x32_f16 v[126:129], v[66:69], v[176:179], v[126:129]
	v_mfma_f32_16x16x32_f16 v[118:121], v[74:77], v[176:179], v[118:121]
	v_mfma_f32_16x16x32_f16 v[110:113], v[66:69], v[184:187], v[110:113]
	v_mfma_f32_16x16x32_f16 v[106:109], v[74:77], v[184:187], v[106:109]
	v_mfma_f32_16x16x32_f16 v[142:145], v[70:73], v[102:105], v[142:145]
	v_mfma_f32_16x16x32_f16 v[134:137], v[78:81], v[102:105], v[134:137]
	v_mfma_f32_16x16x32_f16 v[126:129], v[70:73], v[180:183], v[126:129]
	v_mfma_f32_16x16x32_f16 v[118:121], v[78:81], v[180:183], v[118:121]
	v_mfma_f32_16x16x32_f16 v[110:113], v[70:73], v[188:191], v[110:113]
	v_mfma_f32_16x16x32_f16 v[106:109], v[78:81], v[188:191], v[106:109]
	v_mfma_f32_16x16x32_f16 v[146:149], v[204:207], v[90:93], v[146:149]
	v_mfma_f32_16x16x32_f16 v[150:153], v[196:199], v[90:93], v[150:153]
	v_mfma_f32_16x16x32_f16 v[146:149], v[220:223], v[94:97], v[146:149]
	v_mfma_f32_16x16x32_f16 v[138:141], v[196:199], v[98:101], v[138:141]
	v_mfma_f32_16x16x32_f16 v[150:153], v[200:203], v[94:97], v[150:153]
	v_mfma_f32_16x16x32_f16 v[138:141], v[200:203], v[102:105], v[138:141]
	v_mfma_f32_16x16x32_f16 v[130:133], v[204:207], v[98:101], v[130:133]
	v_mfma_f32_16x16x32_f16 v[130:133], v[220:223], v[102:105], v[130:133]
	v_mfma_f32_16x16x32_f16 v[122:125], v[196:199], v[176:179], v[122:125]
	v_mfma_f32_16x16x32_f16 v[122:125], v[200:203], v[180:183], v[122:125]
	v_mfma_f32_16x16x32_f16 v[114:117], v[204:207], v[176:179], v[114:117]
	v_mfma_f32_16x16x32_f16 v[86:89], v[196:199], v[184:187], v[86:89]
	v_mfma_f32_16x16x32_f16 v[82:85], v[204:207], v[184:187], v[82:85]
	v_mfma_f32_16x16x32_f16 v[114:117], v[220:223], v[180:183], v[114:117]
	v_mfma_f32_16x16x32_f16 v[86:89], v[200:203], v[188:191], v[86:89]
	v_mfma_f32_16x16x32_f16 v[82:85], v[220:223], v[188:191], v[82:85]
	s_barrier
	v_lshl_add_u64 v[224:225], v[192:193], 0, s[92:93]
	s_mov_b32 m0, s0
	s_nop 0
	global_load_lds_dwordx4 v[224:225], off
	v_lshl_add_u64 v[224:225], v[212:213], 0, s[92:93]
	s_add_i32 m0, s0, 0x2000
	s_nop 0
	global_load_lds_dwordx4 v[224:225], off
	s_mov_b32 m0, s89
	v_lshl_add_u64 v[192:193], v[214:215], 0, s[92:93]
	ds_read_b128 v[90:93], v195 offset:49152
	ds_read_b128 v[94:97], v195 offset:50176
	ds_read_b128 v[98:101], v195 offset:51200
	ds_read_b128 v[102:105], v195 offset:52224
	ds_read_b128 v[176:179], v195 offset:53248
	ds_read_b128 v[180:183], v195 offset:54272
	ds_read_b128 v[184:187], v195 offset:55296
	ds_read_b128 v[188:191], v195 offset:56320
	global_load_lds_dwordx4 v[192:193], off
	v_lshl_add_u64 v[192:193], v[216:217], 0, s[92:93]
	s_mov_b32 m0, s35
	s_nop 0
	global_load_lds_dwordx4 v[192:193], off
	s_add_u32 s0, s48, 0x80080
	s_addc_u32 s1, s49, 0
	s_add_i32 s26, s26, s64
	v_lshl_add_u64 v[224:225], s[0:1], 0, v[0:1]
	s_mov_b32 m0, s26
	s_nop 0
	global_load_lds_dwordx4 v[224:225], off
	v_lshl_add_u64 v[224:225], s[0:1], 0, v[162:163]
	s_add_i32 m0, s26, 0x2000
	s_nop 0
	global_load_lds_dwordx4 v[224:225], off
	s_add_i32 s60, s60, 2
	s_add_u32 vcc_lo, vcc_lo, 0x100
	s_addc_u32 vcc_hi, vcc_hi, 0
	s_add_u32 s21, s21, 0x100
	s_addc_u32 s66, s66, 0
	s_cmp_gt_u32 s60, 29
	s_waitcnt vmcnt(8) lgkmcnt(0)
	s_barrier
	v_mfma_f32_16x16x32_f16 v[62:65], v[66:69], v[90:93], v[62:65]
	v_mfma_f32_16x16x32_f16 v[58:61], v[74:77], v[90:93], v[58:61]
	v_mfma_f32_16x16x32_f16 v[46:49], v[66:69], v[98:101], v[46:49]
	v_mfma_f32_16x16x32_f16 v[38:41], v[74:77], v[98:101], v[38:41]
	v_mfma_f32_16x16x32_f16 v[30:33], v[66:69], v[176:179], v[30:33]
	v_mfma_f32_16x16x32_f16 v[22:25], v[74:77], v[176:179], v[22:25]
	v_mfma_f32_16x16x32_f16 v[14:17], v[66:69], v[184:187], v[14:17]
	v_mfma_f32_16x16x32_f16 v[10:13], v[74:77], v[184:187], v[10:13]
	v_mfma_f32_16x16x32_f16 v[62:65], v[70:73], v[94:97], v[62:65]
	v_mfma_f32_16x16x32_f16 v[58:61], v[78:81], v[94:97], v[58:61]
	v_mfma_f32_16x16x32_f16 v[46:49], v[70:73], v[102:105], v[46:49]
	v_mfma_f32_16x16x32_f16 v[38:41], v[78:81], v[102:105], v[38:41]
	v_mfma_f32_16x16x32_f16 v[30:33], v[70:73], v[180:183], v[30:33]
	v_mfma_f32_16x16x32_f16 v[22:25], v[78:81], v[180:183], v[22:25]
	v_mfma_f32_16x16x32_f16 v[14:17], v[70:73], v[188:191], v[14:17]
	v_mfma_f32_16x16x32_f16 v[10:13], v[78:81], v[188:191], v[10:13]
	v_mfma_f32_16x16x32_f16 v[54:57], v[196:199], v[90:93], v[54:57]
	v_mfma_f32_16x16x32_f16 v[50:53], v[204:207], v[90:93], v[50:53]
	v_mfma_f32_16x16x32_f16 v[42:45], v[196:199], v[98:101], v[42:45]
	v_mfma_f32_16x16x32_f16 v[34:37], v[204:207], v[98:101], v[34:37]
	v_mfma_f32_16x16x32_f16 v[26:29], v[196:199], v[176:179], v[26:29]
	v_mfma_f32_16x16x32_f16 v[18:21], v[204:207], v[176:179], v[18:21]
	v_mfma_f32_16x16x32_f16 v[6:9], v[196:199], v[184:187], v[6:9]
	v_mfma_f32_16x16x32_f16 v[2:5], v[204:207], v[184:187], v[2:5]
	v_mfma_f32_16x16x32_f16 v[54:57], v[200:203], v[94:97], v[54:57]
	v_mfma_f32_16x16x32_f16 v[50:53], v[220:223], v[94:97], v[50:53]
	v_mfma_f32_16x16x32_f16 v[42:45], v[200:203], v[102:105], v[42:45]
	v_mfma_f32_16x16x32_f16 v[34:37], v[220:223], v[102:105], v[34:37]
	v_mfma_f32_16x16x32_f16 v[26:29], v[200:203], v[180:183], v[26:29]
	v_mfma_f32_16x16x32_f16 v[18:21], v[220:223], v[180:183], v[18:21]
	v_mfma_f32_16x16x32_f16 v[6:9], v[200:203], v[188:191], v[6:9]
	v_mfma_f32_16x16x32_f16 v[2:5], v[220:223], v[188:191], v[2:5]
	s_barrier
	s_cbranch_scc0 .LBB0_92
.Lg4x_92:
	s_cmpk_gt_u32 s10, 0xff
	s_cbranch_scc1 .Lgx1
	s_barrier

; #define PG8_STAGE(bufoff, gbase, voff) do { _Pragma("unroll") for (int _i = 0; _i < 2; ++_i) \
;         __builtin_amdgcn_global_load_lds((const unsigned*)((const char*)(gbase) + (voff)[_i]), (LAS unsigned*)(lds + (bufoff) + ldsw + _i * 8192), 16, 0, 0); } while (0)
; #define PG8_LDA(dst, b, h) do { _Pragma("unroll") for (int m = 0; m < 4; ++m) _Pragma("unroll") for (int k = 0; k < 2; ++k) dst[m][k] = *(const LAS h16x8*)(lds + PG8_SA(b, h) + aoff + m * 2048 + k * 1024); } while (0)
; #define PG8_LDB(dst, b, h) do { _Pragma("unroll") for (int n = 0; n < 2; ++n) _Pragma("unroll") for (int k = 0; k < 2; ++k) dst[n][k] = *(const LAS h16x8*)(lds + PG8_SB(b, h) + boff + n * 2048 + k * 1024); } while (0)
; #define PG8_WAIT_V(n) asm volatile("s_waitcnt vmcnt(" #n ")" ::: "memory")
; #define PG8_WAIT_L(n) asm volatile("s_waitcnt lgkmcnt(" #n ")" ::: "memory")
; #define PG8_BAR __builtin_amdgcn_s_barrier()
; #define PG8_SCHED __builtin_amdgcn_sched_barrier(0)
; template <class Epi, class AMap>
; __device__ __forceinline__ void gemm_phase(LAS unsigned char* lds, const AMap am, const int lda, const h16* Bt, const int ldb, const int M, const int N, const int K, const Epi& E) {
;     ...
;         const bool has_next = S.next(ui + 1, nxt);
;         const char* nA = has_next ? am(nxt.pn) + (size_t)nxt.pm * tstepA : cA; const char* nB = has_next ? (const char*)Bt + (size_t)nxt.pn * tstepB : cB;
; #pragma unroll 1
;         for (int t = 0; t < nt; t += 2) {
;             const bool last = (t == nt - 2);
;             const char* a1 = cA + (size_t)(t + 1) * kstep;
;             const char* a2 = last ? nA : cA + (size_t)(t + 2) * kstep; const char* b2 = last ? nB : cB + (size_t)(t + 2) * kstep;
;             const char* a3 = a2 + kstep; const char* b3 = b2 + kstep;
;             PG8_LDB(B0, 0, 0); PG8_SCHED; PG8_LDA(At, 0, 0); PG8_STAGE(PG8_SA(1, 1), a1 + hstepA, voffA);
;             PG8_WAIT_L(8); PG8_BAR; PG8_WAIT_L(0); PG8_MMA(0, 0, At, B0); PG8_BAR; PG8_SCHED;
;             PG8_LDB(B1, 0, 1); PG8_STAGE(PG8_SB(0, 0), b2, voffB);
;             PG8_BAR; PG8_WAIT_L(0); PG8_MMA(0, 1, At, B1); PG8_BAR;
;             PG8_LDA(At, 0, 1); PG8_STAGE(PG8_SA(0, 0), a2, voffA);
;             PG8_BAR; PG8_WAIT_L(0); PG8_MMA(1, 0, At, B0); PG8_BAR; PG8_SCHED;
;             PG8_STAGE(PG8_SB(0, 1), b2 + hstepB, voffB);
;             PG8_WAIT_V(6); PG8_BAR; PG8_MMA(1, 1, At, B1); PG8_BAR;
.LBB0_146:
	s_ashr_i32 s41, s40, 31
	s_lshl_b64 s[20:21], s[40:41], 20
	v_cmp_lt_i64_e32 vcc, s[42:43], v[208:209]
	s_add_u32 s42, s70, s20
	s_addc_u32 s43, s69, s21
	s_and_b64 s[20:21], vcc, exec
	s_cselect_b32 s41, s43, s27
	s_cselect_b32 s29, s42, s26
	s_ashr_i32 s1, s0, 31
	s_lshl_b64 s[20:21], s[0:1], 20
	s_add_u32 s44, s65, s20
	s_addc_u32 s45, s68, s21
	s_and_b64 s[20:21], vcc, exec
	s_cselect_b32 s1, s45, s47
	s_cselect_b32 s20, s44, s46
	s_add_u32 s26, s26, 0x80080
	s_addc_u32 s27, s27, 0
	s_add_u32 s21, s46, 0x100
	s_addc_u32 s50, s47, 0
	s_mov_b32 s51, -2
	s_add_u32 s46, s26, 0xfff80080
	s_addc_u32 s47, s27, -1
	s_add_i32 s60, 0, 0x10000
	v_add_u32_e32 v144, s60, v147
	ds_read_b128 v[140:143], v144
	ds_read_b128 v[150:153], v144 offset:1024
	ds_read_b128 v[154:157], v144 offset:2048
	ds_read_b128 v[158:161], v144 offset:3072
	s_cmp_eq_u32 s51, 28
	s_cselect_b32 s49, s41, s47
	s_cselect_b32 s48, s29, s46
	s_cselect_b32 s47, s1, s50
	s_cselect_b32 s46, s20, s21
	v_lshl_add_u64 v[144:145], s[26:27], 0, v[136:137]
	s_add_i32 m0, s23, 0xc000
	ds_read_b128 v[162:165], v149
	ds_read_b128 v[166:169], v149 offset:1024
	ds_read_b128 v[170:173], v149 offset:2048
	ds_read_b128 v[174:177], v149 offset:3072
	ds_read_b128 v[178:181], v149 offset:4096
	ds_read_b128 v[182:185], v149 offset:5120
	ds_read_b128 v[186:189], v149 offset:6144
	ds_read_b128 v[190:193], v149 offset:7168
	global_load_lds_dwordx4 v[144:145], off
	v_lshl_add_u64 v[144:145], s[26:27], 0, v[138:139]
	s_add_i32 m0, s23, 0xe000
	s_nop 0
	global_load_lds_dwordx4 v[144:145], off
	s_waitcnt lgkmcnt(11)
	s_add_i32 s66, 0, 0x14000
	v_add_u32_e32 v144, s66, v147
	s_add_i32 s60, s60, s64
	ds_read_b128 v[194:197], v144
	ds_read_b128 v[198:201], v144 offset:1024
	ds_read_b128 v[202:205], v144 offset:2048
	ds_read_b128 v[220:223], v144 offset:3072
	s_waitcnt vmcnt(8) lgkmcnt(0)
	s_barrier
	v_mfma_f32_16x16x32_f16 v[126:129], v[140:143], v[162:165], 0
	v_mfma_f32_16x16x32_f16 v[122:125], v[154:157], v[162:165], 0
	v_mfma_f32_16x16x32_f16 v[110:113], v[140:143], v[170:173], 0
	v_mfma_f32_16x16x32_f16 v[106:109], v[154:157], v[170:173], 0
	v_mfma_f32_16x16x32_f16 v[94:97], v[140:143], v[178:181], 0
	v_mfma_f32_16x16x32_f16 v[90:93], v[154:157], v[178:181], 0
	v_mfma_f32_16x16x32_f16 v[78:81], v[140:143], v[186:189], 0
	v_mfma_f32_16x16x32_f16 v[74:77], v[154:157], v[186:189], 0
	v_mfma_f32_16x16x32_f16 v[126:129], v[150:153], v[166:169], v[126:129]
	v_mfma_f32_16x16x32_f16 v[122:125], v[158:161], v[166:169], v[122:125]
	v_mfma_f32_16x16x32_f16 v[110:113], v[150:153], v[174:177], v[110:113]
	v_mfma_f32_16x16x32_f16 v[106:109], v[158:161], v[174:177], v[106:109]
	v_mfma_f32_16x16x32_f16 v[94:97], v[150:153], v[182:185], v[94:97]
	v_mfma_f32_16x16x32_f16 v[90:93], v[158:161], v[182:185], v[90:93]
	v_mfma_f32_16x16x32_f16 v[78:81], v[150:153], v[190:193], v[78:81]
	v_mfma_f32_16x16x32_f16 v[74:77], v[158:161], v[190:193], v[74:77]
	v_mfma_f32_16x16x32_f16 v[118:121], v[194:197], v[162:165], 0
	v_mfma_f32_16x16x32_f16 v[114:117], v[202:205], v[162:165], 0
	v_mfma_f32_16x16x32_f16 v[102:105], v[194:197], v[170:173], 0
	v_mfma_f32_16x16x32_f16 v[98:101], v[202:205], v[170:173], 0
	v_mfma_f32_16x16x32_f16 v[86:89], v[194:197], v[178:181], 0
	v_mfma_f32_16x16x32_f16 v[82:85], v[202:205], v[178:181], 0
	v_mfma_f32_16x16x32_f16 v[70:73], v[194:197], v[186:189], 0
	v_mfma_f32_16x16x32_f16 v[66:69], v[202:205], v[186:189], 0
	v_mfma_f32_16x16x32_f16 v[118:121], v[198:201], v[166:169], v[118:121]
	v_mfma_f32_16x16x32_f16 v[114:117], v[220:223], v[166:169], v[114:117]
	v_mfma_f32_16x16x32_f16 v[102:105], v[198:201], v[174:177], v[102:105]
	v_mfma_f32_16x16x32_f16 v[98:101], v[220:223], v[174:177], v[98:101]
	v_mfma_f32_16x16x32_f16 v[86:89], v[198:201], v[182:185], v[86:89]
	v_mfma_f32_16x16x32_f16 v[82:85], v[220:223], v[182:185], v[82:85]
	v_mfma_f32_16x16x32_f16 v[70:73], v[198:201], v[190:193], v[70:73]
	v_mfma_f32_16x16x32_f16 v[66:69], v[220:223], v[190:193], v[66:69]
	s_barrier
	v_lshl_add_u64 v[144:145], s[46:47], 0, v[0:1]
	s_mov_b32 m0, s60
	v_lshl_add_u64 v[206:207], s[46:47], 0, v[134:135]
	global_load_lds_dwordx4 v[144:145], off
	s_add_i32 m0, s60, 0x2000
	s_nop 0
	global_load_lds_dwordx4 v[206:207], off
	s_mov_b32 m0, s23
	v_lshl_add_u64 v[212:213], s[48:49], 0, v[130:131]
	ds_read_b128 v[162:165], v149 offset:16384
	ds_read_b128 v[166:169], v149 offset:17408
	ds_read_b128 v[170:173], v149 offset:18432
	ds_read_b128 v[174:177], v149 offset:19456
	ds_read_b128 v[178:181], v149 offset:20480
	ds_read_b128 v[182:185], v149 offset:21504
	ds_read_b128 v[186:189], v149 offset:22528
	ds_read_b128 v[190:193], v149 offset:23552
	global_load_lds_dwordx4 v[212:213], off
	v_lshl_add_u64 v[214:215], s[48:49], 0, v[132:133]
	s_mov_b32 m0, s71
	s_nop 0
	global_load_lds_dwordx4 v[214:215], off
	s_add_u32 s78, s46, 0x80000
	s_addc_u32 s79, s47, 0
	s_add_i32 s60, s66, s64
	v_lshl_add_u64 v[232:233], s[78:79], 0, v[0:1]
	s_mov_b32 m0, s60
	s_nop 0
	global_load_lds_dwordx4 v[232:233], off
	v_lshl_add_u64 v[232:233], s[78:79], 0, v[134:135]
	s_add_i32 m0, s60, 0x2000
	s_nop 0
	global_load_lds_dwordx4 v[232:233], off
	s_waitcnt vmcnt(8) lgkmcnt(0)
	s_barrier
; #define PG8_STAGE(bufoff, gbase, voff) do { _Pragma("unroll") for (int _i = 0; _i < 2; ++_i) \
;         __builtin_amdgcn_global_load_lds((const unsigned*)((const char*)(gbase) + (voff)[_i]), (LAS unsigned*)(lds + (bufoff) + ldsw + _i * 8192), 16, 0, 0); } while (0)
; #define PG8_LDA(dst, b, h) do { _Pragma("unroll") for (int m = 0; m < 4; ++m) _Pragma("unroll") for (int k = 0; k < 2; ++k) dst[m][k] = *(const LAS h16x8*)(lds + PG8_SA(b, h) + aoff + m * 2048 + k * 1024); } while (0)
; #define PG8_LDB(dst, b, h) do { _Pragma("unroll") for (int n = 0; n < 2; ++n) _Pragma("unroll") for (int k = 0; k < 2; ++k) dst[n][k] = *(const LAS h16x8*)(lds + PG8_SB(b, h) + boff + n * 2048 + k * 1024); } while (0)
; #define PG8_MMA(ai, bj, At, Bt_) do { __builtin_amdgcn_s_setprio(1); _Pragma("unroll") for (int m = 0; m < 4; ++m) _Pragma("unroll") for (int n = 0; n < 2; ++n) _Pragma("unroll") for (int k = 0; k < 2; ++k) \
;         acc[ai][bj][m][n] = __builtin_amdgcn_mfma_f32_16x16x32_f16(Bt_[n][k], At[m][k], acc[ai][bj][m][n], 0, 0, 0); __builtin_amdgcn_s_setprio(0); } while (0)
; #define PG8_WAIT_V(n) asm volatile("s_waitcnt vmcnt(" #n ")" ::: "memory")
; #define PG8_WAIT_L(n) asm volatile("s_waitcnt lgkmcnt(" #n ")" ::: "memory")
; #define PG8_BAR __builtin_amdgcn_s_barrier()
; #define PG8_SCHED __builtin_amdgcn_sched_barrier(0)
; template <class Epi, class AMap>
; __device__ __forceinline__ void gemm_phase(LAS unsigned char* lds, const AMap am, const int lda, const h16* Bt, const int ldb, const int M, const int N, const int K, const Epi& E) {
;     ...
;             PG8_WAIT_V(6); PG8_BAR; PG8_MMA(1, 1, At, B1); PG8_BAR;
;             PG8_LDB(B0, 1, 0); PG8_SCHED; PG8_LDA(At, 1, 0); PG8_STAGE(PG8_SA(0, 1), a2 + hstepA, voffA);
;             PG8_WAIT_L(8); PG8_BAR; PG8_WAIT_L(0); PG8_MMA(0, 0, At, B0); PG8_BAR; PG8_SCHED;
;             PG8_LDB(B1, 1, 1); PG8_STAGE(PG8_SB(1, 0), b3, voffB);
;             PG8_BAR; PG8_WAIT_L(0); PG8_MMA(0, 1, At, B1); PG8_BAR;
;             PG8_LDA(At, 1, 1); PG8_STAGE(PG8_SA(1, 0), a3, voffA);
;             PG8_BAR; PG8_WAIT_L(0); PG8_MMA(1, 0, At, B0); PG8_BAR; PG8_SCHED;
	v_mfma_f32_16x16x32_f16 v[62:65], v[140:143], v[162:165], 0
	v_mfma_f32_16x16x32_f16 v[58:61], v[154:157], v[162:165], 0
	v_mfma_f32_16x16x32_f16 v[46:49], v[140:143], v[170:173], 0
	v_mfma_f32_16x16x32_f16 v[42:45], v[154:157], v[170:173], 0
	v_mfma_f32_16x16x32_f16 v[30:33], v[140:143], v[178:181], 0
	v_mfma_f32_16x16x32_f16 v[26:29], v[154:157], v[178:181], 0
	v_mfma_f32_16x16x32_f16 v[14:17], v[140:143], v[186:189], 0
	v_mfma_f32_16x16x32_f16 v[10:13], v[154:157], v[186:189], 0
	v_mfma_f32_16x16x32_f16 v[62:65], v[150:153], v[166:169], v[62:65]
	v_mfma_f32_16x16x32_f16 v[58:61], v[158:161], v[166:169], v[58:61]
	v_mfma_f32_16x16x32_f16 v[46:49], v[150:153], v[174:177], v[46:49]
	v_mfma_f32_16x16x32_f16 v[42:45], v[158:161], v[174:177], v[42:45]
	v_mfma_f32_16x16x32_f16 v[30:33], v[150:153], v[182:185], v[30:33]
	v_mfma_f32_16x16x32_f16 v[26:29], v[158:161], v[182:185], v[26:29]
	v_mfma_f32_16x16x32_f16 v[14:17], v[150:153], v[190:193], v[14:17]
	v_mfma_f32_16x16x32_f16 v[10:13], v[158:161], v[190:193], v[10:13]
	v_mfma_f32_16x16x32_f16 v[54:57], v[194:197], v[162:165], 0
	v_mfma_f32_16x16x32_f16 v[50:53], v[202:205], v[162:165], 0
	v_mfma_f32_16x16x32_f16 v[38:41], v[194:197], v[170:173], 0
	v_mfma_f32_16x16x32_f16 v[34:37], v[202:205], v[170:173], 0
	v_mfma_f32_16x16x32_f16 v[22:25], v[194:197], v[178:181], 0
	v_mfma_f32_16x16x32_f16 v[18:21], v[202:205], v[178:181], 0
	v_mfma_f32_16x16x32_f16 v[6:9], v[194:197], v[186:189], 0
	v_mfma_f32_16x16x32_f16 v[2:5], v[202:205], v[186:189], 0
	v_mfma_f32_16x16x32_f16 v[54:57], v[198:201], v[166:169], v[54:57]
	v_mfma_f32_16x16x32_f16 v[50:53], v[220:223], v[166:169], v[50:53]
	v_mfma_f32_16x16x32_f16 v[38:41], v[198:201], v[174:177], v[38:41]
	v_mfma_f32_16x16x32_f16 v[34:37], v[220:223], v[174:177], v[34:37]
	v_mfma_f32_16x16x32_f16 v[22:25], v[198:201], v[182:185], v[22:25]
	v_mfma_f32_16x16x32_f16 v[18:21], v[220:223], v[182:185], v[18:21]
	v_mfma_f32_16x16x32_f16 v[6:9], v[198:201], v[190:193], v[6:9]
	v_mfma_f32_16x16x32_f16 v[2:5], v[220:223], v[190:193], v[2:5]
	s_barrier
	s_add_i32 s60, 0, 0x18000
	v_add_u32_e32 v234, s60, v147
	ds_read_b128 v[140:143], v234
	ds_read_b128 v[150:153], v234 offset:1024
	ds_read_b128 v[154:157], v234 offset:2048
	ds_read_b128 v[158:161], v234 offset:3072
	s_add_u32 s48, s48, 0x80000
	s_addc_u32 s49, s49, 0
	s_mov_b32 m0, s72
	v_lshl_add_u64 v[232:233], s[48:49], 0, v[130:131]
	ds_read_b128 v[162:165], v149 offset:32768
	ds_read_b128 v[166:169], v149 offset:33792
	ds_read_b128 v[170:173], v149 offset:34816
	ds_read_b128 v[174:177], v149 offset:35840
	ds_read_b128 v[178:181], v149 offset:36864
	ds_read_b128 v[182:185], v149 offset:37888
	ds_read_b128 v[186:189], v149 offset:38912
	ds_read_b128 v[190:193], v149 offset:39936
	global_load_lds_dwordx4 v[232:233], off
	v_lshl_add_u64 v[232:233], s[48:49], 0, v[132:133]
	s_mov_b32 m0, s73
	s_nop 0
	global_load_lds_dwordx4 v[232:233], off
	s_waitcnt lgkmcnt(11)
	s_add_i32 s48, 0, 0x1c000
	s_add_i32 s49, s60, s64
	v_add_u32_e32 v216, s48, v147
	v_lshl_add_u64 v[144:145], v[144:145], 0, s[92:93]
	s_mov_b32 m0, s49
	ds_read_b128 v[194:197], v216
	ds_read_b128 v[198:201], v216 offset:1024
	ds_read_b128 v[202:205], v216 offset:2048
	ds_read_b128 v[220:223], v216 offset:3072
	s_waitcnt vmcnt(8) lgkmcnt(0)
	s_barrier
	v_mfma_f32_16x16x32_f16 v[126:129], v[140:143], v[162:165], v[126:129]
	v_mfma_f32_16x16x32_f16 v[122:125], v[154:157], v[162:165], v[122:125]
	v_mfma_f32_16x16x32_f16 v[110:113], v[140:143], v[170:173], v[110:113]
	v_mfma_f32_16x16x32_f16 v[106:109], v[154:157], v[170:173], v[106:109]
	v_mfma_f32_16x16x32_f16 v[94:97], v[140:143], v[178:181], v[94:97]
	v_mfma_f32_16x16x32_f16 v[90:93], v[154:157], v[178:181], v[90:93]
	v_mfma_f32_16x16x32_f16 v[78:81], v[140:143], v[186:189], v[78:81]
	v_mfma_f32_16x16x32_f16 v[74:77], v[154:157], v[186:189], v[74:77]
	v_mfma_f32_16x16x32_f16 v[126:129], v[150:153], v[166:169], v[126:129]
	v_mfma_f32_16x16x32_f16 v[122:125], v[158:161], v[166:169], v[122:125]
	v_mfma_f32_16x16x32_f16 v[110:113], v[150:153], v[174:177], v[110:113]
	v_mfma_f32_16x16x32_f16 v[106:109], v[158:161], v[174:177], v[106:109]
	v_mfma_f32_16x16x32_f16 v[94:97], v[150:153], v[182:185], v[94:97]
	v_mfma_f32_16x16x32_f16 v[90:93], v[158:161], v[182:185], v[90:93]
	v_mfma_f32_16x16x32_f16 v[78:81], v[150:153], v[190:193], v[78:81]
	v_mfma_f32_16x16x32_f16 v[74:77], v[158:161], v[190:193], v[74:77]
	v_mfma_f32_16x16x32_f16 v[118:121], v[194:197], v[162:165], v[118:121]
	v_mfma_f32_16x16x32_f16 v[114:117], v[202:205], v[162:165], v[114:117]
	v_mfma_f32_16x16x32_f16 v[102:105], v[194:197], v[170:173], v[102:105]
	v_mfma_f32_16x16x32_f16 v[98:101], v[202:205], v[170:173], v[98:101]
	v_mfma_f32_16x16x32_f16 v[86:89], v[194:197], v[178:181], v[86:89]
	v_mfma_f32_16x16x32_f16 v[82:85], v[202:205], v[178:181], v[82:85]
	v_mfma_f32_16x16x32_f16 v[70:73], v[194:197], v[186:189], v[70:73]
	v_mfma_f32_16x16x32_f16 v[66:69], v[202:205], v[186:189], v[66:69]
	v_mfma_f32_16x16x32_f16 v[118:121], v[198:201], v[166:169], v[118:121]
	v_mfma_f32_16x16x32_f16 v[114:117], v[220:223], v[166:169], v[114:117]
	v_mfma_f32_16x16x32_f16 v[102:105], v[198:201], v[174:177], v[102:105]
	v_mfma_f32_16x16x32_f16 v[98:101], v[220:223], v[174:177], v[98:101]
	v_mfma_f32_16x16x32_f16 v[86:89], v[198:201], v[182:185], v[86:89]
	v_mfma_f32_16x16x32_f16 v[82:85], v[220:223], v[182:185], v[82:85]
	v_mfma_f32_16x16x32_f16 v[70:73], v[198:201], v[190:193], v[70:73]
	v_mfma_f32_16x16x32_f16 v[66:69], v[220:223], v[190:193], v[66:69]
	s_barrier
; #define PG8_STAGE(bufoff, gbase, voff) do { _Pragma("unroll") for (int _i = 0; _i < 2; ++_i) \
;         __builtin_amdgcn_global_load_lds((const unsigned*)((const char*)(gbase) + (voff)[_i]), (LAS unsigned*)(lds + (bufoff) + ldsw + _i * 8192), 16, 0, 0); } while (0)
; #define PG8_LDA(dst, b, h) do { _Pragma("unroll") for (int m = 0; m < 4; ++m) _Pragma("unroll") for (int k = 0; k < 2; ++k) dst[m][k] = *(const LAS h16x8*)(lds + PG8_SA(b, h) + aoff + m * 2048 + k * 1024); } while (0)
; #define PG8_LDB(dst, b, h) do { _Pragma("unroll") for (int n = 0; n < 2; ++n) _Pragma("unroll") for (int k = 0; k < 2; ++k) dst[n][k] = *(const LAS h16x8*)(lds + PG8_SB(b, h) + boff + n * 2048 + k * 1024); } while (0)
; #define PG8_MMA(ai, bj, At, Bt_) do { __builtin_amdgcn_s_setprio(1); _Pragma("unroll") for (int m = 0; m < 4; ++m) _Pragma("unroll") for (int n = 0; n < 2; ++n) _Pragma("unroll") for (int k = 0; k < 2; ++k) \
;         acc[ai][bj][m][n] = __builtin_amdgcn_mfma_f32_16x16x32_f16(Bt_[n][k], At[m][k], acc[ai][bj][m][n], 0, 0, 0); __builtin_amdgcn_s_setprio(0); } while (0)
; #define PG8_WAIT_V(n) asm volatile("s_waitcnt vmcnt(" #n ")" ::: "memory")
; #define PG8_WAIT_L(n) asm volatile("s_waitcnt lgkmcnt(" #n ")" ::: "memory")
; #define PG8_BAR __builtin_amdgcn_s_barrier()
; #define PG8_SCHED __builtin_amdgcn_sched_barrier(0)
; template <class Epi, class AMap>
; __device__ __forceinline__ void gemm_phase(LAS unsigned char* lds, const AMap am, const int lda, const h16* Bt, const int ldb, const int M, const int N, const int K, const Epi& E) {
;     ...
;         for (int t = 0; t < nt; t += 2) {
;             const bool last = (t == nt - 2);
;             const char* a1 = cA + (size_t)(t + 1) * kstep;
;             const char* a2 = last ? nA : cA + (size_t)(t + 2) * kstep; const char* b2 = last ? nB : cB + (size_t)(t + 2) * kstep;
;             const char* a3 = a2 + kstep; const char* b3 = b2 + kstep;
;             PG8_LDB(B0, 0, 0); PG8_SCHED; PG8_LDA(At, 0, 0); PG8_STAGE(PG8_SA(1, 1), a1 + hstepA, voffA);
;             PG8_WAIT_L(8); PG8_BAR; PG8_WAIT_L(0); PG8_MMA(0, 0, At, B0); PG8_BAR; PG8_SCHED;
;     ...
;             PG8_LDA(At, 1, 1); PG8_STAGE(PG8_SA(1, 0), a3, voffA);
;             PG8_BAR; PG8_WAIT_L(0); PG8_MMA(1, 0, At, B0); PG8_BAR; PG8_SCHED;
;             PG8_STAGE(PG8_SB(1, 1), b3 + hstepB, voffB);
;             PG8_WAIT_V(6); PG8_BAR; PG8_MMA(1, 1, At, B1); PG8_BAR;
	global_load_lds_dwordx4 v[144:145], off
	v_lshl_add_u64 v[144:145], v[206:207], 0, s[92:93]
	s_add_i32 m0, s49, 0x2000
	s_nop 0
	global_load_lds_dwordx4 v[144:145], off
	s_mov_b32 m0, s74
	v_lshl_add_u64 v[144:145], v[212:213], 0, s[92:93]
	ds_read_b128 v[162:165], v149 offset:49152
	ds_read_b128 v[166:169], v149 offset:50176
	ds_read_b128 v[170:173], v149 offset:51200
	ds_read_b128 v[174:177], v149 offset:52224
	ds_read_b128 v[178:181], v149 offset:53248
	ds_read_b128 v[182:185], v149 offset:54272
	ds_read_b128 v[186:189], v149 offset:55296
	ds_read_b128 v[190:193], v149 offset:56320
	global_load_lds_dwordx4 v[144:145], off
	v_lshl_add_u64 v[144:145], v[214:215], 0, s[92:93]
	s_mov_b32 m0, s75
	s_nop 0
	global_load_lds_dwordx4 v[144:145], off
	s_add_u32 s46, s46, 0x80080
	s_addc_u32 s47, s47, 0
	s_add_i32 s48, s48, s64
	v_lshl_add_u64 v[232:233], s[46:47], 0, v[0:1]
	s_mov_b32 m0, s48
	s_nop 0
	global_load_lds_dwordx4 v[232:233], off
	v_lshl_add_u64 v[232:233], s[46:47], 0, v[134:135]
	s_add_i32 m0, s48, 0x2000
	s_nop 0
	global_load_lds_dwordx4 v[232:233], off
	s_add_i32 s51, s51, 2
	s_add_u32 s26, s26, 0x100
	s_addc_u32 s27, s27, 0
	s_add_u32 s21, s21, 0x100
	s_addc_u32 s50, s50, 0
	s_cmp_gt_u32 s51, 29
	s_waitcnt vmcnt(8) lgkmcnt(0)
	s_barrier
	v_mfma_f32_16x16x32_f16 v[62:65], v[140:143], v[162:165], v[62:65]
	v_mfma_f32_16x16x32_f16 v[58:61], v[154:157], v[162:165], v[58:61]
	v_mfma_f32_16x16x32_f16 v[46:49], v[140:143], v[170:173], v[46:49]
	v_mfma_f32_16x16x32_f16 v[42:45], v[154:157], v[170:173], v[42:45]
	v_mfma_f32_16x16x32_f16 v[30:33], v[140:143], v[178:181], v[30:33]
	v_mfma_f32_16x16x32_f16 v[26:29], v[154:157], v[178:181], v[26:29]
	v_mfma_f32_16x16x32_f16 v[14:17], v[140:143], v[186:189], v[14:17]
	v_mfma_f32_16x16x32_f16 v[10:13], v[154:157], v[186:189], v[10:13]
	v_mfma_f32_16x16x32_f16 v[62:65], v[150:153], v[166:169], v[62:65]
	v_mfma_f32_16x16x32_f16 v[58:61], v[158:161], v[166:169], v[58:61]
	v_mfma_f32_16x16x32_f16 v[46:49], v[150:153], v[174:177], v[46:49]
	v_mfma_f32_16x16x32_f16 v[42:45], v[158:161], v[174:177], v[42:45]
	v_mfma_f32_16x16x32_f16 v[30:33], v[150:153], v[182:185], v[30:33]
	v_mfma_f32_16x16x32_f16 v[26:29], v[158:161], v[182:185], v[26:29]
	v_mfma_f32_16x16x32_f16 v[14:17], v[150:153], v[190:193], v[14:17]
	v_mfma_f32_16x16x32_f16 v[10:13], v[158:161], v[190:193], v[10:13]
	v_mfma_f32_16x16x32_f16 v[54:57], v[194:197], v[162:165], v[54:57]
	v_mfma_f32_16x16x32_f16 v[50:53], v[202:205], v[162:165], v[50:53]
	v_mfma_f32_16x16x32_f16 v[38:41], v[194:197], v[170:173], v[38:41]
	v_mfma_f32_16x16x32_f16 v[34:37], v[202:205], v[170:173], v[34:37]
	v_mfma_f32_16x16x32_f16 v[22:25], v[194:197], v[178:181], v[22:25]
	v_mfma_f32_16x16x32_f16 v[18:21], v[202:205], v[178:181], v[18:21]
	v_mfma_f32_16x16x32_f16 v[6:9], v[194:197], v[186:189], v[6:9]
	v_mfma_f32_16x16x32_f16 v[2:5], v[202:205], v[186:189], v[2:5]
	v_mfma_f32_16x16x32_f16 v[54:57], v[198:201], v[166:169], v[54:57]
	v_mfma_f32_16x16x32_f16 v[50:53], v[220:223], v[166:169], v[50:53]
	v_mfma_f32_16x16x32_f16 v[38:41], v[198:201], v[174:177], v[38:41]
	v_mfma_f32_16x16x32_f16 v[34:37], v[220:223], v[174:177], v[34:37]
	v_mfma_f32_16x16x32_f16 v[22:25], v[198:201], v[182:185], v[22:25]
	v_mfma_f32_16x16x32_f16 v[18:21], v[220:223], v[182:185], v[18:21]
	v_mfma_f32_16x16x32_f16 v[6:9], v[198:201], v[190:193], v[6:9]
	v_mfma_f32_16x16x32_f16 v[2:5], v[220:223], v[190:193], v[2:5]
	s_barrier
	s_cbranch_scc1 .Lg4x_147
.LBB0_147:
	s_add_u32 s46, s26, 0xfff80080
	s_addc_u32 s47, s27, -1
	s_add_i32 s60, 0, 0x10000
	v_add_u32_e32 v144, s60, v147
	ds_read_b128 v[140:143], v144
	ds_read_b128 v[150:153], v144 offset:1024
	ds_read_b128 v[154:157], v144 offset:2048
	ds_read_b128 v[158:161], v144 offset:3072
	s_cmp_eq_u32 s51, 28
	s_cselect_b32 s49, s41, s47
	s_cselect_b32 s48, s29, s46
	s_cselect_b32 s47, s1, s50
	s_cselect_b32 s46, s20, s21
	v_lshl_add_u64 v[144:145], s[26:27], 0, v[136:137]
	s_add_i32 m0, s23, 0xc000
	ds_read_b128 v[162:165], v149
	ds_read_b128 v[166:169], v149 offset:1024
	ds_read_b128 v[170:173], v149 offset:2048
	ds_read_b128 v[174:177], v149 offset:3072
	ds_read_b128 v[178:181], v149 offset:4096
	ds_read_b128 v[182:185], v149 offset:5120
	ds_read_b128 v[186:189], v149 offset:6144
	ds_read_b128 v[190:193], v149 offset:7168
	global_load_lds_dwordx4 v[144:145], off
	v_lshl_add_u64 v[144:145], s[26:27], 0, v[138:139]
	s_add_i32 m0, s23, 0xe000
	s_nop 0
	global_load_lds_dwordx4 v[144:145], off
	s_waitcnt lgkmcnt(11)
	s_add_i32 s66, 0, 0x14000
	v_add_u32_e32 v144, s66, v147
	s_add_i32 s60, s60, s64
	ds_read_b128 v[194:197], v144
	ds_read_b128 v[198:201], v144 offset:1024
	ds_read_b128 v[202:205], v144 offset:2048
	ds_read_b128 v[220:223], v144 offset:3072
	s_waitcnt vmcnt(8) lgkmcnt(0)
	s_barrier
; #define PG8_STAGE(bufoff, gbase, voff) do { _Pragma("unroll") for (int _i = 0; _i < 2; ++_i) \
;         __builtin_amdgcn_global_load_lds((const unsigned*)((const char*)(gbase) + (voff)[_i]), (LAS unsigned*)(lds + (bufoff) + ldsw + _i * 8192), 16, 0, 0); } while (0)
; #define PG8_LDA(dst, b, h) do { _Pragma("unroll") for (int m = 0; m < 4; ++m) _Pragma("unroll") for (int k = 0; k < 2; ++k) dst[m][k] = *(const LAS h16x8*)(lds + PG8_SA(b, h) + aoff + m * 2048 + k * 1024); } while (0)
; #define PG8_LDB(dst, b, h) do { _Pragma("unroll") for (int n = 0; n < 2; ++n) _Pragma("unroll") for (int k = 0; k < 2; ++k) dst[n][k] = *(const LAS h16x8*)(lds + PG8_SB(b, h) + boff + n * 2048 + k * 1024); } while (0)
; #define PG8_MMA(ai, bj, At, Bt_) do { __builtin_amdgcn_s_setprio(1); _Pragma("unroll") for (int m = 0; m < 4; ++m) _Pragma("unroll") for (int n = 0; n < 2; ++n) _Pragma("unroll") for (int k = 0; k < 2; ++k) \
;         acc[ai][bj][m][n] = __builtin_amdgcn_mfma_f32_16x16x32_f16(Bt_[n][k], At[m][k], acc[ai][bj][m][n], 0, 0, 0); __builtin_amdgcn_s_setprio(0); } while (0)
; #define PG8_WAIT_V(n) asm volatile("s_waitcnt vmcnt(" #n ")" ::: "memory")
; #define PG8_WAIT_L(n) asm volatile("s_waitcnt lgkmcnt(" #n ")" ::: "memory")
; #define PG8_BAR __builtin_amdgcn_s_barrier()
; #define PG8_SCHED __builtin_amdgcn_sched_barrier(0)
; template <class Epi, class AMap>
; __device__ __forceinline__ void gemm_phase(LAS unsigned char* lds, const AMap am, const int lda, const h16* Bt, const int ldb, const int M, const int N, const int K, const Epi& E) {
;     ...
;             PG8_LDB(B0, 0, 0); PG8_SCHED; PG8_LDA(At, 0, 0); PG8_STAGE(PG8_SA(1, 1), a1 + hstepA, voffA);
;             PG8_WAIT_L(8); PG8_BAR; PG8_WAIT_L(0); PG8_MMA(0, 0, At, B0); PG8_BAR; PG8_SCHED;
;             PG8_LDB(B1, 0, 1); PG8_STAGE(PG8_SB(0, 0), b2, voffB);
;             PG8_BAR; PG8_WAIT_L(0); PG8_MMA(0, 1, At, B1); PG8_BAR;
;             PG8_LDA(At, 0, 1); PG8_STAGE(PG8_SA(0, 0), a2, voffA);
;             PG8_BAR; PG8_WAIT_L(0); PG8_MMA(1, 0, At, B0); PG8_BAR; PG8_SCHED;
;             PG8_STAGE(PG8_SB(0, 1), b2 + hstepB, voffB);
;             PG8_WAIT_V(6); PG8_BAR; PG8_MMA(1, 1, At, B1); PG8_BAR;
	v_mfma_f32_16x16x32_f16 v[126:129], v[140:143], v[162:165], v[126:129]
	v_mfma_f32_16x16x32_f16 v[122:125], v[154:157], v[162:165], v[122:125]
	v_mfma_f32_16x16x32_f16 v[110:113], v[140:143], v[170:173], v[110:113]
	v_mfma_f32_16x16x32_f16 v[106:109], v[154:157], v[170:173], v[106:109]
	v_mfma_f32_16x16x32_f16 v[94:97], v[140:143], v[178:181], v[94:97]
	v_mfma_f32_16x16x32_f16 v[90:93], v[154:157], v[178:181], v[90:93]
	v_mfma_f32_16x16x32_f16 v[78:81], v[140:143], v[186:189], v[78:81]
	v_mfma_f32_16x16x32_f16 v[74:77], v[154:157], v[186:189], v[74:77]
	v_mfma_f32_16x16x32_f16 v[126:129], v[150:153], v[166:169], v[126:129]
	v_mfma_f32_16x16x32_f16 v[122:125], v[158:161], v[166:169], v[122:125]
	v_mfma_f32_16x16x32_f16 v[110:113], v[150:153], v[174:177], v[110:113]
	v_mfma_f32_16x16x32_f16 v[106:109], v[158:161], v[174:177], v[106:109]
	v_mfma_f32_16x16x32_f16 v[94:97], v[150:153], v[182:185], v[94:97]
	v_mfma_f32_16x16x32_f16 v[90:93], v[158:161], v[182:185], v[90:93]
	v_mfma_f32_16x16x32_f16 v[78:81], v[150:153], v[190:193], v[78:81]
	v_mfma_f32_16x16x32_f16 v[74:77], v[158:161], v[190:193], v[74:77]
	v_mfma_f32_16x16x32_f16 v[118:121], v[194:197], v[162:165], v[118:121]
	v_mfma_f32_16x16x32_f16 v[114:117], v[202:205], v[162:165], v[114:117]
	v_mfma_f32_16x16x32_f16 v[102:105], v[194:197], v[170:173], v[102:105]
	v_mfma_f32_16x16x32_f16 v[98:101], v[202:205], v[170:173], v[98:101]
	v_mfma_f32_16x16x32_f16 v[86:89], v[194:197], v[178:181], v[86:89]
	v_mfma_f32_16x16x32_f16 v[82:85], v[202:205], v[178:181], v[82:85]
	v_mfma_f32_16x16x32_f16 v[70:73], v[194:197], v[186:189], v[70:73]
	v_mfma_f32_16x16x32_f16 v[66:69], v[202:205], v[186:189], v[66:69]
	v_mfma_f32_16x16x32_f16 v[118:121], v[198:201], v[166:169], v[118:121]
	v_mfma_f32_16x16x32_f16 v[114:117], v[220:223], v[166:169], v[114:117]
	v_mfma_f32_16x16x32_f16 v[102:105], v[198:201], v[174:177], v[102:105]
	v_mfma_f32_16x16x32_f16 v[98:101], v[220:223], v[174:177], v[98:101]
	v_mfma_f32_16x16x32_f16 v[86:89], v[198:201], v[182:185], v[86:89]
	v_mfma_f32_16x16x32_f16 v[82:85], v[220:223], v[182:185], v[82:85]
	v_mfma_f32_16x16x32_f16 v[70:73], v[198:201], v[190:193], v[70:73]
	v_mfma_f32_16x16x32_f16 v[66:69], v[220:223], v[190:193], v[66:69]
	s_barrier
	v_lshl_add_u64 v[144:145], s[46:47], 0, v[0:1]
	s_mov_b32 m0, s60
	v_lshl_add_u64 v[206:207], s[46:47], 0, v[134:135]
	global_load_lds_dwordx4 v[144:145], off
	s_add_i32 m0, s60, 0x2000
	s_nop 0
	global_load_lds_dwordx4 v[206:207], off
	s_mov_b32 m0, s23
	v_lshl_add_u64 v[212:213], s[48:49], 0, v[130:131]
	ds_read_b128 v[162:165], v149 offset:16384
	ds_read_b128 v[166:169], v149 offset:17408
	ds_read_b128 v[170:173], v149 offset:18432
	ds_read_b128 v[174:177], v149 offset:19456
	ds_read_b128 v[178:181], v149 offset:20480
	ds_read_b128 v[182:185], v149 offset:21504
	ds_read_b128 v[186:189], v149 offset:22528
	ds_read_b128 v[190:193], v149 offset:23552
	global_load_lds_dwordx4 v[212:213], off
	v_lshl_add_u64 v[214:215], s[48:49], 0, v[132:133]
	s_mov_b32 m0, s71
	s_nop 0
	global_load_lds_dwordx4 v[214:215], off
	s_add_u32 s78, s46, 0x80000
	s_addc_u32 s79, s47, 0
	s_add_i32 s60, s66, s64
	v_lshl_add_u64 v[232:233], s[78:79], 0, v[0:1]
	s_mov_b32 m0, s60
	s_nop 0
	global_load_lds_dwordx4 v[232:233], off
	v_lshl_add_u64 v[232:233], s[78:79], 0, v[134:135]
	s_add_i32 m0, s60, 0x2000
	s_nop 0
	global_load_lds_dwordx4 v[232:233], off
	s_waitcnt vmcnt(8) lgkmcnt(0)
	s_barrier
	v_mfma_f32_16x16x32_f16 v[62:65], v[140:143], v[162:165], v[62:65]
	v_mfma_f32_16x16x32_f16 v[58:61], v[154:157], v[162:165], v[58:61]
	v_mfma_f32_16x16x32_f16 v[46:49], v[140:143], v[170:173], v[46:49]
	v_mfma_f32_16x16x32_f16 v[42:45], v[154:157], v[170:173], v[42:45]
	v_mfma_f32_16x16x32_f16 v[30:33], v[140:143], v[178:181], v[30:33]
	v_mfma_f32_16x16x32_f16 v[26:29], v[154:157], v[178:181], v[26:29]
	v_mfma_f32_16x16x32_f16 v[14:17], v[140:143], v[186:189], v[14:17]
	v_mfma_f32_16x16x32_f16 v[10:13], v[154:157], v[186:189], v[10:13]
	v_mfma_f32_16x16x32_f16 v[62:65], v[150:153], v[166:169], v[62:65]
	v_mfma_f32_16x16x32_f16 v[58:61], v[158:161], v[166:169], v[58:61]
	v_mfma_f32_16x16x32_f16 v[46:49], v[150:153], v[174:177], v[46:49]
	v_mfma_f32_16x16x32_f16 v[42:45], v[158:161], v[174:177], v[42:45]
	v_mfma_f32_16x16x32_f16 v[30:33], v[150:153], v[182:185], v[30:33]
	v_mfma_f32_16x16x32_f16 v[26:29], v[158:161], v[182:185], v[26:29]
	v_mfma_f32_16x16x32_f16 v[14:17], v[150:153], v[190:193], v[14:17]
	v_mfma_f32_16x16x32_f16 v[10:13], v[158:161], v[190:193], v[10:13]
	v_mfma_f32_16x16x32_f16 v[54:57], v[194:197], v[162:165], v[54:57]
	v_mfma_f32_16x16x32_f16 v[50:53], v[202:205], v[162:165], v[50:53]
	v_mfma_f32_16x16x32_f16 v[38:41], v[194:197], v[170:173], v[38:41]
	v_mfma_f32_16x16x32_f16 v[34:37], v[202:205], v[170:173], v[34:37]
	v_mfma_f32_16x16x32_f16 v[22:25], v[194:197], v[178:181], v[22:25]
	v_mfma_f32_16x16x32_f16 v[18:21], v[202:205], v[178:181], v[18:21]
	v_mfma_f32_16x16x32_f16 v[6:9], v[194:197], v[186:189], v[6:9]
	v_mfma_f32_16x16x32_f16 v[2:5], v[202:205], v[186:189], v[2:5]
	v_mfma_f32_16x16x32_f16 v[54:57], v[198:201], v[166:169], v[54:57]
	v_mfma_f32_16x16x32_f16 v[50:53], v[220:223], v[166:169], v[50:53]
	v_mfma_f32_16x16x32_f16 v[38:41], v[198:201], v[174:177], v[38:41]
	v_mfma_f32_16x16x32_f16 v[34:37], v[220:223], v[174:177], v[34:37]
	v_mfma_f32_16x16x32_f16 v[22:25], v[198:201], v[182:185], v[22:25]
	v_mfma_f32_16x16x32_f16 v[18:21], v[220:223], v[182:185], v[18:21]
	v_mfma_f32_16x16x32_f16 v[6:9], v[198:201], v[190:193], v[6:9]
	v_mfma_f32_16x16x32_f16 v[2:5], v[220:223], v[190:193], v[2:5]
	s_barrier
; #define PG8_STAGE(bufoff, gbase, voff) do { _Pragma("unroll") for (int _i = 0; _i < 2; ++_i) \
;         __builtin_amdgcn_global_load_lds((const unsigned*)((const char*)(gbase) + (voff)[_i]), (LAS unsigned*)(lds + (bufoff) + ldsw + _i * 8192), 16, 0, 0); } while (0)
; #define PG8_LDA(dst, b, h) do { _Pragma("unroll") for (int m = 0; m < 4; ++m) _Pragma("unroll") for (int k = 0; k < 2; ++k) dst[m][k] = *(const LAS h16x8*)(lds + PG8_SA(b, h) + aoff + m * 2048 + k * 1024); } while (0)
; #define PG8_LDB(dst, b, h) do { _Pragma("unroll") for (int n = 0; n < 2; ++n) _Pragma("unroll") for (int k = 0; k < 2; ++k) dst[n][k] = *(const LAS h16x8*)(lds + PG8_SB(b, h) + boff + n * 2048 + k * 1024); } while (0)
; #define PG8_MMA(ai, bj, At, Bt_) do { __builtin_amdgcn_s_setprio(1); _Pragma("unroll") for (int m = 0; m < 4; ++m) _Pragma("unroll") for (int n = 0; n < 2; ++n) _Pragma("unroll") for (int k = 0; k < 2; ++k) \
;         acc[ai][bj][m][n] = __builtin_amdgcn_mfma_f32_16x16x32_f16(Bt_[n][k], At[m][k], acc[ai][bj][m][n], 0, 0, 0); __builtin_amdgcn_s_setprio(0); } while (0)
; #define PG8_WAIT_V(n) asm volatile("s_waitcnt vmcnt(" #n ")" ::: "memory")
; #define PG8_WAIT_L(n) asm volatile("s_waitcnt lgkmcnt(" #n ")" ::: "memory")
; #define PG8_BAR __builtin_amdgcn_s_barrier()
; #define PG8_SCHED __builtin_amdgcn_sched_barrier(0)
; template <class Epi, class AMap>
; __device__ __forceinline__ void gemm_phase(LAS unsigned char* lds, const AMap am, const int lda, const h16* Bt, const int ldb, const int M, const int N, const int K, const Epi& E) {
;     ...
;             PG8_LDB(B0, 1, 0); PG8_SCHED; PG8_LDA(At, 1, 0); PG8_STAGE(PG8_SA(0, 1), a2 + hstepA, voffA);
;             PG8_WAIT_L(8); PG8_BAR; PG8_WAIT_L(0); PG8_MMA(0, 0, At, B0); PG8_BAR; PG8_SCHED;
;             PG8_LDB(B1, 1, 1); PG8_STAGE(PG8_SB(1, 0), b3, voffB);
;             PG8_BAR; PG8_WAIT_L(0); PG8_MMA(0, 1, At, B1); PG8_BAR;
;             PG8_LDA(At, 1, 1); PG8_STAGE(PG8_SA(1, 0), a3, voffA);
;             PG8_BAR; PG8_WAIT_L(0); PG8_MMA(1, 0, At, B0); PG8_BAR; PG8_SCHED;
;             PG8_STAGE(PG8_SB(1, 1), b3 + hstepB, voffB);
;             PG8_WAIT_V(6); PG8_BAR; PG8_MMA(1, 1, At, B1); PG8_BAR;
	s_add_i32 s60, 0, 0x18000
	v_add_u32_e32 v234, s60, v147
	ds_read_b128 v[140:143], v234
	ds_read_b128 v[150:153], v234 offset:1024
	ds_read_b128 v[154:157], v234 offset:2048
	ds_read_b128 v[158:161], v234 offset:3072
	s_add_u32 s48, s48, 0x80000
	s_addc_u32 s49, s49, 0
	s_mov_b32 m0, s72
	v_lshl_add_u64 v[232:233], s[48:49], 0, v[130:131]
	ds_read_b128 v[162:165], v149 offset:32768
	ds_read_b128 v[166:169], v149 offset:33792
	ds_read_b128 v[170:173], v149 offset:34816
	ds_read_b128 v[174:177], v149 offset:35840
	ds_read_b128 v[178:181], v149 offset:36864
	ds_read_b128 v[182:185], v149 offset:37888
	ds_read_b128 v[186:189], v149 offset:38912
	ds_read_b128 v[190:193], v149 offset:39936
	global_load_lds_dwordx4 v[232:233], off
	v_lshl_add_u64 v[232:233], s[48:49], 0, v[132:133]
	s_mov_b32 m0, s73
	s_nop 0
	global_load_lds_dwordx4 v[232:233], off
	s_waitcnt lgkmcnt(11)
	s_add_i32 s48, 0, 0x1c000
	s_add_i32 s49, s60, s64
	v_add_u32_e32 v216, s48, v147
	v_lshl_add_u64 v[144:145], v[144:145], 0, s[92:93]
	s_mov_b32 m0, s49
	ds_read_b128 v[194:197], v216
	ds_read_b128 v[198:201], v216 offset:1024
	ds_read_b128 v[202:205], v216 offset:2048
	ds_read_b128 v[220:223], v216 offset:3072
	s_waitcnt vmcnt(8) lgkmcnt(0)
	s_barrier
	v_mfma_f32_16x16x32_f16 v[126:129], v[140:143], v[162:165], v[126:129]
	v_mfma_f32_16x16x32_f16 v[122:125], v[154:157], v[162:165], v[122:125]
	v_mfma_f32_16x16x32_f16 v[110:113], v[140:143], v[170:173], v[110:113]
	v_mfma_f32_16x16x32_f16 v[106:109], v[154:157], v[170:173], v[106:109]
	v_mfma_f32_16x16x32_f16 v[94:97], v[140:143], v[178:181], v[94:97]
	v_mfma_f32_16x16x32_f16 v[90:93], v[154:157], v[178:181], v[90:93]
	v_mfma_f32_16x16x32_f16 v[78:81], v[140:143], v[186:189], v[78:81]
	v_mfma_f32_16x16x32_f16 v[74:77], v[154:157], v[186:189], v[74:77]
	v_mfma_f32_16x16x32_f16 v[126:129], v[150:153], v[166:169], v[126:129]
	v_mfma_f32_16x16x32_f16 v[122:125], v[158:161], v[166:169], v[122:125]
	v_mfma_f32_16x16x32_f16 v[110:113], v[150:153], v[174:177], v[110:113]
	v_mfma_f32_16x16x32_f16 v[106:109], v[158:161], v[174:177], v[106:109]
	v_mfma_f32_16x16x32_f16 v[94:97], v[150:153], v[182:185], v[94:97]
	v_mfma_f32_16x16x32_f16 v[90:93], v[158:161], v[182:185], v[90:93]
	v_mfma_f32_16x16x32_f16 v[78:81], v[150:153], v[190:193], v[78:81]
	v_mfma_f32_16x16x32_f16 v[74:77], v[158:161], v[190:193], v[74:77]
	v_mfma_f32_16x16x32_f16 v[118:121], v[194:197], v[162:165], v[118:121]
	v_mfma_f32_16x16x32_f16 v[114:117], v[202:205], v[162:165], v[114:117]
	v_mfma_f32_16x16x32_f16 v[102:105], v[194:197], v[170:173], v[102:105]
	v_mfma_f32_16x16x32_f16 v[98:101], v[202:205], v[170:173], v[98:101]
	v_mfma_f32_16x16x32_f16 v[86:89], v[194:197], v[178:181], v[86:89]
	v_mfma_f32_16x16x32_f16 v[82:85], v[202:205], v[178:181], v[82:85]
	v_mfma_f32_16x16x32_f16 v[70:73], v[194:197], v[186:189], v[70:73]
	v_mfma_f32_16x16x32_f16 v[66:69], v[202:205], v[186:189], v[66:69]
	v_mfma_f32_16x16x32_f16 v[118:121], v[198:201], v[166:169], v[118:121]
	v_mfma_f32_16x16x32_f16 v[114:117], v[220:223], v[166:169], v[114:117]
	v_mfma_f32_16x16x32_f16 v[102:105], v[198:201], v[174:177], v[102:105]
	v_mfma_f32_16x16x32_f16 v[98:101], v[220:223], v[174:177], v[98:101]
	v_mfma_f32_16x16x32_f16 v[86:89], v[198:201], v[182:185], v[86:89]
	v_mfma_f32_16x16x32_f16 v[82:85], v[220:223], v[182:185], v[82:85]
	v_mfma_f32_16x16x32_f16 v[70:73], v[198:201], v[190:193], v[70:73]
	v_mfma_f32_16x16x32_f16 v[66:69], v[220:223], v[190:193], v[66:69]
	s_barrier
	global_load_lds_dwordx4 v[144:145], off
	v_lshl_add_u64 v[144:145], v[206:207], 0, s[92:93]
	s_add_i32 m0, s49, 0x2000
	s_nop 0
	global_load_lds_dwordx4 v[144:145], off
	s_mov_b32 m0, s74
	v_lshl_add_u64 v[144:145], v[212:213], 0, s[92:93]
	ds_read_b128 v[162:165], v149 offset:49152
	ds_read_b128 v[166:169], v149 offset:50176
	ds_read_b128 v[170:173], v149 offset:51200
	ds_read_b128 v[174:177], v149 offset:52224
	ds_read_b128 v[178:181], v149 offset:53248
	ds_read_b128 v[182:185], v149 offset:54272
	ds_read_b128 v[186:189], v149 offset:55296
	ds_read_b128 v[190:193], v149 offset:56320
	global_load_lds_dwordx4 v[144:145], off
	v_lshl_add_u64 v[144:145], v[214:215], 0, s[92:93]
	s_mov_b32 m0, s75
	s_nop 0
	global_load_lds_dwordx4 v[144:145], off
	s_add_u32 s46, s46, 0x80080
	s_addc_u32 s47, s47, 0
	s_add_i32 s48, s48, s64
	v_lshl_add_u64 v[232:233], s[46:47], 0, v[0:1]
	s_mov_b32 m0, s48
	s_nop 0
	global_load_lds_dwordx4 v[232:233], off
	v_lshl_add_u64 v[232:233], s[46:47], 0, v[134:135]
	s_add_i32 m0, s48, 0x2000
	s_nop 0
	global_load_lds_dwordx4 v[232:233], off
	s_add_i32 s51, s51, 2
	s_add_u32 s26, s26, 0x100
	s_addc_u32 s27, s27, 0
	s_add_u32 s21, s21, 0x100
	s_addc_u32 s50, s50, 0
	s_cmp_gt_u32 s51, 29
	s_waitcnt vmcnt(8) lgkmcnt(0)
	s_barrier
	v_mfma_f32_16x16x32_f16 v[62:65], v[140:143], v[162:165], v[62:65]
	v_mfma_f32_16x16x32_f16 v[58:61], v[154:157], v[162:165], v[58:61]
	v_mfma_f32_16x16x32_f16 v[46:49], v[140:143], v[170:173], v[46:49]
	v_mfma_f32_16x16x32_f16 v[42:45], v[154:157], v[170:173], v[42:45]
	v_mfma_f32_16x16x32_f16 v[30:33], v[140:143], v[178:181], v[30:33]
	v_mfma_f32_16x16x32_f16 v[26:29], v[154:157], v[178:181], v[26:29]
	v_mfma_f32_16x16x32_f16 v[14:17], v[140:143], v[186:189], v[14:17]
	v_mfma_f32_16x16x32_f16 v[10:13], v[154:157], v[186:189], v[10:13]
	v_mfma_f32_16x16x32_f16 v[62:65], v[150:153], v[166:169], v[62:65]
	v_mfma_f32_16x16x32_f16 v[58:61], v[158:161], v[166:169], v[58:61]
	v_mfma_f32_16x16x32_f16 v[46:49], v[150:153], v[174:177], v[46:49]
	v_mfma_f32_16x16x32_f16 v[42:45], v[158:161], v[174:177], v[42:45]
	v_mfma_f32_16x16x32_f16 v[30:33], v[150:153], v[182:185], v[30:33]
	v_mfma_f32_16x16x32_f16 v[26:29], v[158:161], v[182:185], v[26:29]
	v_mfma_f32_16x16x32_f16 v[14:17], v[150:153], v[190:193], v[14:17]
	v_mfma_f32_16x16x32_f16 v[10:13], v[158:161], v[190:193], v[10:13]
	v_mfma_f32_16x16x32_f16 v[54:57], v[194:197], v[162:165], v[54:57]
	v_mfma_f32_16x16x32_f16 v[50:53], v[202:205], v[162:165], v[50:53]
	v_mfma_f32_16x16x32_f16 v[38:41], v[194:197], v[170:173], v[38:41]
	v_mfma_f32_16x16x32_f16 v[34:37], v[202:205], v[170:173], v[34:37]
	v_mfma_f32_16x16x32_f16 v[22:25], v[194:197], v[178:181], v[22:25]
	v_mfma_f32_16x16x32_f16 v[18:21], v[202:205], v[178:181], v[18:21]
	v_mfma_f32_16x16x32_f16 v[6:9], v[194:197], v[186:189], v[6:9]
	v_mfma_f32_16x16x32_f16 v[2:5], v[202:205], v[186:189], v[2:5]
	v_mfma_f32_16x16x32_f16 v[54:57], v[198:201], v[166:169], v[54:57]
	v_mfma_f32_16x16x32_f16 v[50:53], v[220:223], v[166:169], v[50:53]
	v_mfma_f32_16x16x32_f16 v[38:41], v[198:201], v[174:177], v[38:41]
	v_mfma_f32_16x16x32_f16 v[34:37], v[220:223], v[174:177], v[34:37]
	v_mfma_f32_16x16x32_f16 v[22:25], v[198:201], v[182:185], v[22:25]
	v_mfma_f32_16x16x32_f16 v[18:21], v[220:223], v[182:185], v[18:21]
	v_mfma_f32_16x16x32_f16 v[6:9], v[198:201], v[190:193], v[6:9]
	v_mfma_f32_16x16x32_f16 v[2:5], v[220:223], v[190:193], v[2:5]
	s_barrier
	s_cbranch_scc0 .LBB0_147
.Lg4x_147:
	s_cmpk_gt_u32 s62, 0xff
	s_cbranch_scc1 .Lgx2
	s_barrier

; #define PG8_STAGE(bufoff, gbase, voff) do { _Pragma("unroll") for (int _i = 0; _i < 2; ++_i) \
;         __builtin_amdgcn_global_load_lds((const unsigned*)((const char*)(gbase) + (voff)[_i]), (LAS unsigned*)(lds + (bufoff) + ldsw + _i * 8192), 16, 0, 0); } while (0)
; #define PG8_LDA(dst, b, h) do { _Pragma("unroll") for (int m = 0; m < 4; ++m) _Pragma("unroll") for (int k = 0; k < 2; ++k) dst[m][k] = *(const LAS h16x8*)(lds + PG8_SA(b, h) + aoff + m * 2048 + k * 1024); } while (0)
; #define PG8_LDB(dst, b, h) do { _Pragma("unroll") for (int n = 0; n < 2; ++n) _Pragma("unroll") for (int k = 0; k < 2; ++k) dst[n][k] = *(const LAS h16x8*)(lds + PG8_SB(b, h) + boff + n * 2048 + k * 1024); } while (0)
; #define PG8_WAIT_V(n) asm volatile("s_waitcnt vmcnt(" #n ")" ::: "memory")
; #define PG8_WAIT_L(n) asm volatile("s_waitcnt lgkmcnt(" #n ")" ::: "memory")
; #define PG8_BAR __builtin_amdgcn_s_barrier()
; #define PG8_SCHED __builtin_amdgcn_sched_barrier(0)
; template <class Epi, class AMap>
; __device__ __forceinline__ void gemm_phase(LAS unsigned char* lds, const AMap am, const int lda, const h16* Bt, const int ldb, const int M, const int N, const int K, const Epi& E) {
;     ...
;         const bool has_next = S.next(ui + 1, nxt);
;         const char* nA = has_next ? am(nxt.pn) + (size_t)nxt.pm * tstepA : cA; const char* nB = has_next ? (const char*)Bt + (size_t)nxt.pn * tstepB : cB;
; #pragma unroll 1
;         for (int t = 0; t < nt; t += 2) {
;             const bool last = (t == nt - 2);
;             const char* a1 = cA + (size_t)(t + 1) * kstep;
;             const char* a2 = last ? nA : cA + (size_t)(t + 2) * kstep; const char* b2 = last ? nB : cB + (size_t)(t + 2) * kstep;
;             const char* a3 = a2 + kstep; const char* b3 = b2 + kstep;
;             PG8_LDB(B0, 0, 0); PG8_SCHED; PG8_LDA(At, 0, 0); PG8_STAGE(PG8_SA(1, 1), a1 + hstepA, voffA);
;             PG8_WAIT_L(8); PG8_BAR; PG8_WAIT_L(0); PG8_MMA(0, 0, At, B0); PG8_BAR; PG8_SCHED;
;             PG8_LDB(B1, 0, 1); PG8_STAGE(PG8_SB(0, 0), b2, voffB);
;             PG8_BAR; PG8_WAIT_L(0); PG8_MMA(0, 1, At, B1); PG8_BAR;
;             PG8_LDA(At, 0, 1); PG8_STAGE(PG8_SA(0, 0), a2, voffA);
;             PG8_BAR; PG8_WAIT_L(0); PG8_MMA(1, 0, At, B0); PG8_BAR; PG8_SCHED;
;             PG8_STAGE(PG8_SB(0, 1), b2 + hstepB, voffB);
;             PG8_WAIT_V(6); PG8_BAR; PG8_MMA(1, 1, At, B1); PG8_BAR;
.LBB0_267:
	s_ashr_i32 s45, s44, 31
	s_lshl_b64 s[20:21], s[44:45], 20
	s_add_u32 s68, s94, s20
	v_cmp_lt_i64_e32 vcc, s[48:49], v[218:219]
	s_addc_u32 s69, s95, s21
	s_and_b64 s[20:21], vcc, exec
	s_cselect_b32 s23, s69, s41
	s_cselect_b32 s27, s68, s40
	s_ashr_i32 s1, s0, 31
	s_lshl_b64 s[20:21], s[0:1], 20
	s_add_u32 s70, s9, s20
	s_addc_u32 s71, s11, s21
	s_and_b64 s[20:21], vcc, exec
	s_cselect_b32 s1, s71, s43
	s_cselect_b32 s20, s70, s42
	s_add_u32 s40, s40, 0x80080
	s_addc_u32 s41, s41, 0
	s_add_u32 s21, s42, 0x100
	s_addc_u32 s29, s43, 0
	s_mov_b32 s35, -2
	s_add_u32 s42, s40, 0xfff80080
	s_addc_u32 s43, s41, -1
	s_add_i32 s45, 0, 0x10000
	v_add_u32_e32 v0, s45, v149
	ds_read_b128 v[142:145], v0
	ds_read_b128 v[154:157], v0 offset:1024
	ds_read_b128 v[158:161], v0 offset:2048
	ds_read_b128 v[162:165], v0 offset:3072
	s_cmp_eq_u32 s35, 28
	s_cselect_b32 s49, s23, s43
	s_cselect_b32 s48, s27, s42
	s_cselect_b32 s43, s1, s29
	s_cselect_b32 s42, s20, s21
	v_lshl_add_u64 v[146:147], s[40:41], 0, v[138:139]
	s_add_i32 m0, s72, 0xc000
	ds_read_b128 v[166:169], v153
	ds_read_b128 v[170:173], v153 offset:1024
	ds_read_b128 v[174:177], v153 offset:2048
	ds_read_b128 v[178:181], v153 offset:3072
	ds_read_b128 v[182:185], v153 offset:4096
	ds_read_b128 v[186:189], v153 offset:5120
	ds_read_b128 v[190:193], v153 offset:6144
	ds_read_b128 v[194:197], v153 offset:7168
	global_load_lds_dwordx4 v[146:147], off
	v_lshl_add_u64 v[146:147], s[40:41], 0, v[140:141]
	s_add_i32 m0, s72, 0xe000
	s_nop 0
	global_load_lds_dwordx4 v[146:147], off
	s_waitcnt lgkmcnt(11)
	s_add_i32 s60, 0, 0x14000
	s_add_i32 s45, s45, s65
	v_add_u32_e32 v0, s60, v149
	v_lshl_add_u64 v[146:147], s[42:43], 0, v[132:133]
	s_mov_b32 m0, s45
	ds_read_b128 v[198:201], v0
	ds_read_b128 v[202:205], v0 offset:1024
	ds_read_b128 v[220:223], v0 offset:2048
	ds_read_b128 v[224:227], v0 offset:3072
	s_waitcnt vmcnt(8) lgkmcnt(0)
	s_barrier
	v_mfma_f32_16x16x32_f16 v[126:129], v[142:145], v[166:169], 0
	v_mfma_f32_16x16x32_f16 v[122:125], v[158:161], v[166:169], 0
	v_mfma_f32_16x16x32_f16 v[110:113], v[142:145], v[174:177], 0
	v_mfma_f32_16x16x32_f16 v[106:109], v[158:161], v[174:177], 0
	v_mfma_f32_16x16x32_f16 v[94:97], v[142:145], v[182:185], 0
	v_mfma_f32_16x16x32_f16 v[90:93], v[158:161], v[182:185], 0
	v_mfma_f32_16x16x32_f16 v[78:81], v[142:145], v[190:193], 0
	v_mfma_f32_16x16x32_f16 v[74:77], v[158:161], v[190:193], 0
	v_mfma_f32_16x16x32_f16 v[126:129], v[154:157], v[170:173], v[126:129]
	v_mfma_f32_16x16x32_f16 v[122:125], v[162:165], v[170:173], v[122:125]
	v_mfma_f32_16x16x32_f16 v[110:113], v[154:157], v[178:181], v[110:113]
	v_mfma_f32_16x16x32_f16 v[106:109], v[162:165], v[178:181], v[106:109]
	v_mfma_f32_16x16x32_f16 v[94:97], v[154:157], v[186:189], v[94:97]
	v_mfma_f32_16x16x32_f16 v[90:93], v[162:165], v[186:189], v[90:93]
	v_mfma_f32_16x16x32_f16 v[78:81], v[154:157], v[194:197], v[78:81]
	v_mfma_f32_16x16x32_f16 v[74:77], v[162:165], v[194:197], v[74:77]
	v_mfma_f32_16x16x32_f16 v[118:121], v[198:201], v[166:169], 0
	v_mfma_f32_16x16x32_f16 v[114:117], v[220:223], v[166:169], 0
	v_mfma_f32_16x16x32_f16 v[102:105], v[198:201], v[174:177], 0
	v_mfma_f32_16x16x32_f16 v[98:101], v[220:223], v[174:177], 0
	v_mfma_f32_16x16x32_f16 v[86:89], v[198:201], v[182:185], 0
	v_mfma_f32_16x16x32_f16 v[82:85], v[220:223], v[182:185], 0
	v_mfma_f32_16x16x32_f16 v[70:73], v[198:201], v[190:193], 0
	v_mfma_f32_16x16x32_f16 v[66:69], v[220:223], v[190:193], 0
	v_mfma_f32_16x16x32_f16 v[118:121], v[202:205], v[170:173], v[118:121]
	v_mfma_f32_16x16x32_f16 v[114:117], v[224:227], v[170:173], v[114:117]
	v_mfma_f32_16x16x32_f16 v[102:105], v[202:205], v[178:181], v[102:105]
	v_mfma_f32_16x16x32_f16 v[98:101], v[224:227], v[178:181], v[98:101]
	v_mfma_f32_16x16x32_f16 v[86:89], v[202:205], v[186:189], v[86:89]
	v_mfma_f32_16x16x32_f16 v[82:85], v[224:227], v[186:189], v[82:85]
	v_mfma_f32_16x16x32_f16 v[70:73], v[202:205], v[194:197], v[70:73]
	v_mfma_f32_16x16x32_f16 v[66:69], v[224:227], v[194:197], v[66:69]
	s_barrier
	global_load_lds_dwordx4 v[146:147], off
	v_lshl_add_u64 v[206:207], s[42:43], 0, v[136:137]
	s_add_i32 m0, s45, 0x2000
	s_nop 0
	global_load_lds_dwordx4 v[206:207], off
	s_mov_b32 m0, s72
	v_lshl_add_u64 v[212:213], s[48:49], 0, v[130:131]
	ds_read_b128 v[166:169], v153 offset:16384
	ds_read_b128 v[170:173], v153 offset:17408
	ds_read_b128 v[174:177], v153 offset:18432
	ds_read_b128 v[178:181], v153 offset:19456
	ds_read_b128 v[182:185], v153 offset:20480
	ds_read_b128 v[186:189], v153 offset:21504
	ds_read_b128 v[190:193], v153 offset:22528
	ds_read_b128 v[194:197], v153 offset:23552
	global_load_lds_dwordx4 v[212:213], off
	v_lshl_add_u64 v[228:229], s[48:49], 0, v[134:135]
	s_mov_b32 m0, s73
	s_nop 0
	global_load_lds_dwordx4 v[228:229], off
	s_add_u32 s50, s42, 0x80000
	s_addc_u32 s51, s43, 0
	s_add_i32 s45, s60, s65
	v_lshl_add_u64 v[232:233], s[50:51], 0, v[132:133]
	s_mov_b32 m0, s45
	s_nop 0
	global_load_lds_dwordx4 v[232:233], off
	v_lshl_add_u64 v[232:233], s[50:51], 0, v[136:137]
	s_add_i32 m0, s45, 0x2000
	s_nop 0
	global_load_lds_dwordx4 v[232:233], off
	s_waitcnt vmcnt(8) lgkmcnt(0)
	s_barrier
; #define PG8_STAGE(bufoff, gbase, voff) do { _Pragma("unroll") for (int _i = 0; _i < 2; ++_i) \
;         __builtin_amdgcn_global_load_lds((const unsigned*)((const char*)(gbase) + (voff)[_i]), (LAS unsigned*)(lds + (bufoff) + ldsw + _i * 8192), 16, 0, 0); } while (0)
; #define PG8_LDA(dst, b, h) do { _Pragma("unroll") for (int m = 0; m < 4; ++m) _Pragma("unroll") for (int k = 0; k < 2; ++k) dst[m][k] = *(const LAS h16x8*)(lds + PG8_SA(b, h) + aoff + m * 2048 + k * 1024); } while (0)
; #define PG8_LDB(dst, b, h) do { _Pragma("unroll") for (int n = 0; n < 2; ++n) _Pragma("unroll") for (int k = 0; k < 2; ++k) dst[n][k] = *(const LAS h16x8*)(lds + PG8_SB(b, h) + boff + n * 2048 + k * 1024); } while (0)
; #define PG8_MMA(ai, bj, At, Bt_) do { __builtin_amdgcn_s_setprio(1); _Pragma("unroll") for (int m = 0; m < 4; ++m) _Pragma("unroll") for (int n = 0; n < 2; ++n) _Pragma("unroll") for (int k = 0; k < 2; ++k) \
;         acc[ai][bj][m][n] = __builtin_amdgcn_mfma_f32_16x16x32_f16(Bt_[n][k], At[m][k], acc[ai][bj][m][n], 0, 0, 0); __builtin_amdgcn_s_setprio(0); } while (0)
; #define PG8_WAIT_V(n) asm volatile("s_waitcnt vmcnt(" #n ")" ::: "memory")
; #define PG8_WAIT_L(n) asm volatile("s_waitcnt lgkmcnt(" #n ")" ::: "memory")
; #define PG8_BAR __builtin_amdgcn_s_barrier()
; #define PG8_SCHED __builtin_amdgcn_sched_barrier(0)
; template <class Epi, class AMap>
; __device__ __forceinline__ void gemm_phase(LAS unsigned char* lds, const AMap am, const int lda, const h16* Bt, const int ldb, const int M, const int N, const int K, const Epi& E) {
;     ...
;             PG8_WAIT_V(6); PG8_BAR; PG8_MMA(1, 1, At, B1); PG8_BAR;
;             PG8_LDB(B0, 1, 0); PG8_SCHED; PG8_LDA(At, 1, 0); PG8_STAGE(PG8_SA(0, 1), a2 + hstepA, voffA);
;             PG8_WAIT_L(8); PG8_BAR; PG8_WAIT_L(0); PG8_MMA(0, 0, At, B0); PG8_BAR; PG8_SCHED;
;             PG8_LDB(B1, 1, 1); PG8_STAGE(PG8_SB(1, 0), b3, voffB);
;             PG8_BAR; PG8_WAIT_L(0); PG8_MMA(0, 1, At, B1); PG8_BAR;
;             PG8_LDA(At, 1, 1); PG8_STAGE(PG8_SA(1, 0), a3, voffA);
;             PG8_BAR; PG8_WAIT_L(0); PG8_MMA(1, 0, At, B0); PG8_BAR; PG8_SCHED;
	v_mfma_f32_16x16x32_f16 v[62:65], v[142:145], v[166:169], 0
	v_mfma_f32_16x16x32_f16 v[58:61], v[158:161], v[166:169], 0
	v_mfma_f32_16x16x32_f16 v[46:49], v[142:145], v[174:177], 0
	v_mfma_f32_16x16x32_f16 v[42:45], v[158:161], v[174:177], 0
	v_mfma_f32_16x16x32_f16 v[30:33], v[142:145], v[182:185], 0
	v_mfma_f32_16x16x32_f16 v[26:29], v[158:161], v[182:185], 0
	v_mfma_f32_16x16x32_f16 v[14:17], v[142:145], v[190:193], 0
	v_mfma_f32_16x16x32_f16 v[10:13], v[158:161], v[190:193], 0
	v_mfma_f32_16x16x32_f16 v[62:65], v[154:157], v[170:173], v[62:65]
	v_mfma_f32_16x16x32_f16 v[58:61], v[162:165], v[170:173], v[58:61]
	v_mfma_f32_16x16x32_f16 v[46:49], v[154:157], v[178:181], v[46:49]
	v_mfma_f32_16x16x32_f16 v[42:45], v[162:165], v[178:181], v[42:45]
	v_mfma_f32_16x16x32_f16 v[30:33], v[154:157], v[186:189], v[30:33]
	v_mfma_f32_16x16x32_f16 v[26:29], v[162:165], v[186:189], v[26:29]
	v_mfma_f32_16x16x32_f16 v[14:17], v[154:157], v[194:197], v[14:17]
	v_mfma_f32_16x16x32_f16 v[10:13], v[162:165], v[194:197], v[10:13]
	v_mfma_f32_16x16x32_f16 v[54:57], v[198:201], v[166:169], 0
	v_mfma_f32_16x16x32_f16 v[50:53], v[220:223], v[166:169], 0
	v_mfma_f32_16x16x32_f16 v[38:41], v[198:201], v[174:177], 0
	v_mfma_f32_16x16x32_f16 v[34:37], v[220:223], v[174:177], 0
	v_mfma_f32_16x16x32_f16 v[22:25], v[198:201], v[182:185], 0
	v_mfma_f32_16x16x32_f16 v[18:21], v[220:223], v[182:185], 0
	v_mfma_f32_16x16x32_f16 v[6:9], v[198:201], v[190:193], 0
	v_mfma_f32_16x16x32_f16 v[2:5], v[220:223], v[190:193], 0
	v_mfma_f32_16x16x32_f16 v[54:57], v[202:205], v[170:173], v[54:57]
	v_mfma_f32_16x16x32_f16 v[50:53], v[224:227], v[170:173], v[50:53]
	v_mfma_f32_16x16x32_f16 v[38:41], v[202:205], v[178:181], v[38:41]
	v_mfma_f32_16x16x32_f16 v[34:37], v[224:227], v[178:181], v[34:37]
	v_mfma_f32_16x16x32_f16 v[22:25], v[202:205], v[186:189], v[22:25]
	v_mfma_f32_16x16x32_f16 v[18:21], v[224:227], v[186:189], v[18:21]
	v_mfma_f32_16x16x32_f16 v[6:9], v[202:205], v[194:197], v[6:9]
	v_mfma_f32_16x16x32_f16 v[2:5], v[224:227], v[194:197], v[2:5]
	s_barrier
	s_add_i32 s45, 0, 0x18000
	v_add_u32_e32 v0, s45, v149
	ds_read_b128 v[142:145], v0
	ds_read_b128 v[154:157], v0 offset:1024
	ds_read_b128 v[158:161], v0 offset:2048
	ds_read_b128 v[162:165], v0 offset:3072
	s_add_u32 s48, s48, 0x80000
	s_addc_u32 s49, s49, 0
	s_mov_b32 m0, s74
	v_lshl_add_u64 v[232:233], s[48:49], 0, v[130:131]
	ds_read_b128 v[166:169], v153 offset:32768
	ds_read_b128 v[170:173], v153 offset:33792
	ds_read_b128 v[174:177], v153 offset:34816
	ds_read_b128 v[178:181], v153 offset:35840
	ds_read_b128 v[182:185], v153 offset:36864
	ds_read_b128 v[186:189], v153 offset:37888
	ds_read_b128 v[190:193], v153 offset:38912
	ds_read_b128 v[194:197], v153 offset:39936
	global_load_lds_dwordx4 v[232:233], off
	v_lshl_add_u64 v[232:233], s[48:49], 0, v[134:135]
	s_mov_b32 m0, s75
	s_nop 0
	global_load_lds_dwordx4 v[232:233], off
	s_waitcnt lgkmcnt(11)
	s_add_i32 s48, 0, 0x1c000
	s_add_i32 s45, s45, s65
	v_add_u32_e32 v0, s48, v149
	v_lshl_add_u64 v[146:147], v[146:147], 0, s[92:93]
	s_mov_b32 m0, s45
	ds_read_b128 v[198:201], v0
	ds_read_b128 v[202:205], v0 offset:1024
	ds_read_b128 v[220:223], v0 offset:2048
	ds_read_b128 v[224:227], v0 offset:3072
	s_waitcnt vmcnt(8) lgkmcnt(0)
	s_barrier
	v_mfma_f32_16x16x32_f16 v[126:129], v[142:145], v[166:169], v[126:129]
	v_mfma_f32_16x16x32_f16 v[122:125], v[158:161], v[166:169], v[122:125]
	v_mfma_f32_16x16x32_f16 v[110:113], v[142:145], v[174:177], v[110:113]
	v_mfma_f32_16x16x32_f16 v[106:109], v[158:161], v[174:177], v[106:109]
	v_mfma_f32_16x16x32_f16 v[94:97], v[142:145], v[182:185], v[94:97]
	v_mfma_f32_16x16x32_f16 v[90:93], v[158:161], v[182:185], v[90:93]
	v_mfma_f32_16x16x32_f16 v[78:81], v[142:145], v[190:193], v[78:81]
	v_mfma_f32_16x16x32_f16 v[74:77], v[158:161], v[190:193], v[74:77]
	v_mfma_f32_16x16x32_f16 v[126:129], v[154:157], v[170:173], v[126:129]
	v_mfma_f32_16x16x32_f16 v[122:125], v[162:165], v[170:173], v[122:125]
	v_mfma_f32_16x16x32_f16 v[110:113], v[154:157], v[178:181], v[110:113]
	v_mfma_f32_16x16x32_f16 v[106:109], v[162:165], v[178:181], v[106:109]
	v_mfma_f32_16x16x32_f16 v[94:97], v[154:157], v[186:189], v[94:97]
	v_mfma_f32_16x16x32_f16 v[90:93], v[162:165], v[186:189], v[90:93]
	v_mfma_f32_16x16x32_f16 v[78:81], v[154:157], v[194:197], v[78:81]
	v_mfma_f32_16x16x32_f16 v[74:77], v[162:165], v[194:197], v[74:77]
	v_mfma_f32_16x16x32_f16 v[118:121], v[198:201], v[166:169], v[118:121]
	v_mfma_f32_16x16x32_f16 v[114:117], v[220:223], v[166:169], v[114:117]
	v_mfma_f32_16x16x32_f16 v[102:105], v[198:201], v[174:177], v[102:105]
	v_mfma_f32_16x16x32_f16 v[98:101], v[220:223], v[174:177], v[98:101]
	v_mfma_f32_16x16x32_f16 v[86:89], v[198:201], v[182:185], v[86:89]
	v_mfma_f32_16x16x32_f16 v[82:85], v[220:223], v[182:185], v[82:85]
	v_mfma_f32_16x16x32_f16 v[70:73], v[198:201], v[190:193], v[70:73]
	v_mfma_f32_16x16x32_f16 v[66:69], v[220:223], v[190:193], v[66:69]
	v_mfma_f32_16x16x32_f16 v[118:121], v[202:205], v[170:173], v[118:121]
	v_mfma_f32_16x16x32_f16 v[114:117], v[224:227], v[170:173], v[114:117]
	v_mfma_f32_16x16x32_f16 v[102:105], v[202:205], v[178:181], v[102:105]
	v_mfma_f32_16x16x32_f16 v[98:101], v[224:227], v[178:181], v[98:101]
	v_mfma_f32_16x16x32_f16 v[86:89], v[202:205], v[186:189], v[86:89]
	v_mfma_f32_16x16x32_f16 v[82:85], v[224:227], v[186:189], v[82:85]
	v_mfma_f32_16x16x32_f16 v[70:73], v[202:205], v[194:197], v[70:73]
	v_mfma_f32_16x16x32_f16 v[66:69], v[224:227], v[194:197], v[66:69]
	s_barrier
; #define PG8_STAGE(bufoff, gbase, voff) do { _Pragma("unroll") for (int _i = 0; _i < 2; ++_i) \
;         __builtin_amdgcn_global_load_lds((const unsigned*)((const char*)(gbase) + (voff)[_i]), (LAS unsigned*)(lds + (bufoff) + ldsw + _i * 8192), 16, 0, 0); } while (0)
; #define PG8_LDA(dst, b, h) do { _Pragma("unroll") for (int m = 0; m < 4; ++m) _Pragma("unroll") for (int k = 0; k < 2; ++k) dst[m][k] = *(const LAS h16x8*)(lds + PG8_SA(b, h) + aoff + m * 2048 + k * 1024); } while (0)
; #define PG8_LDB(dst, b, h) do { _Pragma("unroll") for (int n = 0; n < 2; ++n) _Pragma("unroll") for (int k = 0; k < 2; ++k) dst[n][k] = *(const LAS h16x8*)(lds + PG8_SB(b, h) + boff + n * 2048 + k * 1024); } while (0)
; #define PG8_MMA(ai, bj, At, Bt_) do { __builtin_amdgcn_s_setprio(1); _Pragma("unroll") for (int m = 0; m < 4; ++m) _Pragma("unroll") for (int n = 0; n < 2; ++n) _Pragma("unroll") for (int k = 0; k < 2; ++k) \
;         acc[ai][bj][m][n] = __builtin_amdgcn_mfma_f32_16x16x32_f16(Bt_[n][k], At[m][k], acc[ai][bj][m][n], 0, 0, 0); __builtin_amdgcn_s_setprio(0); } while (0)
; #define PG8_WAIT_V(n) asm volatile("s_waitcnt vmcnt(" #n ")" ::: "memory")
; #define PG8_WAIT_L(n) asm volatile("s_waitcnt lgkmcnt(" #n ")" ::: "memory")
; #define PG8_BAR __builtin_amdgcn_s_barrier()
; #define PG8_SCHED __builtin_amdgcn_sched_barrier(0)
; template <class Epi, class AMap>
; __device__ __forceinline__ void gemm_phase(LAS unsigned char* lds, const AMap am, const int lda, const h16* Bt, const int ldb, const int M, const int N, const int K, const Epi& E) {
;     ...
;         for (int t = 0; t < nt; t += 2) {
;             const bool last = (t == nt - 2);
;             const char* a1 = cA + (size_t)(t + 1) * kstep;
;             const char* a2 = last ? nA : cA + (size_t)(t + 2) * kstep; const char* b2 = last ? nB : cB + (size_t)(t + 2) * kstep;
;             const char* a3 = a2 + kstep; const char* b3 = b2 + kstep;
;             PG8_LDB(B0, 0, 0); PG8_SCHED; PG8_LDA(At, 0, 0); PG8_STAGE(PG8_SA(1, 1), a1 + hstepA, voffA);
;             PG8_WAIT_L(8); PG8_BAR; PG8_WAIT_L(0); PG8_MMA(0, 0, At, B0); PG8_BAR; PG8_SCHED;
;     ...
;             PG8_LDA(At, 1, 1); PG8_STAGE(PG8_SA(1, 0), a3, voffA);
;             PG8_BAR; PG8_WAIT_L(0); PG8_MMA(1, 0, At, B0); PG8_BAR; PG8_SCHED;
;             PG8_STAGE(PG8_SB(1, 1), b3 + hstepB, voffB);
;             PG8_WAIT_V(6); PG8_BAR; PG8_MMA(1, 1, At, B1); PG8_BAR;
	global_load_lds_dwordx4 v[146:147], off
	v_lshl_add_u64 v[146:147], v[206:207], 0, s[92:93]
	s_add_i32 m0, s45, 0x2000
	s_nop 0
	global_load_lds_dwordx4 v[146:147], off
	s_mov_b32 m0, s77
	v_lshl_add_u64 v[146:147], v[212:213], 0, s[92:93]
	ds_read_b128 v[166:169], v153 offset:49152
	ds_read_b128 v[170:173], v153 offset:50176
	ds_read_b128 v[174:177], v153 offset:51200
	ds_read_b128 v[178:181], v153 offset:52224
	ds_read_b128 v[182:185], v153 offset:53248
	ds_read_b128 v[186:189], v153 offset:54272
	ds_read_b128 v[190:193], v153 offset:55296
	ds_read_b128 v[194:197], v153 offset:56320
	global_load_lds_dwordx4 v[146:147], off
	v_lshl_add_u64 v[146:147], v[228:229], 0, s[92:93]
	s_mov_b32 m0, s78
	s_nop 0
	global_load_lds_dwordx4 v[146:147], off
	s_add_u32 s42, s42, 0x80080
	s_addc_u32 s43, s43, 0
	s_add_i32 s45, s48, s65
	v_lshl_add_u64 v[232:233], s[42:43], 0, v[132:133]
	s_mov_b32 m0, s45
	s_nop 0
	global_load_lds_dwordx4 v[232:233], off
	v_lshl_add_u64 v[232:233], s[42:43], 0, v[136:137]
	s_add_i32 m0, s45, 0x2000
	s_nop 0
	global_load_lds_dwordx4 v[232:233], off
	s_add_i32 s35, s35, 2
	s_add_u32 s40, s40, 0x100
	s_addc_u32 s41, s41, 0
	s_add_u32 s21, s21, 0x100
	s_addc_u32 s29, s29, 0
	s_cmp_gt_u32 s35, 29
	s_waitcnt vmcnt(8) lgkmcnt(0)
	s_barrier
	v_mfma_f32_16x16x32_f16 v[62:65], v[142:145], v[166:169], v[62:65]
	v_mfma_f32_16x16x32_f16 v[58:61], v[158:161], v[166:169], v[58:61]
	v_mfma_f32_16x16x32_f16 v[46:49], v[142:145], v[174:177], v[46:49]
	v_mfma_f32_16x16x32_f16 v[42:45], v[158:161], v[174:177], v[42:45]
	v_mfma_f32_16x16x32_f16 v[30:33], v[142:145], v[182:185], v[30:33]
	v_mfma_f32_16x16x32_f16 v[26:29], v[158:161], v[182:185], v[26:29]
	v_mfma_f32_16x16x32_f16 v[14:17], v[142:145], v[190:193], v[14:17]
	v_mfma_f32_16x16x32_f16 v[10:13], v[158:161], v[190:193], v[10:13]
	v_mfma_f32_16x16x32_f16 v[62:65], v[154:157], v[170:173], v[62:65]
	v_mfma_f32_16x16x32_f16 v[58:61], v[162:165], v[170:173], v[58:61]
	v_mfma_f32_16x16x32_f16 v[46:49], v[154:157], v[178:181], v[46:49]
	v_mfma_f32_16x16x32_f16 v[42:45], v[162:165], v[178:181], v[42:45]
	v_mfma_f32_16x16x32_f16 v[30:33], v[154:157], v[186:189], v[30:33]
	v_mfma_f32_16x16x32_f16 v[26:29], v[162:165], v[186:189], v[26:29]
	v_mfma_f32_16x16x32_f16 v[14:17], v[154:157], v[194:197], v[14:17]
	v_mfma_f32_16x16x32_f16 v[10:13], v[162:165], v[194:197], v[10:13]
	v_mfma_f32_16x16x32_f16 v[54:57], v[198:201], v[166:169], v[54:57]
	v_mfma_f32_16x16x32_f16 v[50:53], v[220:223], v[166:169], v[50:53]
	v_mfma_f32_16x16x32_f16 v[38:41], v[198:201], v[174:177], v[38:41]
	v_mfma_f32_16x16x32_f16 v[34:37], v[220:223], v[174:177], v[34:37]
	v_mfma_f32_16x16x32_f16 v[22:25], v[198:201], v[182:185], v[22:25]
	v_mfma_f32_16x16x32_f16 v[18:21], v[220:223], v[182:185], v[18:21]
	v_mfma_f32_16x16x32_f16 v[6:9], v[198:201], v[190:193], v[6:9]
	v_mfma_f32_16x16x32_f16 v[2:5], v[220:223], v[190:193], v[2:5]
	v_mfma_f32_16x16x32_f16 v[54:57], v[202:205], v[170:173], v[54:57]
	v_mfma_f32_16x16x32_f16 v[50:53], v[224:227], v[170:173], v[50:53]
	v_mfma_f32_16x16x32_f16 v[38:41], v[202:205], v[178:181], v[38:41]
	v_mfma_f32_16x16x32_f16 v[34:37], v[224:227], v[178:181], v[34:37]
	v_mfma_f32_16x16x32_f16 v[22:25], v[202:205], v[186:189], v[22:25]
	v_mfma_f32_16x16x32_f16 v[18:21], v[224:227], v[186:189], v[18:21]
	v_mfma_f32_16x16x32_f16 v[6:9], v[202:205], v[194:197], v[6:9]
	v_mfma_f32_16x16x32_f16 v[2:5], v[224:227], v[194:197], v[2:5]
	s_barrier
	s_cbranch_scc1 .Lg4x_268
.LBB0_268:
	s_add_u32 s42, s40, 0xfff80080
	s_addc_u32 s43, s41, -1
	s_add_i32 s45, 0, 0x10000
	v_add_u32_e32 v0, s45, v149
	ds_read_b128 v[142:145], v0
	ds_read_b128 v[154:157], v0 offset:1024
	ds_read_b128 v[158:161], v0 offset:2048
	ds_read_b128 v[162:165], v0 offset:3072
	s_cmp_eq_u32 s35, 28
	s_cselect_b32 s49, s23, s43
	s_cselect_b32 s48, s27, s42
	s_cselect_b32 s43, s1, s29
	s_cselect_b32 s42, s20, s21
	v_lshl_add_u64 v[146:147], s[40:41], 0, v[138:139]
	s_add_i32 m0, s72, 0xc000
	ds_read_b128 v[166:169], v153
	ds_read_b128 v[170:173], v153 offset:1024
	ds_read_b128 v[174:177], v153 offset:2048
	ds_read_b128 v[178:181], v153 offset:3072
	ds_read_b128 v[182:185], v153 offset:4096
	ds_read_b128 v[186:189], v153 offset:5120
	ds_read_b128 v[190:193], v153 offset:6144
	ds_read_b128 v[194:197], v153 offset:7168
	global_load_lds_dwordx4 v[146:147], off
	v_lshl_add_u64 v[146:147], s[40:41], 0, v[140:141]
	s_add_i32 m0, s72, 0xe000
	s_nop 0
	global_load_lds_dwordx4 v[146:147], off
	s_waitcnt lgkmcnt(11)
	s_add_i32 s60, 0, 0x14000
	s_add_i32 s45, s45, s65
	v_add_u32_e32 v0, s60, v149
	v_lshl_add_u64 v[146:147], s[42:43], 0, v[132:133]
	s_mov_b32 m0, s45
	ds_read_b128 v[198:201], v0
	ds_read_b128 v[202:205], v0 offset:1024
	ds_read_b128 v[220:223], v0 offset:2048
	ds_read_b128 v[224:227], v0 offset:3072
	s_waitcnt vmcnt(8) lgkmcnt(0)
	s_barrier
; #define PG8_STAGE(bufoff, gbase, voff) do { _Pragma("unroll") for (int _i = 0; _i < 2; ++_i) \
;         __builtin_amdgcn_global_load_lds((const unsigned*)((const char*)(gbase) + (voff)[_i]), (LAS unsigned*)(lds + (bufoff) + ldsw + _i * 8192), 16, 0, 0); } while (0)
; #define PG8_LDA(dst, b, h) do { _Pragma("unroll") for (int m = 0; m < 4; ++m) _Pragma("unroll") for (int k = 0; k < 2; ++k) dst[m][k] = *(const LAS h16x8*)(lds + PG8_SA(b, h) + aoff + m * 2048 + k * 1024); } while (0)
; #define PG8_LDB(dst, b, h) do { _Pragma("unroll") for (int n = 0; n < 2; ++n) _Pragma("unroll") for (int k = 0; k < 2; ++k) dst[n][k] = *(const LAS h16x8*)(lds + PG8_SB(b, h) + boff + n * 2048 + k * 1024); } while (0)
; #define PG8_MMA(ai, bj, At, Bt_) do { __builtin_amdgcn_s_setprio(1); _Pragma("unroll") for (int m = 0; m < 4; ++m) _Pragma("unroll") for (int n = 0; n < 2; ++n) _Pragma("unroll") for (int k = 0; k < 2; ++k) \
;         acc[ai][bj][m][n] = __builtin_amdgcn_mfma_f32_16x16x32_f16(Bt_[n][k], At[m][k], acc[ai][bj][m][n], 0, 0, 0); __builtin_amdgcn_s_setprio(0); } while (0)
; #define PG8_WAIT_V(n) asm volatile("s_waitcnt vmcnt(" #n ")" ::: "memory")
; #define PG8_WAIT_L(n) asm volatile("s_waitcnt lgkmcnt(" #n ")" ::: "memory")
; #define PG8_BAR __builtin_amdgcn_s_barrier()
; #define PG8_SCHED __builtin_amdgcn_sched_barrier(0)
; template <class Epi, class AMap>
; __device__ __forceinline__ void gemm_phase(LAS unsigned char* lds, const AMap am, const int lda, const h16* Bt, const int ldb, const int M, const int N, const int K, const Epi& E) {
;     ...
;             PG8_LDB(B0, 0, 0); PG8_SCHED; PG8_LDA(At, 0, 0); PG8_STAGE(PG8_SA(1, 1), a1 + hstepA, voffA);
;             PG8_WAIT_L(8); PG8_BAR; PG8_WAIT_L(0); PG8_MMA(0, 0, At, B0); PG8_BAR; PG8_SCHED;
;             PG8_LDB(B1, 0, 1); PG8_STAGE(PG8_SB(0, 0), b2, voffB);
;             PG8_BAR; PG8_WAIT_L(0); PG8_MMA(0, 1, At, B1); PG8_BAR;
;             PG8_LDA(At, 0, 1); PG8_STAGE(PG8_SA(0, 0), a2, voffA);
;             PG8_BAR; PG8_WAIT_L(0); PG8_MMA(1, 0, At, B0); PG8_BAR; PG8_SCHED;
;             PG8_STAGE(PG8_SB(0, 1), b2 + hstepB, voffB);
;             PG8_WAIT_V(6); PG8_BAR; PG8_MMA(1, 1, At, B1); PG8_BAR;
	v_mfma_f32_16x16x32_f16 v[126:129], v[142:145], v[166:169], v[126:129]
	v_mfma_f32_16x16x32_f16 v[122:125], v[158:161], v[166:169], v[122:125]
	v_mfma_f32_16x16x32_f16 v[110:113], v[142:145], v[174:177], v[110:113]
	v_mfma_f32_16x16x32_f16 v[106:109], v[158:161], v[174:177], v[106:109]
	v_mfma_f32_16x16x32_f16 v[94:97], v[142:145], v[182:185], v[94:97]
	v_mfma_f32_16x16x32_f16 v[90:93], v[158:161], v[182:185], v[90:93]
	v_mfma_f32_16x16x32_f16 v[78:81], v[142:145], v[190:193], v[78:81]
	v_mfma_f32_16x16x32_f16 v[74:77], v[158:161], v[190:193], v[74:77]
	v_mfma_f32_16x16x32_f16 v[126:129], v[154:157], v[170:173], v[126:129]
	v_mfma_f32_16x16x32_f16 v[122:125], v[162:165], v[170:173], v[122:125]
	v_mfma_f32_16x16x32_f16 v[110:113], v[154:157], v[178:181], v[110:113]
	v_mfma_f32_16x16x32_f16 v[106:109], v[162:165], v[178:181], v[106:109]
	v_mfma_f32_16x16x32_f16 v[94:97], v[154:157], v[186:189], v[94:97]
	v_mfma_f32_16x16x32_f16 v[90:93], v[162:165], v[186:189], v[90:93]
	v_mfma_f32_16x16x32_f16 v[78:81], v[154:157], v[194:197], v[78:81]
	v_mfma_f32_16x16x32_f16 v[74:77], v[162:165], v[194:197], v[74:77]
	v_mfma_f32_16x16x32_f16 v[118:121], v[198:201], v[166:169], v[118:121]
	v_mfma_f32_16x16x32_f16 v[114:117], v[220:223], v[166:169], v[114:117]
	v_mfma_f32_16x16x32_f16 v[102:105], v[198:201], v[174:177], v[102:105]
	v_mfma_f32_16x16x32_f16 v[98:101], v[220:223], v[174:177], v[98:101]
	v_mfma_f32_16x16x32_f16 v[86:89], v[198:201], v[182:185], v[86:89]
	v_mfma_f32_16x16x32_f16 v[82:85], v[220:223], v[182:185], v[82:85]
	v_mfma_f32_16x16x32_f16 v[70:73], v[198:201], v[190:193], v[70:73]
	v_mfma_f32_16x16x32_f16 v[66:69], v[220:223], v[190:193], v[66:69]
	v_mfma_f32_16x16x32_f16 v[118:121], v[202:205], v[170:173], v[118:121]
	v_mfma_f32_16x16x32_f16 v[114:117], v[224:227], v[170:173], v[114:117]
	v_mfma_f32_16x16x32_f16 v[102:105], v[202:205], v[178:181], v[102:105]
	v_mfma_f32_16x16x32_f16 v[98:101], v[224:227], v[178:181], v[98:101]
	v_mfma_f32_16x16x32_f16 v[86:89], v[202:205], v[186:189], v[86:89]
	v_mfma_f32_16x16x32_f16 v[82:85], v[224:227], v[186:189], v[82:85]
	v_mfma_f32_16x16x32_f16 v[70:73], v[202:205], v[194:197], v[70:73]
	v_mfma_f32_16x16x32_f16 v[66:69], v[224:227], v[194:197], v[66:69]
	s_barrier
	global_load_lds_dwordx4 v[146:147], off
	v_lshl_add_u64 v[206:207], s[42:43], 0, v[136:137]
	s_add_i32 m0, s45, 0x2000
	s_nop 0
	global_load_lds_dwordx4 v[206:207], off
	s_mov_b32 m0, s72
	v_lshl_add_u64 v[212:213], s[48:49], 0, v[130:131]
	ds_read_b128 v[166:169], v153 offset:16384
	ds_read_b128 v[170:173], v153 offset:17408
	ds_read_b128 v[174:177], v153 offset:18432
	ds_read_b128 v[178:181], v153 offset:19456
	ds_read_b128 v[182:185], v153 offset:20480
	ds_read_b128 v[186:189], v153 offset:21504
	ds_read_b128 v[190:193], v153 offset:22528
	ds_read_b128 v[194:197], v153 offset:23552
	global_load_lds_dwordx4 v[212:213], off
	v_lshl_add_u64 v[228:229], s[48:49], 0, v[134:135]
	s_mov_b32 m0, s73
	s_nop 0
	global_load_lds_dwordx4 v[228:229], off
	s_add_u32 s50, s42, 0x80000
	s_addc_u32 s51, s43, 0
	s_add_i32 s45, s60, s65
	v_lshl_add_u64 v[232:233], s[50:51], 0, v[132:133]
	s_mov_b32 m0, s45
	s_nop 0
	global_load_lds_dwordx4 v[232:233], off
	v_lshl_add_u64 v[232:233], s[50:51], 0, v[136:137]
	s_add_i32 m0, s45, 0x2000
	s_nop 0
	global_load_lds_dwordx4 v[232:233], off
	s_waitcnt vmcnt(8) lgkmcnt(0)
	s_barrier
	v_mfma_f32_16x16x32_f16 v[62:65], v[142:145], v[166:169], v[62:65]
	v_mfma_f32_16x16x32_f16 v[58:61], v[158:161], v[166:169], v[58:61]
	v_mfma_f32_16x16x32_f16 v[46:49], v[142:145], v[174:177], v[46:49]
	v_mfma_f32_16x16x32_f16 v[42:45], v[158:161], v[174:177], v[42:45]
	v_mfma_f32_16x16x32_f16 v[30:33], v[142:145], v[182:185], v[30:33]
	v_mfma_f32_16x16x32_f16 v[26:29], v[158:161], v[182:185], v[26:29]
	v_mfma_f32_16x16x32_f16 v[14:17], v[142:145], v[190:193], v[14:17]
	v_mfma_f32_16x16x32_f16 v[10:13], v[158:161], v[190:193], v[10:13]
	v_mfma_f32_16x16x32_f16 v[62:65], v[154:157], v[170:173], v[62:65]
	v_mfma_f32_16x16x32_f16 v[58:61], v[162:165], v[170:173], v[58:61]
	v_mfma_f32_16x16x32_f16 v[46:49], v[154:157], v[178:181], v[46:49]
	v_mfma_f32_16x16x32_f16 v[42:45], v[162:165], v[178:181], v[42:45]
	v_mfma_f32_16x16x32_f16 v[30:33], v[154:157], v[186:189], v[30:33]
	v_mfma_f32_16x16x32_f16 v[26:29], v[162:165], v[186:189], v[26:29]
	v_mfma_f32_16x16x32_f16 v[14:17], v[154:157], v[194:197], v[14:17]
	v_mfma_f32_16x16x32_f16 v[10:13], v[162:165], v[194:197], v[10:13]
	v_mfma_f32_16x16x32_f16 v[54:57], v[198:201], v[166:169], v[54:57]
	v_mfma_f32_16x16x32_f16 v[50:53], v[220:223], v[166:169], v[50:53]
	v_mfma_f32_16x16x32_f16 v[38:41], v[198:201], v[174:177], v[38:41]
	v_mfma_f32_16x16x32_f16 v[34:37], v[220:223], v[174:177], v[34:37]
	v_mfma_f32_16x16x32_f16 v[22:25], v[198:201], v[182:185], v[22:25]
	v_mfma_f32_16x16x32_f16 v[18:21], v[220:223], v[182:185], v[18:21]
	v_mfma_f32_16x16x32_f16 v[6:9], v[198:201], v[190:193], v[6:9]
	v_mfma_f32_16x16x32_f16 v[2:5], v[220:223], v[190:193], v[2:5]
	v_mfma_f32_16x16x32_f16 v[54:57], v[202:205], v[170:173], v[54:57]
	v_mfma_f32_16x16x32_f16 v[50:53], v[224:227], v[170:173], v[50:53]
	v_mfma_f32_16x16x32_f16 v[38:41], v[202:205], v[178:181], v[38:41]
	v_mfma_f32_16x16x32_f16 v[34:37], v[224:227], v[178:181], v[34:37]
	v_mfma_f32_16x16x32_f16 v[22:25], v[202:205], v[186:189], v[22:25]
	v_mfma_f32_16x16x32_f16 v[18:21], v[224:227], v[186:189], v[18:21]
	v_mfma_f32_16x16x32_f16 v[6:9], v[202:205], v[194:197], v[6:9]
	v_mfma_f32_16x16x32_f16 v[2:5], v[224:227], v[194:197], v[2:5]
	s_barrier
; #define PG8_STAGE(bufoff, gbase, voff) do { _Pragma("unroll") for (int _i = 0; _i < 2; ++_i) \
;         __builtin_amdgcn_global_load_lds((const unsigned*)((const char*)(gbase) + (voff)[_i]), (LAS unsigned*)(lds + (bufoff) + ldsw + _i * 8192), 16, 0, 0); } while (0)
; #define PG8_LDA(dst, b, h) do { _Pragma("unroll") for (int m = 0; m < 4; ++m) _Pragma("unroll") for (int k = 0; k < 2; ++k) dst[m][k] = *(const LAS h16x8*)(lds + PG8_SA(b, h) + aoff + m * 2048 + k * 1024); } while (0)
; #define PG8_LDB(dst, b, h) do { _Pragma("unroll") for (int n = 0; n < 2; ++n) _Pragma("unroll") for (int k = 0; k < 2; ++k) dst[n][k] = *(const LAS h16x8*)(lds + PG8_SB(b, h) + boff + n * 2048 + k * 1024); } while (0)
; #define PG8_MMA(ai, bj, At, Bt_) do { __builtin_amdgcn_s_setprio(1); _Pragma("unroll") for (int m = 0; m < 4; ++m) _Pragma("unroll") for (int n = 0; n < 2; ++n) _Pragma("unroll") for (int k = 0; k < 2; ++k) \
;         acc[ai][bj][m][n] = __builtin_amdgcn_mfma_f32_16x16x32_f16(Bt_[n][k], At[m][k], acc[ai][bj][m][n], 0, 0, 0); __builtin_amdgcn_s_setprio(0); } while (0)
; #define PG8_WAIT_V(n) asm volatile("s_waitcnt vmcnt(" #n ")" ::: "memory")
; #define PG8_WAIT_L(n) asm volatile("s_waitcnt lgkmcnt(" #n ")" ::: "memory")
; #define PG8_BAR __builtin_amdgcn_s_barrier()
; #define PG8_SCHED __builtin_amdgcn_sched_barrier(0)
; template <class Epi, class AMap>
; __device__ __forceinline__ void gemm_phase(LAS unsigned char* lds, const AMap am, const int lda, const h16* Bt, const int ldb, const int M, const int N, const int K, const Epi& E) {
;     ...
;             PG8_LDB(B0, 1, 0); PG8_SCHED; PG8_LDA(At, 1, 0); PG8_STAGE(PG8_SA(0, 1), a2 + hstepA, voffA);
;             PG8_WAIT_L(8); PG8_BAR; PG8_WAIT_L(0); PG8_MMA(0, 0, At, B0); PG8_BAR; PG8_SCHED;
;             PG8_LDB(B1, 1, 1); PG8_STAGE(PG8_SB(1, 0), b3, voffB);
;             PG8_BAR; PG8_WAIT_L(0); PG8_MMA(0, 1, At, B1); PG8_BAR;
;             PG8_LDA(At, 1, 1); PG8_STAGE(PG8_SA(1, 0), a3, voffA);
;             PG8_BAR; PG8_WAIT_L(0); PG8_MMA(1, 0, At, B0); PG8_BAR; PG8_SCHED;
;             PG8_STAGE(PG8_SB(1, 1), b3 + hstepB, voffB);
;             PG8_WAIT_V(6); PG8_BAR; PG8_MMA(1, 1, At, B1); PG8_BAR;
	s_add_i32 s45, 0, 0x18000
	v_add_u32_e32 v0, s45, v149
	ds_read_b128 v[142:145], v0
	ds_read_b128 v[154:157], v0 offset:1024
	ds_read_b128 v[158:161], v0 offset:2048
	ds_read_b128 v[162:165], v0 offset:3072
	s_add_u32 s48, s48, 0x80000
	s_addc_u32 s49, s49, 0
	s_mov_b32 m0, s74
	v_lshl_add_u64 v[232:233], s[48:49], 0, v[130:131]
	ds_read_b128 v[166:169], v153 offset:32768
	ds_read_b128 v[170:173], v153 offset:33792
	ds_read_b128 v[174:177], v153 offset:34816
	ds_read_b128 v[178:181], v153 offset:35840
	ds_read_b128 v[182:185], v153 offset:36864
	ds_read_b128 v[186:189], v153 offset:37888
	ds_read_b128 v[190:193], v153 offset:38912
	ds_read_b128 v[194:197], v153 offset:39936
	global_load_lds_dwordx4 v[232:233], off
	v_lshl_add_u64 v[232:233], s[48:49], 0, v[134:135]
	s_mov_b32 m0, s75
	s_nop 0
	global_load_lds_dwordx4 v[232:233], off
	s_waitcnt lgkmcnt(11)
	s_add_i32 s48, 0, 0x1c000
	s_add_i32 s45, s45, s65
	v_add_u32_e32 v0, s48, v149
	v_lshl_add_u64 v[146:147], v[146:147], 0, s[92:93]
	s_mov_b32 m0, s45
	ds_read_b128 v[198:201], v0
	ds_read_b128 v[202:205], v0 offset:1024
	ds_read_b128 v[220:223], v0 offset:2048
	ds_read_b128 v[224:227], v0 offset:3072
	s_waitcnt vmcnt(8) lgkmcnt(0)
	s_barrier
	v_mfma_f32_16x16x32_f16 v[126:129], v[142:145], v[166:169], v[126:129]
	v_mfma_f32_16x16x32_f16 v[122:125], v[158:161], v[166:169], v[122:125]
	v_mfma_f32_16x16x32_f16 v[110:113], v[142:145], v[174:177], v[110:113]
	v_mfma_f32_16x16x32_f16 v[106:109], v[158:161], v[174:177], v[106:109]
	v_mfma_f32_16x16x32_f16 v[94:97], v[142:145], v[182:185], v[94:97]
	v_mfma_f32_16x16x32_f16 v[90:93], v[158:161], v[182:185], v[90:93]
	v_mfma_f32_16x16x32_f16 v[78:81], v[142:145], v[190:193], v[78:81]
	v_mfma_f32_16x16x32_f16 v[74:77], v[158:161], v[190:193], v[74:77]
	v_mfma_f32_16x16x32_f16 v[126:129], v[154:157], v[170:173], v[126:129]
	v_mfma_f32_16x16x32_f16 v[122:125], v[162:165], v[170:173], v[122:125]
	v_mfma_f32_16x16x32_f16 v[110:113], v[154:157], v[178:181], v[110:113]
	v_mfma_f32_16x16x32_f16 v[106:109], v[162:165], v[178:181], v[106:109]
	v_mfma_f32_16x16x32_f16 v[94:97], v[154:157], v[186:189], v[94:97]
	v_mfma_f32_16x16x32_f16 v[90:93], v[162:165], v[186:189], v[90:93]
	v_mfma_f32_16x16x32_f16 v[78:81], v[154:157], v[194:197], v[78:81]
	v_mfma_f32_16x16x32_f16 v[74:77], v[162:165], v[194:197], v[74:77]
	v_mfma_f32_16x16x32_f16 v[118:121], v[198:201], v[166:169], v[118:121]
	v_mfma_f32_16x16x32_f16 v[114:117], v[220:223], v[166:169], v[114:117]
	v_mfma_f32_16x16x32_f16 v[102:105], v[198:201], v[174:177], v[102:105]
	v_mfma_f32_16x16x32_f16 v[98:101], v[220:223], v[174:177], v[98:101]
	v_mfma_f32_16x16x32_f16 v[86:89], v[198:201], v[182:185], v[86:89]
	v_mfma_f32_16x16x32_f16 v[82:85], v[220:223], v[182:185], v[82:85]
	v_mfma_f32_16x16x32_f16 v[70:73], v[198:201], v[190:193], v[70:73]
	v_mfma_f32_16x16x32_f16 v[66:69], v[220:223], v[190:193], v[66:69]
	v_mfma_f32_16x16x32_f16 v[118:121], v[202:205], v[170:173], v[118:121]
	v_mfma_f32_16x16x32_f16 v[114:117], v[224:227], v[170:173], v[114:117]
	v_mfma_f32_16x16x32_f16 v[102:105], v[202:205], v[178:181], v[102:105]
	v_mfma_f32_16x16x32_f16 v[98:101], v[224:227], v[178:181], v[98:101]
	v_mfma_f32_16x16x32_f16 v[86:89], v[202:205], v[186:189], v[86:89]
	v_mfma_f32_16x16x32_f16 v[82:85], v[224:227], v[186:189], v[82:85]
	v_mfma_f32_16x16x32_f16 v[70:73], v[202:205], v[194:197], v[70:73]
	v_mfma_f32_16x16x32_f16 v[66:69], v[224:227], v[194:197], v[66:69]
	s_barrier
	global_load_lds_dwordx4 v[146:147], off
	v_lshl_add_u64 v[146:147], v[206:207], 0, s[92:93]
	s_add_i32 m0, s45, 0x2000
	s_nop 0
	global_load_lds_dwordx4 v[146:147], off
	s_mov_b32 m0, s77
	v_lshl_add_u64 v[146:147], v[212:213], 0, s[92:93]
	ds_read_b128 v[166:169], v153 offset:49152
	ds_read_b128 v[170:173], v153 offset:50176
	ds_read_b128 v[174:177], v153 offset:51200
	ds_read_b128 v[178:181], v153 offset:52224
	ds_read_b128 v[182:185], v153 offset:53248
	ds_read_b128 v[186:189], v153 offset:54272
	ds_read_b128 v[190:193], v153 offset:55296
	ds_read_b128 v[194:197], v153 offset:56320
	global_load_lds_dwordx4 v[146:147], off
	v_lshl_add_u64 v[146:147], v[228:229], 0, s[92:93]
	s_mov_b32 m0, s78
	s_nop 0
	global_load_lds_dwordx4 v[146:147], off
	s_add_u32 s42, s42, 0x80080
	s_addc_u32 s43, s43, 0
	s_add_i32 s45, s48, s65
	v_lshl_add_u64 v[232:233], s[42:43], 0, v[132:133]
	s_mov_b32 m0, s45
	s_nop 0
	global_load_lds_dwordx4 v[232:233], off
	v_lshl_add_u64 v[232:233], s[42:43], 0, v[136:137]
	s_add_i32 m0, s45, 0x2000
	s_nop 0
	global_load_lds_dwordx4 v[232:233], off
	s_add_i32 s35, s35, 2
	s_add_u32 s40, s40, 0x100
	s_addc_u32 s41, s41, 0
	s_add_u32 s21, s21, 0x100
	s_addc_u32 s29, s29, 0
	s_cmp_gt_u32 s35, 29
	s_waitcnt vmcnt(8) lgkmcnt(0)
	s_barrier
	v_mfma_f32_16x16x32_f16 v[62:65], v[142:145], v[166:169], v[62:65]
	v_mfma_f32_16x16x32_f16 v[58:61], v[158:161], v[166:169], v[58:61]
	v_mfma_f32_16x16x32_f16 v[46:49], v[142:145], v[174:177], v[46:49]
	v_mfma_f32_16x16x32_f16 v[42:45], v[158:161], v[174:177], v[42:45]
	v_mfma_f32_16x16x32_f16 v[30:33], v[142:145], v[182:185], v[30:33]
	v_mfma_f32_16x16x32_f16 v[26:29], v[158:161], v[182:185], v[26:29]
	v_mfma_f32_16x16x32_f16 v[14:17], v[142:145], v[190:193], v[14:17]
	v_mfma_f32_16x16x32_f16 v[10:13], v[158:161], v[190:193], v[10:13]
	v_mfma_f32_16x16x32_f16 v[62:65], v[154:157], v[170:173], v[62:65]
	v_mfma_f32_16x16x32_f16 v[58:61], v[162:165], v[170:173], v[58:61]
	v_mfma_f32_16x16x32_f16 v[46:49], v[154:157], v[178:181], v[46:49]
	v_mfma_f32_16x16x32_f16 v[42:45], v[162:165], v[178:181], v[42:45]
	v_mfma_f32_16x16x32_f16 v[30:33], v[154:157], v[186:189], v[30:33]
	v_mfma_f32_16x16x32_f16 v[26:29], v[162:165], v[186:189], v[26:29]
	v_mfma_f32_16x16x32_f16 v[14:17], v[154:157], v[194:197], v[14:17]
	v_mfma_f32_16x16x32_f16 v[10:13], v[162:165], v[194:197], v[10:13]
	v_mfma_f32_16x16x32_f16 v[54:57], v[198:201], v[166:169], v[54:57]
	v_mfma_f32_16x16x32_f16 v[50:53], v[220:223], v[166:169], v[50:53]
	v_mfma_f32_16x16x32_f16 v[38:41], v[198:201], v[174:177], v[38:41]
	v_mfma_f32_16x16x32_f16 v[34:37], v[220:223], v[174:177], v[34:37]
	v_mfma_f32_16x16x32_f16 v[22:25], v[198:201], v[182:185], v[22:25]
	v_mfma_f32_16x16x32_f16 v[18:21], v[220:223], v[182:185], v[18:21]
	v_mfma_f32_16x16x32_f16 v[6:9], v[198:201], v[190:193], v[6:9]
	v_mfma_f32_16x16x32_f16 v[2:5], v[220:223], v[190:193], v[2:5]
	v_mfma_f32_16x16x32_f16 v[54:57], v[202:205], v[170:173], v[54:57]
	v_mfma_f32_16x16x32_f16 v[50:53], v[224:227], v[170:173], v[50:53]
	v_mfma_f32_16x16x32_f16 v[38:41], v[202:205], v[178:181], v[38:41]
	v_mfma_f32_16x16x32_f16 v[34:37], v[224:227], v[178:181], v[34:37]
	v_mfma_f32_16x16x32_f16 v[22:25], v[202:205], v[186:189], v[22:25]
	v_mfma_f32_16x16x32_f16 v[18:21], v[224:227], v[186:189], v[18:21]
	v_mfma_f32_16x16x32_f16 v[6:9], v[202:205], v[194:197], v[6:9]
	v_mfma_f32_16x16x32_f16 v[2:5], v[224:227], v[194:197], v[2:5]
	s_barrier
	s_cbranch_scc0 .LBB0_268
.Lg4x_268:
	s_cmpk_gt_u32 s64, 0xff
	s_cbranch_scc1 .Lgx3
	s_barrier

; #define PG8_STAGE(bufoff, gbase, voff) do { _Pragma("unroll") for (int _i = 0; _i < 2; ++_i) \
;         __builtin_amdgcn_global_load_lds((const unsigned*)((const char*)(gbase) + (voff)[_i]), (LAS unsigned*)(lds + (bufoff) + ldsw + _i * 8192), 16, 0, 0); } while (0)
; #define PG8_LDA(dst, b, h) do { _Pragma("unroll") for (int m = 0; m < 4; ++m) _Pragma("unroll") for (int k = 0; k < 2; ++k) dst[m][k] = *(const LAS h16x8*)(lds + PG8_SA(b, h) + aoff + m * 2048 + k * 1024); } while (0)
; #define PG8_LDB(dst, b, h) do { _Pragma("unroll") for (int n = 0; n < 2; ++n) _Pragma("unroll") for (int k = 0; k < 2; ++k) dst[n][k] = *(const LAS h16x8*)(lds + PG8_SB(b, h) + boff + n * 2048 + k * 1024); } while (0)
; #define PG8_MMA(ai, bj, At, Bt_) do { __builtin_amdgcn_s_setprio(1); _Pragma("unroll") for (int m = 0; m < 4; ++m) _Pragma("unroll") for (int n = 0; n < 2; ++n) _Pragma("unroll") for (int k = 0; k < 2; ++k) \
;         acc[ai][bj][m][n] = __builtin_amdgcn_mfma_f32_16x16x32_f16(Bt_[n][k], At[m][k], acc[ai][bj][m][n], 0, 0, 0); __builtin_amdgcn_s_setprio(0); } while (0)
; #define PG8_WAIT_V(n) asm volatile("s_waitcnt vmcnt(" #n ")" ::: "memory")
; #define PG8_WAIT_L(n) asm volatile("s_waitcnt lgkmcnt(" #n ")" ::: "memory")
; #define PG8_BAR __builtin_amdgcn_s_barrier()
; #define PG8_SCHED __builtin_amdgcn_sched_barrier(0)
; template <class Epi, class AMap>
; __device__ __forceinline__ void gemm_phase(LAS unsigned char* lds, const AMap am, const int lda, const h16* Bt, const int ldb, const int M, const int N, const int K, const Epi& E) {
;     ...
;             PG8_LDB(B0, 0, 0); PG8_SCHED; PG8_LDA(At, 0, 0); PG8_STAGE(PG8_SA(1, 1), a1 + hstepA, voffA);
;             PG8_WAIT_L(8); PG8_BAR; PG8_WAIT_L(0); PG8_MMA(0, 0, At, B0); PG8_BAR; PG8_SCHED;
;             PG8_LDB(B1, 0, 1); PG8_STAGE(PG8_SB(0, 0), b2, voffB);
;             PG8_BAR; PG8_WAIT_L(0); PG8_MMA(0, 1, At, B1); PG8_BAR;
;             PG8_LDA(At, 0, 1); PG8_STAGE(PG8_SA(0, 0), a2, voffA);
;             PG8_BAR; PG8_WAIT_L(0); PG8_MMA(1, 0, At, B0); PG8_BAR; PG8_SCHED;
;             PG8_STAGE(PG8_SB(0, 1), b2 + hstepB, voffB);
;             PG8_WAIT_V(6); PG8_BAR; PG8_MMA(1, 1, At, B1); PG8_BAR;
.LBB0_621:
	s_add_i32 s51, s26, 2
	s_add_u32 s0, s22, 0x100
	s_addc_u32 s1, s23, 0
	s_add_i32 s60, 0, 0x10000
	v_add_u32_e32 v152, s60, v155
	ds_read_b128 v[90:93], v152
	ds_read_b128 v[94:97], v152 offset:1024
	ds_read_b128 v[148:151], v152 offset:2048
	ds_read_b128 v[158:161], v152 offset:3072
	s_cmp_eq_u32 s82, s26
	s_cselect_b32 s26, s21, s29
	s_cselect_b32 s49, s65, s1
	s_cselect_b32 s48, s64, s0
	s_cselect_b32 s27, s20, s45
	v_lshl_add_u64 v[152:153], s[22:23], 0, v[144:145]
	s_add_i32 m0, s76, 0xc000
	ds_read_b128 v[162:165], v157
	ds_read_b128 v[166:169], v157 offset:1024
	ds_read_b128 v[170:173], v157 offset:2048
	ds_read_b128 v[174:177], v157 offset:3072
	ds_read_b128 v[178:181], v157 offset:4096
	ds_read_b128 v[182:185], v157 offset:5120
	ds_read_b128 v[186:189], v157 offset:6144
	ds_read_b128 v[190:193], v157 offset:7168
	global_load_lds_dwordx4 v[152:153], off
	v_lshl_add_u64 v[152:153], s[22:23], 0, v[146:147]
	s_add_i32 m0, s76, 0xe000
	s_nop 0
	global_load_lds_dwordx4 v[152:153], off
	s_waitcnt lgkmcnt(11)
	s_add_i32 s62, 0, 0x14000
	v_add_u32_e32 v152, s62, v155
	s_add_i32 s22, s60, s73
	ds_read_b128 v[194:197], v152
	ds_read_b128 v[198:201], v152 offset:1024
	ds_read_b128 v[202:205], v152 offset:2048
	ds_read_b128 v[220:223], v152 offset:3072
	s_waitcnt vmcnt(8) lgkmcnt(0)
	s_barrier
	v_mfma_f32_16x16x32_f16 v[130:133], v[90:93], v[162:165], v[130:133]
	v_mfma_f32_16x16x32_f16 v[134:137], v[148:151], v[162:165], v[134:137]
	v_mfma_f32_16x16x32_f16 v[126:129], v[90:93], v[170:173], v[126:129]
	v_mfma_f32_16x16x32_f16 v[122:125], v[148:151], v[170:173], v[122:125]
	v_mfma_f32_16x16x32_f16 v[118:121], v[90:93], v[178:181], v[118:121]
	v_mfma_f32_16x16x32_f16 v[114:117], v[148:151], v[178:181], v[114:117]
	v_mfma_f32_16x16x32_f16 v[110:113], v[90:93], v[186:189], v[110:113]
	v_mfma_f32_16x16x32_f16 v[106:109], v[148:151], v[186:189], v[106:109]
	v_mfma_f32_16x16x32_f16 v[130:133], v[94:97], v[166:169], v[130:133]
	v_mfma_f32_16x16x32_f16 v[134:137], v[158:161], v[166:169], v[134:137]
	v_mfma_f32_16x16x32_f16 v[126:129], v[94:97], v[174:177], v[126:129]
	v_mfma_f32_16x16x32_f16 v[122:125], v[158:161], v[174:177], v[122:125]
	v_mfma_f32_16x16x32_f16 v[118:121], v[94:97], v[182:185], v[118:121]
	v_mfma_f32_16x16x32_f16 v[114:117], v[158:161], v[182:185], v[114:117]
	v_mfma_f32_16x16x32_f16 v[110:113], v[94:97], v[190:193], v[110:113]
	v_mfma_f32_16x16x32_f16 v[106:109], v[158:161], v[190:193], v[106:109]
	v_mfma_f32_16x16x32_f16 v[62:65], v[194:197], v[162:165], v[62:65]
	v_mfma_f32_16x16x32_f16 v[58:61], v[202:205], v[162:165], v[58:61]
	v_mfma_f32_16x16x32_f16 v[54:57], v[194:197], v[170:173], v[54:57]
	v_mfma_f32_16x16x32_f16 v[50:53], v[202:205], v[170:173], v[50:53]
	v_mfma_f32_16x16x32_f16 v[46:49], v[194:197], v[178:181], v[46:49]
	v_mfma_f32_16x16x32_f16 v[42:45], v[202:205], v[178:181], v[42:45]
	v_mfma_f32_16x16x32_f16 v[38:41], v[194:197], v[186:189], v[38:41]
	v_mfma_f32_16x16x32_f16 v[34:37], v[202:205], v[186:189], v[34:37]
	v_mfma_f32_16x16x32_f16 v[62:65], v[198:201], v[166:169], v[62:65]
	v_mfma_f32_16x16x32_f16 v[58:61], v[220:223], v[166:169], v[58:61]
	v_mfma_f32_16x16x32_f16 v[54:57], v[198:201], v[174:177], v[54:57]
	v_mfma_f32_16x16x32_f16 v[50:53], v[220:223], v[174:177], v[50:53]
	v_mfma_f32_16x16x32_f16 v[46:49], v[198:201], v[182:185], v[46:49]
	v_mfma_f32_16x16x32_f16 v[42:45], v[220:223], v[182:185], v[42:45]
	v_mfma_f32_16x16x32_f16 v[38:41], v[198:201], v[190:193], v[38:41]
	v_mfma_f32_16x16x32_f16 v[34:37], v[220:223], v[190:193], v[34:37]
	s_barrier
	v_lshl_add_u64 v[152:153], s[26:27], 0, v[0:1]
	s_mov_b32 m0, s22
	v_lshl_add_u64 v[206:207], s[26:27], 0, v[142:143]
	global_load_lds_dwordx4 v[152:153], off
	s_add_i32 m0, s22, 0x2000
	s_nop 0
	global_load_lds_dwordx4 v[206:207], off
	s_mov_b32 m0, s76
	v_lshl_add_u64 v[212:213], s[48:49], 0, v[138:139]
	ds_read_b128 v[162:165], v157 offset:16384
	ds_read_b128 v[166:169], v157 offset:17408
	ds_read_b128 v[170:173], v157 offset:18432
	ds_read_b128 v[174:177], v157 offset:19456
	ds_read_b128 v[178:181], v157 offset:20480
	ds_read_b128 v[182:185], v157 offset:21504
	ds_read_b128 v[186:189], v157 offset:22528
	ds_read_b128 v[190:193], v157 offset:23552
	global_load_lds_dwordx4 v[212:213], off
	v_lshl_add_u64 v[224:225], s[48:49], 0, v[140:141]
	s_mov_b32 m0, s77
	s_nop 0
	global_load_lds_dwordx4 v[224:225], off
	s_add_u32 s22, s26, 0x10000
	s_addc_u32 s23, s27, 0
	s_add_i32 s60, s62, s73
	v_lshl_add_u64 v[232:233], s[22:23], 0, v[0:1]
	s_mov_b32 m0, s60
	s_nop 0
	global_load_lds_dwordx4 v[232:233], off
	v_lshl_add_u64 v[232:233], s[22:23], 0, v[142:143]
	s_add_i32 m0, s60, 0x2000
	s_nop 0
	global_load_lds_dwordx4 v[232:233], off
	s_waitcnt vmcnt(8) lgkmcnt(0)
	s_barrier
; #define PG8_STAGE(bufoff, gbase, voff) do { _Pragma("unroll") for (int _i = 0; _i < 2; ++_i) \
;         __builtin_amdgcn_global_load_lds((const unsigned*)((const char*)(gbase) + (voff)[_i]), (LAS unsigned*)(lds + (bufoff) + ldsw + _i * 8192), 16, 0, 0); } while (0)
; #define PG8_LDA(dst, b, h) do { _Pragma("unroll") for (int m = 0; m < 4; ++m) _Pragma("unroll") for (int k = 0; k < 2; ++k) dst[m][k] = *(const LAS h16x8*)(lds + PG8_SA(b, h) + aoff + m * 2048 + k * 1024); } while (0)
; #define PG8_LDB(dst, b, h) do { _Pragma("unroll") for (int n = 0; n < 2; ++n) _Pragma("unroll") for (int k = 0; k < 2; ++k) dst[n][k] = *(const LAS h16x8*)(lds + PG8_SB(b, h) + boff + n * 2048 + k * 1024); } while (0)
; #define PG8_MMA(ai, bj, At, Bt_) do { __builtin_amdgcn_s_setprio(1); _Pragma("unroll") for (int m = 0; m < 4; ++m) _Pragma("unroll") for (int n = 0; n < 2; ++n) _Pragma("unroll") for (int k = 0; k < 2; ++k) \
;         acc[ai][bj][m][n] = __builtin_amdgcn_mfma_f32_16x16x32_f16(Bt_[n][k], At[m][k], acc[ai][bj][m][n], 0, 0, 0); __builtin_amdgcn_s_setprio(0); } while (0)
; #define PG8_WAIT_V(n) asm volatile("s_waitcnt vmcnt(" #n ")" ::: "memory")
; #define PG8_WAIT_L(n) asm volatile("s_waitcnt lgkmcnt(" #n ")" ::: "memory")
; #define PG8_BAR __builtin_amdgcn_s_barrier()
; #define PG8_SCHED __builtin_amdgcn_sched_barrier(0)
; template <class Epi, class AMap>
; __device__ __forceinline__ void gemm_phase(LAS unsigned char* lds, const AMap am, const int lda, const h16* Bt, const int ldb, const int M, const int N, const int K, const Epi& E) {
;     ...
;             PG8_WAIT_V(6); PG8_BAR; PG8_MMA(1, 1, At, B1); PG8_BAR;
;             PG8_LDB(B0, 1, 0); PG8_SCHED; PG8_LDA(At, 1, 0); PG8_STAGE(PG8_SA(0, 1), a2 + hstepA, voffA);
;             PG8_WAIT_L(8); PG8_BAR; PG8_WAIT_L(0); PG8_MMA(0, 0, At, B0); PG8_BAR; PG8_SCHED;
;             PG8_LDB(B1, 1, 1); PG8_STAGE(PG8_SB(1, 0), b3, voffB);
;             PG8_BAR; PG8_WAIT_L(0); PG8_MMA(0, 1, At, B1); PG8_BAR;
;             PG8_LDA(At, 1, 1); PG8_STAGE(PG8_SA(1, 0), a3, voffA);
;             PG8_BAR; PG8_WAIT_L(0); PG8_MMA(1, 0, At, B0); PG8_BAR; PG8_SCHED;
	v_mfma_f32_16x16x32_f16 v[102:105], v[90:93], v[162:165], v[102:105]
	v_mfma_f32_16x16x32_f16 v[98:101], v[148:151], v[162:165], v[98:101]
	v_mfma_f32_16x16x32_f16 v[86:89], v[90:93], v[170:173], v[86:89]
	v_mfma_f32_16x16x32_f16 v[82:85], v[148:151], v[170:173], v[82:85]
	v_mfma_f32_16x16x32_f16 v[78:81], v[90:93], v[178:181], v[78:81]
	v_mfma_f32_16x16x32_f16 v[74:77], v[148:151], v[178:181], v[74:77]
	v_mfma_f32_16x16x32_f16 v[70:73], v[90:93], v[186:189], v[70:73]
	v_mfma_f32_16x16x32_f16 v[66:69], v[148:151], v[186:189], v[66:69]
	v_mfma_f32_16x16x32_f16 v[102:105], v[94:97], v[166:169], v[102:105]
	v_mfma_f32_16x16x32_f16 v[98:101], v[158:161], v[166:169], v[98:101]
	v_mfma_f32_16x16x32_f16 v[86:89], v[94:97], v[174:177], v[86:89]
	v_mfma_f32_16x16x32_f16 v[82:85], v[158:161], v[174:177], v[82:85]
	v_mfma_f32_16x16x32_f16 v[78:81], v[94:97], v[182:185], v[78:81]
	v_mfma_f32_16x16x32_f16 v[74:77], v[158:161], v[182:185], v[74:77]
	v_mfma_f32_16x16x32_f16 v[70:73], v[94:97], v[190:193], v[70:73]
	v_mfma_f32_16x16x32_f16 v[66:69], v[158:161], v[190:193], v[66:69]
	v_mfma_f32_16x16x32_f16 v[30:33], v[194:197], v[162:165], v[30:33]
	v_mfma_f32_16x16x32_f16 v[26:29], v[202:205], v[162:165], v[26:29]
	v_mfma_f32_16x16x32_f16 v[22:25], v[194:197], v[170:173], v[22:25]
	v_mfma_f32_16x16x32_f16 v[18:21], v[202:205], v[170:173], v[18:21]
	v_mfma_f32_16x16x32_f16 v[14:17], v[194:197], v[178:181], v[14:17]
	v_mfma_f32_16x16x32_f16 v[10:13], v[202:205], v[178:181], v[10:13]
	v_mfma_f32_16x16x32_f16 v[6:9], v[194:197], v[186:189], v[6:9]
	v_mfma_f32_16x16x32_f16 v[2:5], v[202:205], v[186:189], v[2:5]
	v_mfma_f32_16x16x32_f16 v[30:33], v[198:201], v[166:169], v[30:33]
	v_mfma_f32_16x16x32_f16 v[26:29], v[220:223], v[166:169], v[26:29]
	v_mfma_f32_16x16x32_f16 v[22:25], v[198:201], v[174:177], v[22:25]
	v_mfma_f32_16x16x32_f16 v[18:21], v[220:223], v[174:177], v[18:21]
	v_mfma_f32_16x16x32_f16 v[14:17], v[198:201], v[182:185], v[14:17]
	v_mfma_f32_16x16x32_f16 v[10:13], v[220:223], v[182:185], v[10:13]
	v_mfma_f32_16x16x32_f16 v[6:9], v[198:201], v[190:193], v[6:9]
	v_mfma_f32_16x16x32_f16 v[2:5], v[220:223], v[190:193], v[2:5]
	s_barrier
	s_add_i32 s60, 0, 0x18000
	v_add_u32_e32 v234, s60, v155
	ds_read_b128 v[90:93], v234
	ds_read_b128 v[94:97], v234 offset:1024
	ds_read_b128 v[148:151], v234 offset:2048
	ds_read_b128 v[158:161], v234 offset:3072
	s_add_u32 s22, s48, 0x1c0000
	s_addc_u32 s23, s49, 0
	s_mov_b32 m0, s78
	v_lshl_add_u64 v[232:233], s[22:23], 0, v[138:139]
	ds_read_b128 v[162:165], v157 offset:32768
	ds_read_b128 v[166:169], v157 offset:33792
	ds_read_b128 v[170:173], v157 offset:34816
	ds_read_b128 v[174:177], v157 offset:35840
	ds_read_b128 v[178:181], v157 offset:36864
	ds_read_b128 v[182:185], v157 offset:37888
	ds_read_b128 v[186:189], v157 offset:38912
	ds_read_b128 v[190:193], v157 offset:39936
	global_load_lds_dwordx4 v[232:233], off
	v_lshl_add_u64 v[232:233], s[22:23], 0, v[140:141]
	s_mov_b32 m0, s79
	s_nop 0
	global_load_lds_dwordx4 v[232:233], off
	s_waitcnt lgkmcnt(11)
	s_add_i32 s48, 0, 0x1c000
	s_add_i32 s22, s60, s73
	v_add_u32_e32 v214, s48, v155
	v_lshl_add_u64 v[152:153], v[152:153], 0, s[92:93]
	s_mov_b32 m0, s22
	ds_read_b128 v[194:197], v214
	ds_read_b128 v[198:201], v214 offset:1024
	ds_read_b128 v[202:205], v214 offset:2048
	ds_read_b128 v[220:223], v214 offset:3072
	s_waitcnt vmcnt(8) lgkmcnt(0)
	s_barrier
	v_mfma_f32_16x16x32_f16 v[130:133], v[90:93], v[162:165], v[130:133]
	v_mfma_f32_16x16x32_f16 v[134:137], v[148:151], v[162:165], v[134:137]
	v_mfma_f32_16x16x32_f16 v[126:129], v[90:93], v[170:173], v[126:129]
	v_mfma_f32_16x16x32_f16 v[122:125], v[148:151], v[170:173], v[122:125]
	v_mfma_f32_16x16x32_f16 v[118:121], v[90:93], v[178:181], v[118:121]
	v_mfma_f32_16x16x32_f16 v[114:117], v[148:151], v[178:181], v[114:117]
	v_mfma_f32_16x16x32_f16 v[110:113], v[90:93], v[186:189], v[110:113]
	v_mfma_f32_16x16x32_f16 v[106:109], v[148:151], v[186:189], v[106:109]
	v_mfma_f32_16x16x32_f16 v[130:133], v[94:97], v[166:169], v[130:133]
	v_mfma_f32_16x16x32_f16 v[134:137], v[158:161], v[166:169], v[134:137]
	v_mfma_f32_16x16x32_f16 v[126:129], v[94:97], v[174:177], v[126:129]
	v_mfma_f32_16x16x32_f16 v[122:125], v[158:161], v[174:177], v[122:125]
	v_mfma_f32_16x16x32_f16 v[118:121], v[94:97], v[182:185], v[118:121]
	v_mfma_f32_16x16x32_f16 v[114:117], v[158:161], v[182:185], v[114:117]
	v_mfma_f32_16x16x32_f16 v[110:113], v[94:97], v[190:193], v[110:113]
	v_mfma_f32_16x16x32_f16 v[106:109], v[158:161], v[190:193], v[106:109]
	v_mfma_f32_16x16x32_f16 v[62:65], v[194:197], v[162:165], v[62:65]
	v_mfma_f32_16x16x32_f16 v[58:61], v[202:205], v[162:165], v[58:61]
	v_mfma_f32_16x16x32_f16 v[54:57], v[194:197], v[170:173], v[54:57]
	v_mfma_f32_16x16x32_f16 v[50:53], v[202:205], v[170:173], v[50:53]
	v_mfma_f32_16x16x32_f16 v[46:49], v[194:197], v[178:181], v[46:49]
	v_mfma_f32_16x16x32_f16 v[42:45], v[202:205], v[178:181], v[42:45]
	v_mfma_f32_16x16x32_f16 v[38:41], v[194:197], v[186:189], v[38:41]
	v_mfma_f32_16x16x32_f16 v[34:37], v[202:205], v[186:189], v[34:37]
	v_mfma_f32_16x16x32_f16 v[62:65], v[198:201], v[166:169], v[62:65]
	v_mfma_f32_16x16x32_f16 v[58:61], v[220:223], v[166:169], v[58:61]
	v_mfma_f32_16x16x32_f16 v[54:57], v[198:201], v[174:177], v[54:57]
	v_mfma_f32_16x16x32_f16 v[50:53], v[220:223], v[174:177], v[50:53]
	v_mfma_f32_16x16x32_f16 v[46:49], v[198:201], v[182:185], v[46:49]
	v_mfma_f32_16x16x32_f16 v[42:45], v[220:223], v[182:185], v[42:45]
	v_mfma_f32_16x16x32_f16 v[38:41], v[198:201], v[190:193], v[38:41]
	v_mfma_f32_16x16x32_f16 v[34:37], v[220:223], v[190:193], v[34:37]
	s_barrier
; #define PG8_STAGE(bufoff, gbase, voff) do { _Pragma("unroll") for (int _i = 0; _i < 2; ++_i) \
;         __builtin_amdgcn_global_load_lds((const unsigned*)((const char*)(gbase) + (voff)[_i]), (LAS unsigned*)(lds + (bufoff) + ldsw + _i * 8192), 16, 0, 0); } while (0)
; #define PG8_LDA(dst, b, h) do { _Pragma("unroll") for (int m = 0; m < 4; ++m) _Pragma("unroll") for (int k = 0; k < 2; ++k) dst[m][k] = *(const LAS h16x8*)(lds + PG8_SA(b, h) + aoff + m * 2048 + k * 1024); } while (0)
; #define PG8_LDB(dst, b, h) do { _Pragma("unroll") for (int n = 0; n < 2; ++n) _Pragma("unroll") for (int k = 0; k < 2; ++k) dst[n][k] = *(const LAS h16x8*)(lds + PG8_SB(b, h) + boff + n * 2048 + k * 1024); } while (0)
; #define PG8_MMA(ai, bj, At, Bt_) do { __builtin_amdgcn_s_setprio(1); _Pragma("unroll") for (int m = 0; m < 4; ++m) _Pragma("unroll") for (int n = 0; n < 2; ++n) _Pragma("unroll") for (int k = 0; k < 2; ++k) \
;         acc[ai][bj][m][n] = __builtin_amdgcn_mfma_f32_16x16x32_f16(Bt_[n][k], At[m][k], acc[ai][bj][m][n], 0, 0, 0); __builtin_amdgcn_s_setprio(0); } while (0)
; #define PG8_WAIT_V(n) asm volatile("s_waitcnt vmcnt(" #n ")" ::: "memory")
; #define PG8_WAIT_L(n) asm volatile("s_waitcnt lgkmcnt(" #n ")" ::: "memory")
; #define PG8_BAR __builtin_amdgcn_s_barrier()
; #define PG8_SCHED __builtin_amdgcn_sched_barrier(0)
; template <class Epi, class AMap>
; __device__ __forceinline__ void gemm_phase(LAS unsigned char* lds, const AMap am, const int lda, const h16* Bt, const int ldb, const int M, const int N, const int K, const Epi& E) {
;     ...
;             PG8_LDB(B0, 1, 0); PG8_SCHED; PG8_LDA(At, 1, 0); PG8_STAGE(PG8_SA(0, 1), a2 + hstepA, voffA);
;             PG8_WAIT_L(8); PG8_BAR; PG8_WAIT_L(0); PG8_MMA(0, 0, At, B0); PG8_BAR; PG8_SCHED;
;             PG8_LDB(B1, 1, 1); PG8_STAGE(PG8_SB(1, 0), b3, voffB);
;             PG8_BAR; PG8_WAIT_L(0); PG8_MMA(0, 1, At, B1); PG8_BAR;
;             PG8_LDA(At, 1, 1); PG8_STAGE(PG8_SA(1, 0), a3, voffA);
;             PG8_BAR; PG8_WAIT_L(0); PG8_MMA(1, 0, At, B0); PG8_BAR; PG8_SCHED;
;             PG8_STAGE(PG8_SB(1, 1), b3 + hstepB, voffB);
;             PG8_WAIT_V(6); PG8_BAR; PG8_MMA(1, 1, At, B1); PG8_BAR;
;         }
	global_load_lds_dwordx4 v[152:153], off
	v_lshl_add_u64 v[152:153], v[206:207], 0, s[92:93]
	s_add_i32 m0, s22, 0x2000
	s_nop 0
	global_load_lds_dwordx4 v[152:153], off
	s_mov_b32 m0, s80
	v_lshl_add_u64 v[152:153], v[212:213], 0, s[92:93]
	ds_read_b128 v[162:165], v157 offset:49152
	ds_read_b128 v[166:169], v157 offset:50176
	ds_read_b128 v[170:173], v157 offset:51200
	ds_read_b128 v[174:177], v157 offset:52224
	ds_read_b128 v[178:181], v157 offset:53248
	ds_read_b128 v[182:185], v157 offset:54272
	ds_read_b128 v[186:189], v157 offset:55296
	ds_read_b128 v[190:193], v157 offset:56320
	global_load_lds_dwordx4 v[152:153], off
	v_lshl_add_u64 v[152:153], v[224:225], 0, s[92:93]
	s_mov_b32 m0, s81
	s_nop 0
	global_load_lds_dwordx4 v[152:153], off
	s_add_u32 s22, s26, 0x10080
	s_addc_u32 s23, s27, 0
	s_add_i32 s26, s48, s73
	v_lshl_add_u64 v[232:233], s[22:23], 0, v[0:1]
	s_mov_b32 m0, s26
	s_nop 0
	global_load_lds_dwordx4 v[232:233], off
	v_lshl_add_u64 v[232:233], s[22:23], 0, v[142:143]
	s_add_i32 m0, s26, 0x2000
	s_nop 0
	global_load_lds_dwordx4 v[232:233], off
	s_add_u32 s29, s29, 0x100
	s_addc_u32 s45, s45, 0
	s_cmp_ge_i32 s51, s24
	s_mov_b64 s[22:23], s[0:1]
	s_mov_b32 s26, s51
	s_waitcnt vmcnt(8) lgkmcnt(0)
	s_barrier
	v_mfma_f32_16x16x32_f16 v[102:105], v[90:93], v[162:165], v[102:105]
	v_mfma_f32_16x16x32_f16 v[98:101], v[148:151], v[162:165], v[98:101]
	v_mfma_f32_16x16x32_f16 v[86:89], v[90:93], v[170:173], v[86:89]
	v_mfma_f32_16x16x32_f16 v[82:85], v[148:151], v[170:173], v[82:85]
	v_mfma_f32_16x16x32_f16 v[78:81], v[90:93], v[178:181], v[78:81]
	v_mfma_f32_16x16x32_f16 v[74:77], v[148:151], v[178:181], v[74:77]
	v_mfma_f32_16x16x32_f16 v[70:73], v[90:93], v[186:189], v[70:73]
	v_mfma_f32_16x16x32_f16 v[66:69], v[148:151], v[186:189], v[66:69]
	v_mfma_f32_16x16x32_f16 v[102:105], v[94:97], v[166:169], v[102:105]
	v_mfma_f32_16x16x32_f16 v[98:101], v[158:161], v[166:169], v[98:101]
	v_mfma_f32_16x16x32_f16 v[86:89], v[94:97], v[174:177], v[86:89]
	v_mfma_f32_16x16x32_f16 v[82:85], v[158:161], v[174:177], v[82:85]
	v_mfma_f32_16x16x32_f16 v[78:81], v[94:97], v[182:185], v[78:81]
	v_mfma_f32_16x16x32_f16 v[74:77], v[158:161], v[182:185], v[74:77]
	v_mfma_f32_16x16x32_f16 v[70:73], v[94:97], v[190:193], v[70:73]
	v_mfma_f32_16x16x32_f16 v[66:69], v[158:161], v[190:193], v[66:69]
	v_mfma_f32_16x16x32_f16 v[30:33], v[194:197], v[162:165], v[30:33]
	v_mfma_f32_16x16x32_f16 v[26:29], v[202:205], v[162:165], v[26:29]
	v_mfma_f32_16x16x32_f16 v[22:25], v[194:197], v[170:173], v[22:25]
	v_mfma_f32_16x16x32_f16 v[18:21], v[202:205], v[170:173], v[18:21]
	v_mfma_f32_16x16x32_f16 v[14:17], v[194:197], v[178:181], v[14:17]
	v_mfma_f32_16x16x32_f16 v[10:13], v[202:205], v[178:181], v[10:13]
	v_mfma_f32_16x16x32_f16 v[6:9], v[194:197], v[186:189], v[6:9]
	v_mfma_f32_16x16x32_f16 v[2:5], v[202:205], v[186:189], v[2:5]
	v_mfma_f32_16x16x32_f16 v[30:33], v[198:201], v[166:169], v[30:33]
	v_mfma_f32_16x16x32_f16 v[26:29], v[220:223], v[166:169], v[26:29]
	v_mfma_f32_16x16x32_f16 v[22:25], v[198:201], v[174:177], v[22:25]
	v_mfma_f32_16x16x32_f16 v[18:21], v[220:223], v[174:177], v[18:21]
	v_mfma_f32_16x16x32_f16 v[14:17], v[198:201], v[182:185], v[14:17]
	v_mfma_f32_16x16x32_f16 v[10:13], v[220:223], v[182:185], v[10:13]
	v_mfma_f32_16x16x32_f16 v[6:9], v[198:201], v[190:193], v[6:9]
	v_mfma_f32_16x16x32_f16 v[2:5], v[220:223], v[190:193], v[2:5]
	s_barrier
	s_cbranch_scc0 .LBB0_621
	s_cmpk_gt_u32 s71, 0xff
	s_cbranch_scc1 .Lgx4
	s_barrier

; #define PG8_STAGE(bufoff, gbase, voff) do { _Pragma("unroll") for (int _i = 0; _i < 2; ++_i) \
;         __builtin_amdgcn_global_load_lds((const unsigned*)((const char*)(gbase) + (voff)[_i]), (LAS unsigned*)(lds + (bufoff) + ldsw + _i * 8192), 16, 0, 0); } while (0)
; #define PG8_LDA(dst, b, h) do { _Pragma("unroll") for (int m = 0; m < 4; ++m) _Pragma("unroll") for (int k = 0; k < 2; ++k) dst[m][k] = *(const LAS h16x8*)(lds + PG8_SA(b, h) + aoff + m * 2048 + k * 1024); } while (0)
; #define PG8_LDB(dst, b, h) do { _Pragma("unroll") for (int n = 0; n < 2; ++n) _Pragma("unroll") for (int k = 0; k < 2; ++k) dst[n][k] = *(const LAS h16x8*)(lds + PG8_SB(b, h) + boff + n * 2048 + k * 1024); } while (0)
; #define PG8_MMA(ai, bj, At, Bt_) do { __builtin_amdgcn_s_setprio(1); _Pragma("unroll") for (int m = 0; m < 4; ++m) _Pragma("unroll") for (int n = 0; n < 2; ++n) _Pragma("unroll") for (int k = 0; k < 2; ++k) \
;         acc[ai][bj][m][n] = __builtin_amdgcn_mfma_f32_16x16x32_f16(Bt_[n][k], At[m][k], acc[ai][bj][m][n], 0, 0, 0); __builtin_amdgcn_s_setprio(0); } while (0)
; #define PG8_WAIT_V(n) asm volatile("s_waitcnt vmcnt(" #n ")" ::: "memory")
; #define PG8_WAIT_L(n) asm volatile("s_waitcnt lgkmcnt(" #n ")" ::: "memory")
; #define PG8_BAR __builtin_amdgcn_s_barrier()
; #define PG8_SCHED __builtin_amdgcn_sched_barrier(0)
; template <class Epi, class AMap>
; __device__ __forceinline__ void gemm_phase(LAS unsigned char* lds, const AMap am, const int lda, const h16* Bt, const int ldb, const int M, const int N, const int K, const Epi& E) {
;     ...
;             PG8_LDB(B0, 0, 0); PG8_SCHED; PG8_LDA(At, 0, 0); PG8_STAGE(PG8_SA(1, 1), a1 + hstepA, voffA);
;             PG8_WAIT_L(8); PG8_BAR; PG8_WAIT_L(0); PG8_MMA(0, 0, At, B0); PG8_BAR; PG8_SCHED;
;             PG8_LDB(B1, 0, 1); PG8_STAGE(PG8_SB(0, 0), b2, voffB);
;             PG8_BAR; PG8_WAIT_L(0); PG8_MMA(0, 1, At, B1); PG8_BAR;
;             PG8_LDA(At, 0, 1); PG8_STAGE(PG8_SA(0, 0), a2, voffA);
;             PG8_BAR; PG8_WAIT_L(0); PG8_MMA(1, 0, At, B0); PG8_BAR; PG8_SCHED;
;             PG8_STAGE(PG8_SB(0, 1), b2 + hstepB, voffB);
;             PG8_WAIT_V(6); PG8_BAR; PG8_MMA(1, 1, At, B1); PG8_BAR;
.LBB0_644:
	s_add_i32 s51, s26, 2
	s_add_u32 s0, s22, 0x100
	s_addc_u32 s1, s23, 0
	s_add_i32 s60, 0, 0x10000
	v_add_u32_e32 v234, s60, v203
	ds_read_b128 v[130:133], v234
	ds_read_b128 v[134:137], v234 offset:1024
	ds_read_b128 v[138:141], v234 offset:2048
	ds_read_b128 v[152:155], v234 offset:3072
	s_cmp_eq_u32 s80, s26
	s_cselect_b32 s26, s21, s29
	s_cselect_b32 s49, s47, s1
	s_cselect_b32 s48, s46, s0
	s_cselect_b32 s27, s20, s45
	v_lshl_add_u64 v[232:233], s[22:23], 0, v[148:149]
	s_add_i32 m0, s74, 0xc000
	ds_read_b128 v[156:159], v205
	ds_read_b128 v[160:163], v205 offset:1024
	ds_read_b128 v[164:167], v205 offset:2048
	ds_read_b128 v[168:171], v205 offset:3072
	ds_read_b128 v[172:175], v205 offset:4096
	ds_read_b128 v[176:179], v205 offset:5120
	ds_read_b128 v[180:183], v205 offset:6144
	ds_read_b128 v[184:187], v205 offset:7168
	global_load_lds_dwordx4 v[232:233], off
	v_lshl_add_u64 v[232:233], s[22:23], 0, v[150:151]
	s_add_i32 m0, s74, 0xe000
	s_nop 0
	global_load_lds_dwordx4 v[232:233], off
	s_waitcnt lgkmcnt(11)
	s_add_i32 s62, 0, 0x14000
	v_add_u32_e32 v200, s62, v203
	s_add_i32 s22, s60, s71
	ds_read_b128 v[188:191], v200
	ds_read_b128 v[192:195], v200 offset:1024
	ds_read_b128 v[196:199], v200 offset:2048
	ds_read_b128 v[220:223], v200 offset:3072
	s_waitcnt vmcnt(8) lgkmcnt(0)
	s_barrier
	v_mfma_f32_16x16x32_f16 v[122:125], v[130:133], v[156:159], v[122:125]
	v_mfma_f32_16x16x32_f16 v[126:129], v[138:141], v[156:159], v[126:129]
	v_mfma_f32_16x16x32_f16 v[110:113], v[130:133], v[164:167], v[110:113]
	v_mfma_f32_16x16x32_f16 v[106:109], v[138:141], v[164:167], v[106:109]
	v_mfma_f32_16x16x32_f16 v[94:97], v[130:133], v[172:175], v[94:97]
	v_mfma_f32_16x16x32_f16 v[90:93], v[138:141], v[172:175], v[90:93]
	v_mfma_f32_16x16x32_f16 v[78:81], v[130:133], v[180:183], v[78:81]
	v_mfma_f32_16x16x32_f16 v[74:77], v[138:141], v[180:183], v[74:77]
	v_mfma_f32_16x16x32_f16 v[122:125], v[134:137], v[160:163], v[122:125]
	v_mfma_f32_16x16x32_f16 v[126:129], v[152:155], v[160:163], v[126:129]
	v_mfma_f32_16x16x32_f16 v[110:113], v[134:137], v[168:171], v[110:113]
	v_mfma_f32_16x16x32_f16 v[106:109], v[152:155], v[168:171], v[106:109]
	v_mfma_f32_16x16x32_f16 v[94:97], v[134:137], v[176:179], v[94:97]
	v_mfma_f32_16x16x32_f16 v[90:93], v[152:155], v[176:179], v[90:93]
	v_mfma_f32_16x16x32_f16 v[78:81], v[134:137], v[184:187], v[78:81]
	v_mfma_f32_16x16x32_f16 v[74:77], v[152:155], v[184:187], v[74:77]
	v_mfma_f32_16x16x32_f16 v[118:121], v[188:191], v[156:159], v[118:121]
	v_mfma_f32_16x16x32_f16 v[114:117], v[196:199], v[156:159], v[114:117]
	v_mfma_f32_16x16x32_f16 v[102:105], v[188:191], v[164:167], v[102:105]
	v_mfma_f32_16x16x32_f16 v[98:101], v[196:199], v[164:167], v[98:101]
	v_mfma_f32_16x16x32_f16 v[86:89], v[188:191], v[172:175], v[86:89]
	v_mfma_f32_16x16x32_f16 v[82:85], v[196:199], v[172:175], v[82:85]
	v_mfma_f32_16x16x32_f16 v[70:73], v[188:191], v[180:183], v[70:73]
	v_mfma_f32_16x16x32_f16 v[66:69], v[196:199], v[180:183], v[66:69]
	v_mfma_f32_16x16x32_f16 v[118:121], v[192:195], v[160:163], v[118:121]
	v_mfma_f32_16x16x32_f16 v[114:117], v[220:223], v[160:163], v[114:117]
	v_mfma_f32_16x16x32_f16 v[102:105], v[192:195], v[168:171], v[102:105]
	v_mfma_f32_16x16x32_f16 v[98:101], v[220:223], v[168:171], v[98:101]
	v_mfma_f32_16x16x32_f16 v[86:89], v[192:195], v[176:179], v[86:89]
	v_mfma_f32_16x16x32_f16 v[82:85], v[220:223], v[176:179], v[82:85]
	v_mfma_f32_16x16x32_f16 v[70:73], v[192:195], v[184:187], v[70:73]
	v_mfma_f32_16x16x32_f16 v[66:69], v[220:223], v[184:187], v[66:69]
	s_barrier
	v_lshl_add_u64 v[200:201], s[26:27], 0, v[0:1]
	s_mov_b32 m0, s22
	v_lshl_add_u64 v[206:207], s[26:27], 0, v[146:147]
	global_load_lds_dwordx4 v[200:201], off
	s_add_i32 m0, s22, 0x2000
	s_nop 0
	global_load_lds_dwordx4 v[206:207], off
	s_mov_b32 m0, s74
	v_lshl_add_u64 v[212:213], s[48:49], 0, v[142:143]
	ds_read_b128 v[156:159], v205 offset:16384
	ds_read_b128 v[160:163], v205 offset:17408
	ds_read_b128 v[164:167], v205 offset:18432
	ds_read_b128 v[168:171], v205 offset:19456
	ds_read_b128 v[172:175], v205 offset:20480
	ds_read_b128 v[176:179], v205 offset:21504
	ds_read_b128 v[180:183], v205 offset:22528
	ds_read_b128 v[184:187], v205 offset:23552
	global_load_lds_dwordx4 v[212:213], off
	v_lshl_add_u64 v[224:225], s[48:49], 0, v[144:145]
	s_mov_b32 m0, s75
	s_nop 0
	global_load_lds_dwordx4 v[224:225], off
	s_add_u32 s22, s26, 0x10000
	s_addc_u32 s23, s27, 0
	s_add_i32 s60, s62, s71
	v_lshl_add_u64 v[232:233], s[22:23], 0, v[0:1]
	s_mov_b32 m0, s60
	s_nop 0
	global_load_lds_dwordx4 v[232:233], off
	v_lshl_add_u64 v[232:233], s[22:23], 0, v[146:147]
	s_add_i32 m0, s60, 0x2000
	s_nop 0
	global_load_lds_dwordx4 v[232:233], off
	s_waitcnt vmcnt(8) lgkmcnt(0)
	s_barrier
; #define PG8_STAGE(bufoff, gbase, voff) do { _Pragma("unroll") for (int _i = 0; _i < 2; ++_i) \
;         __builtin_amdgcn_global_load_lds((const unsigned*)((const char*)(gbase) + (voff)[_i]), (LAS unsigned*)(lds + (bufoff) + ldsw + _i * 8192), 16, 0, 0); } while (0)
; #define PG8_LDA(dst, b, h) do { _Pragma("unroll") for (int m = 0; m < 4; ++m) _Pragma("unroll") for (int k = 0; k < 2; ++k) dst[m][k] = *(const LAS h16x8*)(lds + PG8_SA(b, h) + aoff + m * 2048 + k * 1024); } while (0)
; #define PG8_LDB(dst, b, h) do { _Pragma("unroll") for (int n = 0; n < 2; ++n) _Pragma("unroll") for (int k = 0; k < 2; ++k) dst[n][k] = *(const LAS h16x8*)(lds + PG8_SB(b, h) + boff + n * 2048 + k * 1024); } while (0)
; #define PG8_MMA(ai, bj, At, Bt_) do { __builtin_amdgcn_s_setprio(1); _Pragma("unroll") for (int m = 0; m < 4; ++m) _Pragma("unroll") for (int n = 0; n < 2; ++n) _Pragma("unroll") for (int k = 0; k < 2; ++k) \
;         acc[ai][bj][m][n] = __builtin_amdgcn_mfma_f32_16x16x32_f16(Bt_[n][k], At[m][k], acc[ai][bj][m][n], 0, 0, 0); __builtin_amdgcn_s_setprio(0); } while (0)
; #define PG8_WAIT_V(n) asm volatile("s_waitcnt vmcnt(" #n ")" ::: "memory")
; #define PG8_WAIT_L(n) asm volatile("s_waitcnt lgkmcnt(" #n ")" ::: "memory")
; #define PG8_BAR __builtin_amdgcn_s_barrier()
; #define PG8_SCHED __builtin_amdgcn_sched_barrier(0)
; template <class Epi, class AMap>
; __device__ __forceinline__ void gemm_phase(LAS unsigned char* lds, const AMap am, const int lda, const h16* Bt, const int ldb, const int M, const int N, const int K, const Epi& E) {
;     ...
;             PG8_BAR; PG8_WAIT_L(0); PG8_MMA(1, 0, At, B0); PG8_BAR; PG8_SCHED;
;             PG8_STAGE(PG8_SB(0, 1), b2 + hstepB, voffB);
;             PG8_WAIT_V(6); PG8_BAR; PG8_MMA(1, 1, At, B1); PG8_BAR;
;             PG8_LDB(B0, 1, 0); PG8_SCHED; PG8_LDA(At, 1, 0); PG8_STAGE(PG8_SA(0, 1), a2 + hstepA, voffA);
;             PG8_WAIT_L(8); PG8_BAR; PG8_WAIT_L(0); PG8_MMA(0, 0, At, B0); PG8_BAR; PG8_SCHED;
;             PG8_LDB(B1, 1, 1); PG8_STAGE(PG8_SB(1, 0), b3, voffB);
;             PG8_BAR; PG8_WAIT_L(0); PG8_MMA(0, 1, At, B1); PG8_BAR;
;             PG8_LDA(At, 1, 1); PG8_STAGE(PG8_SA(1, 0), a3, voffA);
;             PG8_BAR; PG8_WAIT_L(0); PG8_MMA(1, 0, At, B0); PG8_BAR; PG8_SCHED;
	v_mfma_f32_16x16x32_f16 v[62:65], v[130:133], v[156:159], v[62:65]
	v_mfma_f32_16x16x32_f16 v[58:61], v[138:141], v[156:159], v[58:61]
	v_mfma_f32_16x16x32_f16 v[46:49], v[130:133], v[164:167], v[46:49]
	v_mfma_f32_16x16x32_f16 v[42:45], v[138:141], v[164:167], v[42:45]
	v_mfma_f32_16x16x32_f16 v[30:33], v[130:133], v[172:175], v[30:33]
	v_mfma_f32_16x16x32_f16 v[26:29], v[138:141], v[172:175], v[26:29]
	v_mfma_f32_16x16x32_f16 v[14:17], v[130:133], v[180:183], v[14:17]
	v_mfma_f32_16x16x32_f16 v[10:13], v[138:141], v[180:183], v[10:13]
	v_mfma_f32_16x16x32_f16 v[62:65], v[134:137], v[160:163], v[62:65]
	v_mfma_f32_16x16x32_f16 v[58:61], v[152:155], v[160:163], v[58:61]
	v_mfma_f32_16x16x32_f16 v[46:49], v[134:137], v[168:171], v[46:49]
	v_mfma_f32_16x16x32_f16 v[42:45], v[152:155], v[168:171], v[42:45]
	v_mfma_f32_16x16x32_f16 v[30:33], v[134:137], v[176:179], v[30:33]
	v_mfma_f32_16x16x32_f16 v[26:29], v[152:155], v[176:179], v[26:29]
	v_mfma_f32_16x16x32_f16 v[14:17], v[134:137], v[184:187], v[14:17]
	v_mfma_f32_16x16x32_f16 v[10:13], v[152:155], v[184:187], v[10:13]
	v_mfma_f32_16x16x32_f16 v[54:57], v[188:191], v[156:159], v[54:57]
	v_mfma_f32_16x16x32_f16 v[50:53], v[196:199], v[156:159], v[50:53]
	v_mfma_f32_16x16x32_f16 v[38:41], v[188:191], v[164:167], v[38:41]
	v_mfma_f32_16x16x32_f16 v[34:37], v[196:199], v[164:167], v[34:37]
	v_mfma_f32_16x16x32_f16 v[22:25], v[188:191], v[172:175], v[22:25]
	v_mfma_f32_16x16x32_f16 v[18:21], v[196:199], v[172:175], v[18:21]
	v_mfma_f32_16x16x32_f16 v[6:9], v[188:191], v[180:183], v[6:9]
	v_mfma_f32_16x16x32_f16 v[2:5], v[196:199], v[180:183], v[2:5]
	v_mfma_f32_16x16x32_f16 v[54:57], v[192:195], v[160:163], v[54:57]
	v_mfma_f32_16x16x32_f16 v[50:53], v[220:223], v[160:163], v[50:53]
	v_mfma_f32_16x16x32_f16 v[38:41], v[192:195], v[168:171], v[38:41]
	v_mfma_f32_16x16x32_f16 v[34:37], v[220:223], v[168:171], v[34:37]
	v_mfma_f32_16x16x32_f16 v[22:25], v[192:195], v[176:179], v[22:25]
	v_mfma_f32_16x16x32_f16 v[18:21], v[220:223], v[176:179], v[18:21]
	v_mfma_f32_16x16x32_f16 v[6:9], v[192:195], v[184:187], v[6:9]
	v_mfma_f32_16x16x32_f16 v[2:5], v[220:223], v[184:187], v[2:5]
	s_barrier
	s_add_i32 s60, 0, 0x18000
	v_add_u32_e32 v234, s60, v203
	ds_read_b128 v[130:133], v234
	ds_read_b128 v[134:137], v234 offset:1024
	ds_read_b128 v[138:141], v234 offset:2048
	ds_read_b128 v[152:155], v234 offset:3072
	s_add_u32 s22, s48, 0x1c0000
	s_addc_u32 s23, s49, 0
	s_mov_b32 m0, s76
	v_lshl_add_u64 v[232:233], s[22:23], 0, v[142:143]
	ds_read_b128 v[156:159], v205 offset:32768
	ds_read_b128 v[160:163], v205 offset:33792
	ds_read_b128 v[164:167], v205 offset:34816
	ds_read_b128 v[168:171], v205 offset:35840
	ds_read_b128 v[172:175], v205 offset:36864
	ds_read_b128 v[176:179], v205 offset:37888
	ds_read_b128 v[180:183], v205 offset:38912
	ds_read_b128 v[184:187], v205 offset:39936
	global_load_lds_dwordx4 v[232:233], off
	v_lshl_add_u64 v[232:233], s[22:23], 0, v[144:145]
	s_mov_b32 m0, s77
	s_nop 0
	global_load_lds_dwordx4 v[232:233], off
	s_waitcnt lgkmcnt(11)
	s_add_i32 s48, 0, 0x1c000
	s_add_i32 s22, s60, s71
	v_add_u32_e32 v214, s48, v203
	v_lshl_add_u64 v[200:201], v[200:201], 0, s[92:93]
	s_mov_b32 m0, s22
	ds_read_b128 v[188:191], v214
	ds_read_b128 v[192:195], v214 offset:1024
	ds_read_b128 v[196:199], v214 offset:2048
	ds_read_b128 v[220:223], v214 offset:3072
	s_waitcnt vmcnt(8) lgkmcnt(0)
	s_barrier
	v_mfma_f32_16x16x32_f16 v[122:125], v[130:133], v[156:159], v[122:125]
	v_mfma_f32_16x16x32_f16 v[126:129], v[138:141], v[156:159], v[126:129]
	v_mfma_f32_16x16x32_f16 v[110:113], v[130:133], v[164:167], v[110:113]
	v_mfma_f32_16x16x32_f16 v[106:109], v[138:141], v[164:167], v[106:109]
	v_mfma_f32_16x16x32_f16 v[94:97], v[130:133], v[172:175], v[94:97]
	v_mfma_f32_16x16x32_f16 v[90:93], v[138:141], v[172:175], v[90:93]
	v_mfma_f32_16x16x32_f16 v[78:81], v[130:133], v[180:183], v[78:81]
	v_mfma_f32_16x16x32_f16 v[74:77], v[138:141], v[180:183], v[74:77]
	v_mfma_f32_16x16x32_f16 v[122:125], v[134:137], v[160:163], v[122:125]
	v_mfma_f32_16x16x32_f16 v[126:129], v[152:155], v[160:163], v[126:129]
	v_mfma_f32_16x16x32_f16 v[110:113], v[134:137], v[168:171], v[110:113]
	v_mfma_f32_16x16x32_f16 v[106:109], v[152:155], v[168:171], v[106:109]
	v_mfma_f32_16x16x32_f16 v[94:97], v[134:137], v[176:179], v[94:97]
	v_mfma_f32_16x16x32_f16 v[90:93], v[152:155], v[176:179], v[90:93]
	v_mfma_f32_16x16x32_f16 v[78:81], v[134:137], v[184:187], v[78:81]
	v_mfma_f32_16x16x32_f16 v[74:77], v[152:155], v[184:187], v[74:77]
	v_mfma_f32_16x16x32_f16 v[118:121], v[188:191], v[156:159], v[118:121]
	v_mfma_f32_16x16x32_f16 v[114:117], v[196:199], v[156:159], v[114:117]
	v_mfma_f32_16x16x32_f16 v[102:105], v[188:191], v[164:167], v[102:105]
	v_mfma_f32_16x16x32_f16 v[98:101], v[196:199], v[164:167], v[98:101]
	v_mfma_f32_16x16x32_f16 v[86:89], v[188:191], v[172:175], v[86:89]
	v_mfma_f32_16x16x32_f16 v[82:85], v[196:199], v[172:175], v[82:85]
	v_mfma_f32_16x16x32_f16 v[70:73], v[188:191], v[180:183], v[70:73]
	v_mfma_f32_16x16x32_f16 v[66:69], v[196:199], v[180:183], v[66:69]
	v_mfma_f32_16x16x32_f16 v[118:121], v[192:195], v[160:163], v[118:121]
	v_mfma_f32_16x16x32_f16 v[114:117], v[220:223], v[160:163], v[114:117]
	v_mfma_f32_16x16x32_f16 v[102:105], v[192:195], v[168:171], v[102:105]
	v_mfma_f32_16x16x32_f16 v[98:101], v[220:223], v[168:171], v[98:101]
	v_mfma_f32_16x16x32_f16 v[86:89], v[192:195], v[176:179], v[86:89]
	v_mfma_f32_16x16x32_f16 v[82:85], v[220:223], v[176:179], v[82:85]
	v_mfma_f32_16x16x32_f16 v[70:73], v[192:195], v[184:187], v[70:73]
	v_mfma_f32_16x16x32_f16 v[66:69], v[220:223], v[184:187], v[66:69]
	s_barrier
; #define PG8_STAGE(bufoff, gbase, voff) do { _Pragma("unroll") for (int _i = 0; _i < 2; ++_i) \
;         __builtin_amdgcn_global_load_lds((const unsigned*)((const char*)(gbase) + (voff)[_i]), (LAS unsigned*)(lds + (bufoff) + ldsw + _i * 8192), 16, 0, 0); } while (0)
; #define PG8_LDA(dst, b, h) do { _Pragma("unroll") for (int m = 0; m < 4; ++m) _Pragma("unroll") for (int k = 0; k < 2; ++k) dst[m][k] = *(const LAS h16x8*)(lds + PG8_SA(b, h) + aoff + m * 2048 + k * 1024); } while (0)
; #define PG8_LDB(dst, b, h) do { _Pragma("unroll") for (int n = 0; n < 2; ++n) _Pragma("unroll") for (int k = 0; k < 2; ++k) dst[n][k] = *(const LAS h16x8*)(lds + PG8_SB(b, h) + boff + n * 2048 + k * 1024); } while (0)
; #define PG8_MMA(ai, bj, At, Bt_) do { __builtin_amdgcn_s_setprio(1); _Pragma("unroll") for (int m = 0; m < 4; ++m) _Pragma("unroll") for (int n = 0; n < 2; ++n) _Pragma("unroll") for (int k = 0; k < 2; ++k) \
;         acc[ai][bj][m][n] = __builtin_amdgcn_mfma_f32_16x16x32_f16(Bt_[n][k], At[m][k], acc[ai][bj][m][n], 0, 0, 0); __builtin_amdgcn_s_setprio(0); } while (0)
; #define PG8_WAIT_V(n) asm volatile("s_waitcnt vmcnt(" #n ")" ::: "memory")
; #define PG8_WAIT_L(n) asm volatile("s_waitcnt lgkmcnt(" #n ")" ::: "memory")
; #define PG8_BAR __builtin_amdgcn_s_barrier()
; #define PG8_SCHED __builtin_amdgcn_sched_barrier(0)
; template <class Epi, class AMap>
; __device__ __forceinline__ void gemm_phase(LAS unsigned char* lds, const AMap am, const int lda, const h16* Bt, const int ldb, const int M, const int N, const int K, const Epi& E) {
;     ...
;             PG8_LDB(B0, 1, 0); PG8_SCHED; PG8_LDA(At, 1, 0); PG8_STAGE(PG8_SA(0, 1), a2 + hstepA, voffA);
;             PG8_WAIT_L(8); PG8_BAR; PG8_WAIT_L(0); PG8_MMA(0, 0, At, B0); PG8_BAR; PG8_SCHED;
;             PG8_LDB(B1, 1, 1); PG8_STAGE(PG8_SB(1, 0), b3, voffB);
;             PG8_BAR; PG8_WAIT_L(0); PG8_MMA(0, 1, At, B1); PG8_BAR;
;             PG8_LDA(At, 1, 1); PG8_STAGE(PG8_SA(1, 0), a3, voffA);
;             PG8_BAR; PG8_WAIT_L(0); PG8_MMA(1, 0, At, B0); PG8_BAR; PG8_SCHED;
;             PG8_STAGE(PG8_SB(1, 1), b3 + hstepB, voffB);
;             PG8_WAIT_V(6); PG8_BAR; PG8_MMA(1, 1, At, B1); PG8_BAR;
;         }
	global_load_lds_dwordx4 v[200:201], off
	v_lshl_add_u64 v[200:201], v[206:207], 0, s[92:93]
	s_add_i32 m0, s22, 0x2000
	s_nop 0
	global_load_lds_dwordx4 v[200:201], off
	s_mov_b32 m0, s78
	v_lshl_add_u64 v[200:201], v[212:213], 0, s[92:93]
	ds_read_b128 v[156:159], v205 offset:49152
	ds_read_b128 v[160:163], v205 offset:50176
	ds_read_b128 v[164:167], v205 offset:51200
	ds_read_b128 v[168:171], v205 offset:52224
	ds_read_b128 v[172:175], v205 offset:53248
	ds_read_b128 v[176:179], v205 offset:54272
	ds_read_b128 v[180:183], v205 offset:55296
	ds_read_b128 v[184:187], v205 offset:56320
	global_load_lds_dwordx4 v[200:201], off
	v_lshl_add_u64 v[200:201], v[224:225], 0, s[92:93]
	s_mov_b32 m0, s79
	s_nop 0
	global_load_lds_dwordx4 v[200:201], off
	s_add_u32 s22, s26, 0x10080
	s_addc_u32 s23, s27, 0
	s_add_i32 s26, s48, s71
	v_lshl_add_u64 v[232:233], s[22:23], 0, v[0:1]
	s_mov_b32 m0, s26
	s_nop 0
	global_load_lds_dwordx4 v[232:233], off
	v_lshl_add_u64 v[232:233], s[22:23], 0, v[146:147]
	s_add_i32 m0, s26, 0x2000
	s_nop 0
	global_load_lds_dwordx4 v[232:233], off
	s_add_u32 s29, s29, 0x100
	s_addc_u32 s45, s45, 0
	s_cmp_ge_i32 s51, s24
	s_mov_b64 s[22:23], s[0:1]
	s_mov_b32 s26, s51
	s_waitcnt vmcnt(8) lgkmcnt(0)
	s_barrier
	v_mfma_f32_16x16x32_f16 v[62:65], v[130:133], v[156:159], v[62:65]
	v_mfma_f32_16x16x32_f16 v[58:61], v[138:141], v[156:159], v[58:61]
	v_mfma_f32_16x16x32_f16 v[46:49], v[130:133], v[164:167], v[46:49]
	v_mfma_f32_16x16x32_f16 v[42:45], v[138:141], v[164:167], v[42:45]
	v_mfma_f32_16x16x32_f16 v[30:33], v[130:133], v[172:175], v[30:33]
	v_mfma_f32_16x16x32_f16 v[26:29], v[138:141], v[172:175], v[26:29]
	v_mfma_f32_16x16x32_f16 v[14:17], v[130:133], v[180:183], v[14:17]
	v_mfma_f32_16x16x32_f16 v[10:13], v[138:141], v[180:183], v[10:13]
	v_mfma_f32_16x16x32_f16 v[62:65], v[134:137], v[160:163], v[62:65]
	v_mfma_f32_16x16x32_f16 v[58:61], v[152:155], v[160:163], v[58:61]
	v_mfma_f32_16x16x32_f16 v[46:49], v[134:137], v[168:171], v[46:49]
	v_mfma_f32_16x16x32_f16 v[42:45], v[152:155], v[168:171], v[42:45]
	v_mfma_f32_16x16x32_f16 v[30:33], v[134:137], v[176:179], v[30:33]
	v_mfma_f32_16x16x32_f16 v[26:29], v[152:155], v[176:179], v[26:29]
	v_mfma_f32_16x16x32_f16 v[14:17], v[134:137], v[184:187], v[14:17]
	v_mfma_f32_16x16x32_f16 v[10:13], v[152:155], v[184:187], v[10:13]
	v_mfma_f32_16x16x32_f16 v[54:57], v[188:191], v[156:159], v[54:57]
	v_mfma_f32_16x16x32_f16 v[50:53], v[196:199], v[156:159], v[50:53]
	v_mfma_f32_16x16x32_f16 v[38:41], v[188:191], v[164:167], v[38:41]
	v_mfma_f32_16x16x32_f16 v[34:37], v[196:199], v[164:167], v[34:37]
	v_mfma_f32_16x16x32_f16 v[22:25], v[188:191], v[172:175], v[22:25]
	v_mfma_f32_16x16x32_f16 v[18:21], v[196:199], v[172:175], v[18:21]
	v_mfma_f32_16x16x32_f16 v[6:9], v[188:191], v[180:183], v[6:9]
	v_mfma_f32_16x16x32_f16 v[2:5], v[196:199], v[180:183], v[2:5]
	v_mfma_f32_16x16x32_f16 v[54:57], v[192:195], v[160:163], v[54:57]
	v_mfma_f32_16x16x32_f16 v[50:53], v[220:223], v[160:163], v[50:53]
	v_mfma_f32_16x16x32_f16 v[38:41], v[192:195], v[168:171], v[38:41]
	v_mfma_f32_16x16x32_f16 v[34:37], v[220:223], v[168:171], v[34:37]
	v_mfma_f32_16x16x32_f16 v[22:25], v[192:195], v[176:179], v[22:25]
	v_mfma_f32_16x16x32_f16 v[18:21], v[220:223], v[176:179], v[18:21]
	v_mfma_f32_16x16x32_f16 v[6:9], v[192:195], v[184:187], v[6:9]
	v_mfma_f32_16x16x32_f16 v[2:5], v[220:223], v[184:187], v[2:5]
	s_barrier
	s_cbranch_scc0 .LBB0_644
	s_cmpk_gt_u32 s69, 0xff
	s_cbranch_scc1 .Lgx5
	s_barrier

; #define PG8_STAGE(bufoff, gbase, voff) do { _Pragma("unroll") for (int _i = 0; _i < 2; ++_i) \
;         __builtin_amdgcn_global_load_lds((const unsigned*)((const char*)(gbase) + (voff)[_i]), (LAS unsigned*)(lds + (bufoff) + ldsw + _i * 8192), 16, 0, 0); } while (0)
; #define PG8_LDA(dst, b, h) do { _Pragma("unroll") for (int m = 0; m < 4; ++m) _Pragma("unroll") for (int k = 0; k < 2; ++k) dst[m][k] = *(const LAS h16x8*)(lds + PG8_SA(b, h) + aoff + m * 2048 + k * 1024); } while (0)
; #define PG8_LDB(dst, b, h) do { _Pragma("unroll") for (int n = 0; n < 2; ++n) _Pragma("unroll") for (int k = 0; k < 2; ++k) dst[n][k] = *(const LAS h16x8*)(lds + PG8_SB(b, h) + boff + n * 2048 + k * 1024); } while (0)
; #define PG8_MMA(ai, bj, At, Bt_) do { __builtin_amdgcn_s_setprio(1); _Pragma("unroll") for (int m = 0; m < 4; ++m) _Pragma("unroll") for (int n = 0; n < 2; ++n) _Pragma("unroll") for (int k = 0; k < 2; ++k) \
;         acc[ai][bj][m][n] = __builtin_amdgcn_mfma_f32_16x16x32_f16(Bt_[n][k], At[m][k], acc[ai][bj][m][n], 0, 0, 0); __builtin_amdgcn_s_setprio(0); } while (0)
; #define PG8_WAIT_V(n) asm volatile("s_waitcnt vmcnt(" #n ")" ::: "memory")
; #define PG8_WAIT_L(n) asm volatile("s_waitcnt lgkmcnt(" #n ")" ::: "memory")
; #define PG8_BAR __builtin_amdgcn_s_barrier()
; #define PG8_SCHED __builtin_amdgcn_sched_barrier(0)
; template <class Epi, class AMap>
; __device__ __forceinline__ void gemm_phase(LAS unsigned char* lds, const AMap am, const int lda, const h16* Bt, const int ldb, const int M, const int N, const int K, const Epi& E) {
;     ...
;             PG8_LDB(B0, 0, 0); PG8_SCHED; PG8_LDA(At, 0, 0); PG8_STAGE(PG8_SA(1, 1), a1 + hstepA, voffA);
;             PG8_WAIT_L(8); PG8_BAR; PG8_WAIT_L(0); PG8_MMA(0, 0, At, B0); PG8_BAR; PG8_SCHED;
;             PG8_LDB(B1, 0, 1); PG8_STAGE(PG8_SB(0, 0), b2, voffB);
;             PG8_BAR; PG8_WAIT_L(0); PG8_MMA(0, 1, At, B1); PG8_BAR;
;             PG8_LDA(At, 0, 1); PG8_STAGE(PG8_SA(0, 0), a2, voffA);
;             PG8_BAR; PG8_WAIT_L(0); PG8_MMA(1, 0, At, B0); PG8_BAR; PG8_SCHED;
;             PG8_STAGE(PG8_SB(0, 1), b2 + hstepB, voffB);
;             PG8_WAIT_V(6); PG8_BAR; PG8_MMA(1, 1, At, B1); PG8_BAR;
.LBB0_692:
	s_add_i32 s51, s26, 2
	s_add_u32 s0, s22, 0x100
	s_addc_u32 s1, s23, 0
	s_add_i32 s60, 0, 0x10000
	v_add_u32_e32 v234, s60, v175
	ds_read_b128 v[82:85], v234
	ds_read_b128 v[86:89], v234 offset:1024
	ds_read_b128 v[138:141], v234 offset:2048
	ds_read_b128 v[142:145], v234 offset:3072
	s_cmp_eq_u32 s61, s26
	s_cselect_b32 s26, s21, s29
	s_cselect_b32 s49, s47, s1
	s_cselect_b32 s48, s46, s0
	s_cselect_b32 s27, s20, s45
	v_lshl_add_u64 v[172:173], s[22:23], 0, v[152:153]
	s_add_i32 m0, s74, 0xc000
	ds_read_b128 v[156:159], v177
	ds_read_b128 v[160:163], v177 offset:1024
	ds_read_b128 v[164:167], v177 offset:2048
	ds_read_b128 v[168:171], v177 offset:3072
	ds_read_b128 v[178:181], v177 offset:4096
	ds_read_b128 v[182:185], v177 offset:5120
	ds_read_b128 v[186:189], v177 offset:6144
	ds_read_b128 v[190:193], v177 offset:7168
	global_load_lds_dwordx4 v[172:173], off
	v_lshl_add_u64 v[172:173], s[22:23], 0, v[154:155]
	s_add_i32 m0, s74, 0xe000
	s_nop 0
	global_load_lds_dwordx4 v[172:173], off
	s_waitcnt lgkmcnt(11)
	s_add_i32 s62, 0, 0x14000
	v_add_u32_e32 v172, s62, v175
	s_add_i32 s22, s60, s71
	ds_read_b128 v[194:197], v172
	ds_read_b128 v[198:201], v172 offset:1024
	ds_read_b128 v[202:205], v172 offset:2048
	ds_read_b128 v[220:223], v172 offset:3072
	s_waitcnt vmcnt(8) lgkmcnt(0)
	s_barrier
	v_mfma_f32_16x16x32_f16 v[134:137], v[82:85], v[156:159], v[134:137]
	v_mfma_f32_16x16x32_f16 v[130:133], v[138:141], v[156:159], v[130:133]
	v_mfma_f32_16x16x32_f16 v[126:129], v[82:85], v[164:167], v[126:129]
	v_mfma_f32_16x16x32_f16 v[122:125], v[138:141], v[164:167], v[122:125]
	v_mfma_f32_16x16x32_f16 v[118:121], v[82:85], v[178:181], v[118:121]
	v_mfma_f32_16x16x32_f16 v[114:117], v[138:141], v[178:181], v[114:117]
	v_mfma_f32_16x16x32_f16 v[110:113], v[82:85], v[186:189], v[110:113]
	v_mfma_f32_16x16x32_f16 v[106:109], v[138:141], v[186:189], v[106:109]
	v_mfma_f32_16x16x32_f16 v[134:137], v[86:89], v[160:163], v[134:137]
	v_mfma_f32_16x16x32_f16 v[130:133], v[142:145], v[160:163], v[130:133]
	v_mfma_f32_16x16x32_f16 v[126:129], v[86:89], v[168:171], v[126:129]
	v_mfma_f32_16x16x32_f16 v[122:125], v[142:145], v[168:171], v[122:125]
	v_mfma_f32_16x16x32_f16 v[118:121], v[86:89], v[182:185], v[118:121]
	v_mfma_f32_16x16x32_f16 v[114:117], v[142:145], v[182:185], v[114:117]
	v_mfma_f32_16x16x32_f16 v[110:113], v[86:89], v[190:193], v[110:113]
	v_mfma_f32_16x16x32_f16 v[106:109], v[142:145], v[190:193], v[106:109]
	v_mfma_f32_16x16x32_f16 v[62:65], v[194:197], v[156:159], v[62:65]
	v_mfma_f32_16x16x32_f16 v[58:61], v[202:205], v[156:159], v[58:61]
	v_mfma_f32_16x16x32_f16 v[54:57], v[194:197], v[164:167], v[54:57]
	v_mfma_f32_16x16x32_f16 v[50:53], v[202:205], v[164:167], v[50:53]
	v_mfma_f32_16x16x32_f16 v[46:49], v[194:197], v[178:181], v[46:49]
	v_mfma_f32_16x16x32_f16 v[42:45], v[202:205], v[178:181], v[42:45]
	v_mfma_f32_16x16x32_f16 v[38:41], v[194:197], v[186:189], v[38:41]
	v_mfma_f32_16x16x32_f16 v[34:37], v[202:205], v[186:189], v[34:37]
	v_mfma_f32_16x16x32_f16 v[62:65], v[198:201], v[160:163], v[62:65]
	v_mfma_f32_16x16x32_f16 v[58:61], v[220:223], v[160:163], v[58:61]
	v_mfma_f32_16x16x32_f16 v[54:57], v[198:201], v[168:171], v[54:57]
	v_mfma_f32_16x16x32_f16 v[50:53], v[220:223], v[168:171], v[50:53]
	v_mfma_f32_16x16x32_f16 v[46:49], v[198:201], v[182:185], v[46:49]
	v_mfma_f32_16x16x32_f16 v[42:45], v[220:223], v[182:185], v[42:45]
	v_mfma_f32_16x16x32_f16 v[38:41], v[198:201], v[190:193], v[38:41]
	v_mfma_f32_16x16x32_f16 v[34:37], v[220:223], v[190:193], v[34:37]
	s_barrier
	v_lshl_add_u64 v[172:173], s[26:27], 0, v[0:1]
	s_mov_b32 m0, s22
	v_lshl_add_u64 v[206:207], s[26:27], 0, v[150:151]
	global_load_lds_dwordx4 v[172:173], off
	s_add_i32 m0, s22, 0x2000
	s_nop 0
	global_load_lds_dwordx4 v[206:207], off
	s_mov_b32 m0, s74
	v_lshl_add_u64 v[212:213], s[48:49], 0, v[146:147]
	ds_read_b128 v[156:159], v177 offset:16384
	ds_read_b128 v[160:163], v177 offset:17408
	ds_read_b128 v[164:167], v177 offset:18432
	ds_read_b128 v[168:171], v177 offset:19456
	ds_read_b128 v[178:181], v177 offset:20480
	ds_read_b128 v[182:185], v177 offset:21504
	ds_read_b128 v[186:189], v177 offset:22528
	ds_read_b128 v[190:193], v177 offset:23552
	global_load_lds_dwordx4 v[212:213], off
	v_lshl_add_u64 v[224:225], s[48:49], 0, v[148:149]
	s_mov_b32 m0, s75
	s_nop 0
	global_load_lds_dwordx4 v[224:225], off
	s_add_u32 s22, s26, 0x10000
	s_addc_u32 s23, s27, 0
	s_add_i32 s60, s62, s71
	v_lshl_add_u64 v[232:233], s[22:23], 0, v[0:1]
	s_mov_b32 m0, s60
	s_nop 0
	global_load_lds_dwordx4 v[232:233], off
	v_lshl_add_u64 v[232:233], s[22:23], 0, v[150:151]
	s_add_i32 m0, s60, 0x2000
	s_nop 0
	global_load_lds_dwordx4 v[232:233], off
	s_waitcnt vmcnt(8) lgkmcnt(0)
	s_barrier
; #define PG8_STAGE(bufoff, gbase, voff) do { _Pragma("unroll") for (int _i = 0; _i < 2; ++_i) \
;         __builtin_amdgcn_global_load_lds((const unsigned*)((const char*)(gbase) + (voff)[_i]), (LAS unsigned*)(lds + (bufoff) + ldsw + _i * 8192), 16, 0, 0); } while (0)
; #define PG8_LDA(dst, b, h) do { _Pragma("unroll") for (int m = 0; m < 4; ++m) _Pragma("unroll") for (int k = 0; k < 2; ++k) dst[m][k] = *(const LAS h16x8*)(lds + PG8_SA(b, h) + aoff + m * 2048 + k * 1024); } while (0)
; #define PG8_LDB(dst, b, h) do { _Pragma("unroll") for (int n = 0; n < 2; ++n) _Pragma("unroll") for (int k = 0; k < 2; ++k) dst[n][k] = *(const LAS h16x8*)(lds + PG8_SB(b, h) + boff + n * 2048 + k * 1024); } while (0)
; #define PG8_MMA(ai, bj, At, Bt_) do { __builtin_amdgcn_s_setprio(1); _Pragma("unroll") for (int m = 0; m < 4; ++m) _Pragma("unroll") for (int n = 0; n < 2; ++n) _Pragma("unroll") for (int k = 0; k < 2; ++k) \
;         acc[ai][bj][m][n] = __builtin_amdgcn_mfma_f32_16x16x32_f16(Bt_[n][k], At[m][k], acc[ai][bj][m][n], 0, 0, 0); __builtin_amdgcn_s_setprio(0); } while (0)
; #define PG8_WAIT_V(n) asm volatile("s_waitcnt vmcnt(" #n ")" ::: "memory")
; #define PG8_WAIT_L(n) asm volatile("s_waitcnt lgkmcnt(" #n ")" ::: "memory")
; #define PG8_BAR __builtin_amdgcn_s_barrier()
; #define PG8_SCHED __builtin_amdgcn_sched_barrier(0)
; template <class Epi, class AMap>
; __device__ __forceinline__ void gemm_phase(LAS unsigned char* lds, const AMap am, const int lda, const h16* Bt, const int ldb, const int M, const int N, const int K, const Epi& E) {
;     ...
;             PG8_BAR; PG8_WAIT_L(0); PG8_MMA(1, 0, At, B0); PG8_BAR; PG8_SCHED;
;             PG8_STAGE(PG8_SB(0, 1), b2 + hstepB, voffB);
;             PG8_WAIT_V(6); PG8_BAR; PG8_MMA(1, 1, At, B1); PG8_BAR;
;             PG8_LDB(B0, 1, 0); PG8_SCHED; PG8_LDA(At, 1, 0); PG8_STAGE(PG8_SA(0, 1), a2 + hstepA, voffA);
;             PG8_WAIT_L(8); PG8_BAR; PG8_WAIT_L(0); PG8_MMA(0, 0, At, B0); PG8_BAR; PG8_SCHED;
;             PG8_LDB(B1, 1, 1); PG8_STAGE(PG8_SB(1, 0), b3, voffB);
;             PG8_BAR; PG8_WAIT_L(0); PG8_MMA(0, 1, At, B1); PG8_BAR;
;             PG8_LDA(At, 1, 1); PG8_STAGE(PG8_SA(1, 0), a3, voffA);
;             PG8_BAR; PG8_WAIT_L(0); PG8_MMA(1, 0, At, B0); PG8_BAR; PG8_SCHED;
	v_mfma_f32_16x16x32_f16 v[102:105], v[82:85], v[156:159], v[102:105]
	v_mfma_f32_16x16x32_f16 v[98:101], v[138:141], v[156:159], v[98:101]
	v_mfma_f32_16x16x32_f16 v[94:97], v[82:85], v[164:167], v[94:97]
	v_mfma_f32_16x16x32_f16 v[90:93], v[138:141], v[164:167], v[90:93]
	v_mfma_f32_16x16x32_f16 v[78:81], v[82:85], v[178:181], v[78:81]
	v_mfma_f32_16x16x32_f16 v[74:77], v[138:141], v[178:181], v[74:77]
	v_mfma_f32_16x16x32_f16 v[70:73], v[82:85], v[186:189], v[70:73]
	v_mfma_f32_16x16x32_f16 v[66:69], v[138:141], v[186:189], v[66:69]
	v_mfma_f32_16x16x32_f16 v[102:105], v[86:89], v[160:163], v[102:105]
	v_mfma_f32_16x16x32_f16 v[98:101], v[142:145], v[160:163], v[98:101]
	v_mfma_f32_16x16x32_f16 v[94:97], v[86:89], v[168:171], v[94:97]
	v_mfma_f32_16x16x32_f16 v[90:93], v[142:145], v[168:171], v[90:93]
	v_mfma_f32_16x16x32_f16 v[78:81], v[86:89], v[182:185], v[78:81]
	v_mfma_f32_16x16x32_f16 v[74:77], v[142:145], v[182:185], v[74:77]
	v_mfma_f32_16x16x32_f16 v[70:73], v[86:89], v[190:193], v[70:73]
	v_mfma_f32_16x16x32_f16 v[66:69], v[142:145], v[190:193], v[66:69]
	v_mfma_f32_16x16x32_f16 v[30:33], v[194:197], v[156:159], v[30:33]
	v_mfma_f32_16x16x32_f16 v[26:29], v[202:205], v[156:159], v[26:29]
	v_mfma_f32_16x16x32_f16 v[22:25], v[194:197], v[164:167], v[22:25]
	v_mfma_f32_16x16x32_f16 v[18:21], v[202:205], v[164:167], v[18:21]
	v_mfma_f32_16x16x32_f16 v[14:17], v[194:197], v[178:181], v[14:17]
	v_mfma_f32_16x16x32_f16 v[10:13], v[202:205], v[178:181], v[10:13]
	v_mfma_f32_16x16x32_f16 v[6:9], v[194:197], v[186:189], v[6:9]
	v_mfma_f32_16x16x32_f16 v[2:5], v[202:205], v[186:189], v[2:5]
	v_mfma_f32_16x16x32_f16 v[30:33], v[198:201], v[160:163], v[30:33]
	v_mfma_f32_16x16x32_f16 v[26:29], v[220:223], v[160:163], v[26:29]
	v_mfma_f32_16x16x32_f16 v[22:25], v[198:201], v[168:171], v[22:25]
	v_mfma_f32_16x16x32_f16 v[18:21], v[220:223], v[168:171], v[18:21]
	v_mfma_f32_16x16x32_f16 v[14:17], v[198:201], v[182:185], v[14:17]
	v_mfma_f32_16x16x32_f16 v[10:13], v[220:223], v[182:185], v[10:13]
	v_mfma_f32_16x16x32_f16 v[6:9], v[198:201], v[190:193], v[6:9]
	v_mfma_f32_16x16x32_f16 v[2:5], v[220:223], v[190:193], v[2:5]
	s_barrier
	s_add_i32 s60, 0, 0x18000
	v_add_u32_e32 v234, s60, v175
	ds_read_b128 v[82:85], v234
	ds_read_b128 v[86:89], v234 offset:1024
	ds_read_b128 v[138:141], v234 offset:2048
	ds_read_b128 v[142:145], v234 offset:3072
	s_add_u32 s22, s48, 0x1c0000
	s_addc_u32 s23, s49, 0
	s_mov_b32 m0, s76
	v_lshl_add_u64 v[232:233], s[22:23], 0, v[146:147]
	ds_read_b128 v[156:159], v177 offset:32768
	ds_read_b128 v[160:163], v177 offset:33792
	ds_read_b128 v[164:167], v177 offset:34816
	ds_read_b128 v[168:171], v177 offset:35840
	ds_read_b128 v[178:181], v177 offset:36864
	ds_read_b128 v[182:185], v177 offset:37888
	ds_read_b128 v[186:189], v177 offset:38912
	ds_read_b128 v[190:193], v177 offset:39936
	global_load_lds_dwordx4 v[232:233], off
	v_lshl_add_u64 v[232:233], s[22:23], 0, v[148:149]
	s_mov_b32 m0, s77
	s_nop 0
	global_load_lds_dwordx4 v[232:233], off
	s_waitcnt lgkmcnt(11)
	s_add_i32 s48, 0, 0x1c000
	s_add_i32 s22, s60, s71
	v_add_u32_e32 v214, s48, v175
	v_lshl_add_u64 v[172:173], v[172:173], 0, s[92:93]
	s_mov_b32 m0, s22
	ds_read_b128 v[194:197], v214
	ds_read_b128 v[198:201], v214 offset:1024
	ds_read_b128 v[202:205], v214 offset:2048
	ds_read_b128 v[220:223], v214 offset:3072
	s_waitcnt vmcnt(8) lgkmcnt(0)
	s_barrier
	v_mfma_f32_16x16x32_f16 v[134:137], v[82:85], v[156:159], v[134:137]
	v_mfma_f32_16x16x32_f16 v[130:133], v[138:141], v[156:159], v[130:133]
	v_mfma_f32_16x16x32_f16 v[126:129], v[82:85], v[164:167], v[126:129]
	v_mfma_f32_16x16x32_f16 v[122:125], v[138:141], v[164:167], v[122:125]
	v_mfma_f32_16x16x32_f16 v[118:121], v[82:85], v[178:181], v[118:121]
	v_mfma_f32_16x16x32_f16 v[114:117], v[138:141], v[178:181], v[114:117]
	v_mfma_f32_16x16x32_f16 v[110:113], v[82:85], v[186:189], v[110:113]
	v_mfma_f32_16x16x32_f16 v[106:109], v[138:141], v[186:189], v[106:109]
	v_mfma_f32_16x16x32_f16 v[134:137], v[86:89], v[160:163], v[134:137]
	v_mfma_f32_16x16x32_f16 v[130:133], v[142:145], v[160:163], v[130:133]
	v_mfma_f32_16x16x32_f16 v[126:129], v[86:89], v[168:171], v[126:129]
	v_mfma_f32_16x16x32_f16 v[122:125], v[142:145], v[168:171], v[122:125]
	v_mfma_f32_16x16x32_f16 v[118:121], v[86:89], v[182:185], v[118:121]
	v_mfma_f32_16x16x32_f16 v[114:117], v[142:145], v[182:185], v[114:117]
	v_mfma_f32_16x16x32_f16 v[110:113], v[86:89], v[190:193], v[110:113]
	v_mfma_f32_16x16x32_f16 v[106:109], v[142:145], v[190:193], v[106:109]
	v_mfma_f32_16x16x32_f16 v[62:65], v[194:197], v[156:159], v[62:65]
	v_mfma_f32_16x16x32_f16 v[58:61], v[202:205], v[156:159], v[58:61]
	v_mfma_f32_16x16x32_f16 v[54:57], v[194:197], v[164:167], v[54:57]
	v_mfma_f32_16x16x32_f16 v[50:53], v[202:205], v[164:167], v[50:53]
	v_mfma_f32_16x16x32_f16 v[46:49], v[194:197], v[178:181], v[46:49]
	v_mfma_f32_16x16x32_f16 v[42:45], v[202:205], v[178:181], v[42:45]
	v_mfma_f32_16x16x32_f16 v[38:41], v[194:197], v[186:189], v[38:41]
	v_mfma_f32_16x16x32_f16 v[34:37], v[202:205], v[186:189], v[34:37]
	v_mfma_f32_16x16x32_f16 v[62:65], v[198:201], v[160:163], v[62:65]
	v_mfma_f32_16x16x32_f16 v[58:61], v[220:223], v[160:163], v[58:61]
	v_mfma_f32_16x16x32_f16 v[54:57], v[198:201], v[168:171], v[54:57]
	v_mfma_f32_16x16x32_f16 v[50:53], v[220:223], v[168:171], v[50:53]
	v_mfma_f32_16x16x32_f16 v[46:49], v[198:201], v[182:185], v[46:49]
	v_mfma_f32_16x16x32_f16 v[42:45], v[220:223], v[182:185], v[42:45]
	v_mfma_f32_16x16x32_f16 v[38:41], v[198:201], v[190:193], v[38:41]
	v_mfma_f32_16x16x32_f16 v[34:37], v[220:223], v[190:193], v[34:37]
	s_barrier
; #define PG8_STAGE(bufoff, gbase, voff) do { _Pragma("unroll") for (int _i = 0; _i < 2; ++_i) \
;         __builtin_amdgcn_global_load_lds((const unsigned*)((const char*)(gbase) + (voff)[_i]), (LAS unsigned*)(lds + (bufoff) + ldsw + _i * 8192), 16, 0, 0); } while (0)
; #define PG8_LDA(dst, b, h) do { _Pragma("unroll") for (int m = 0; m < 4; ++m) _Pragma("unroll") for (int k = 0; k < 2; ++k) dst[m][k] = *(const LAS h16x8*)(lds + PG8_SA(b, h) + aoff + m * 2048 + k * 1024); } while (0)
; #define PG8_LDB(dst, b, h) do { _Pragma("unroll") for (int n = 0; n < 2; ++n) _Pragma("unroll") for (int k = 0; k < 2; ++k) dst[n][k] = *(const LAS h16x8*)(lds + PG8_SB(b, h) + boff + n * 2048 + k * 1024); } while (0)
; #define PG8_MMA(ai, bj, At, Bt_) do { __builtin_amdgcn_s_setprio(1); _Pragma("unroll") for (int m = 0; m < 4; ++m) _Pragma("unroll") for (int n = 0; n < 2; ++n) _Pragma("unroll") for (int k = 0; k < 2; ++k) \
;         acc[ai][bj][m][n] = __builtin_amdgcn_mfma_f32_16x16x32_f16(Bt_[n][k], At[m][k], acc[ai][bj][m][n], 0, 0, 0); __builtin_amdgcn_s_setprio(0); } while (0)
; #define PG8_WAIT_V(n) asm volatile("s_waitcnt vmcnt(" #n ")" ::: "memory")
; #define PG8_WAIT_L(n) asm volatile("s_waitcnt lgkmcnt(" #n ")" ::: "memory")
; #define PG8_BAR __builtin_amdgcn_s_barrier()
; #define PG8_SCHED __builtin_amdgcn_sched_barrier(0)
; template <class Epi, class AMap>
; __device__ __forceinline__ void gemm_phase(LAS unsigned char* lds, const AMap am, const int lda, const h16* Bt, const int ldb, const int M, const int N, const int K, const Epi& E) {
;     ...
;             PG8_LDB(B0, 1, 0); PG8_SCHED; PG8_LDA(At, 1, 0); PG8_STAGE(PG8_SA(0, 1), a2 + hstepA, voffA);
;             PG8_WAIT_L(8); PG8_BAR; PG8_WAIT_L(0); PG8_MMA(0, 0, At, B0); PG8_BAR; PG8_SCHED;
;             PG8_LDB(B1, 1, 1); PG8_STAGE(PG8_SB(1, 0), b3, voffB);
;             PG8_BAR; PG8_WAIT_L(0); PG8_MMA(0, 1, At, B1); PG8_BAR;
;             PG8_LDA(At, 1, 1); PG8_STAGE(PG8_SA(1, 0), a3, voffA);
;             PG8_BAR; PG8_WAIT_L(0); PG8_MMA(1, 0, At, B0); PG8_BAR; PG8_SCHED;
;             PG8_STAGE(PG8_SB(1, 1), b3 + hstepB, voffB);
;             PG8_WAIT_V(6); PG8_BAR; PG8_MMA(1, 1, At, B1); PG8_BAR;
;         }
	global_load_lds_dwordx4 v[172:173], off
	v_lshl_add_u64 v[172:173], v[206:207], 0, s[92:93]
	s_add_i32 m0, s22, 0x2000
	s_nop 0
	global_load_lds_dwordx4 v[172:173], off
	s_mov_b32 m0, s79
	v_lshl_add_u64 v[172:173], v[212:213], 0, s[92:93]
	ds_read_b128 v[156:159], v177 offset:49152
	ds_read_b128 v[160:163], v177 offset:50176
	ds_read_b128 v[164:167], v177 offset:51200
	ds_read_b128 v[168:171], v177 offset:52224
	ds_read_b128 v[178:181], v177 offset:53248
	ds_read_b128 v[182:185], v177 offset:54272
	ds_read_b128 v[186:189], v177 offset:55296
	ds_read_b128 v[190:193], v177 offset:56320
	global_load_lds_dwordx4 v[172:173], off
	v_lshl_add_u64 v[172:173], v[224:225], 0, s[92:93]
	s_mov_b32 m0, s80
	s_nop 0
	global_load_lds_dwordx4 v[172:173], off
	s_add_u32 s22, s26, 0x10080
	s_addc_u32 s23, s27, 0
	s_add_i32 s26, s48, s71
	v_lshl_add_u64 v[232:233], s[22:23], 0, v[0:1]
	s_mov_b32 m0, s26
	s_nop 0
	global_load_lds_dwordx4 v[232:233], off
	v_lshl_add_u64 v[232:233], s[22:23], 0, v[150:151]
	s_add_i32 m0, s26, 0x2000
	s_nop 0
	global_load_lds_dwordx4 v[232:233], off
	s_add_u32 s29, s29, 0x100
	s_addc_u32 s45, s45, 0
	s_cmp_ge_i32 s51, s24
	s_mov_b64 s[22:23], s[0:1]
	s_mov_b32 s26, s51
	s_waitcnt vmcnt(8) lgkmcnt(0)
	s_barrier
	v_mfma_f32_16x16x32_f16 v[102:105], v[82:85], v[156:159], v[102:105]
	v_mfma_f32_16x16x32_f16 v[98:101], v[138:141], v[156:159], v[98:101]
	v_mfma_f32_16x16x32_f16 v[94:97], v[82:85], v[164:167], v[94:97]
	v_mfma_f32_16x16x32_f16 v[90:93], v[138:141], v[164:167], v[90:93]
	v_mfma_f32_16x16x32_f16 v[78:81], v[82:85], v[178:181], v[78:81]
	v_mfma_f32_16x16x32_f16 v[74:77], v[138:141], v[178:181], v[74:77]
	v_mfma_f32_16x16x32_f16 v[70:73], v[82:85], v[186:189], v[70:73]
	v_mfma_f32_16x16x32_f16 v[66:69], v[138:141], v[186:189], v[66:69]
	v_mfma_f32_16x16x32_f16 v[102:105], v[86:89], v[160:163], v[102:105]
	v_mfma_f32_16x16x32_f16 v[98:101], v[142:145], v[160:163], v[98:101]
	v_mfma_f32_16x16x32_f16 v[94:97], v[86:89], v[168:171], v[94:97]
	v_mfma_f32_16x16x32_f16 v[90:93], v[142:145], v[168:171], v[90:93]
	v_mfma_f32_16x16x32_f16 v[78:81], v[86:89], v[182:185], v[78:81]
	v_mfma_f32_16x16x32_f16 v[74:77], v[142:145], v[182:185], v[74:77]
	v_mfma_f32_16x16x32_f16 v[70:73], v[86:89], v[190:193], v[70:73]
	v_mfma_f32_16x16x32_f16 v[66:69], v[142:145], v[190:193], v[66:69]
	v_mfma_f32_16x16x32_f16 v[30:33], v[194:197], v[156:159], v[30:33]
	v_mfma_f32_16x16x32_f16 v[26:29], v[202:205], v[156:159], v[26:29]
	v_mfma_f32_16x16x32_f16 v[22:25], v[194:197], v[164:167], v[22:25]
	v_mfma_f32_16x16x32_f16 v[18:21], v[202:205], v[164:167], v[18:21]
	v_mfma_f32_16x16x32_f16 v[14:17], v[194:197], v[178:181], v[14:17]
	v_mfma_f32_16x16x32_f16 v[10:13], v[202:205], v[178:181], v[10:13]
	v_mfma_f32_16x16x32_f16 v[6:9], v[194:197], v[186:189], v[6:9]
	v_mfma_f32_16x16x32_f16 v[2:5], v[202:205], v[186:189], v[2:5]
	v_mfma_f32_16x16x32_f16 v[30:33], v[198:201], v[160:163], v[30:33]
	v_mfma_f32_16x16x32_f16 v[26:29], v[220:223], v[160:163], v[26:29]
	v_mfma_f32_16x16x32_f16 v[22:25], v[198:201], v[168:171], v[22:25]
	v_mfma_f32_16x16x32_f16 v[18:21], v[220:223], v[168:171], v[18:21]
	v_mfma_f32_16x16x32_f16 v[14:17], v[198:201], v[182:185], v[14:17]
	v_mfma_f32_16x16x32_f16 v[10:13], v[220:223], v[182:185], v[10:13]
	v_mfma_f32_16x16x32_f16 v[6:9], v[198:201], v[190:193], v[6:9]
	v_mfma_f32_16x16x32_f16 v[2:5], v[220:223], v[190:193], v[2:5]
	s_barrier
	s_cbranch_scc0 .LBB0_692
	s_cmpk_gt_u32 s69, 0xff
	s_cbranch_scc1 .Lgx7
	s_barrier

; #define PG8_STAGE(bufoff, gbase, voff) do { _Pragma("unroll") for (int _i = 0; _i < 2; ++_i) \
;         __builtin_amdgcn_global_load_lds((const unsigned*)((const char*)(gbase) + (voff)[_i]), (LAS unsigned*)(lds + (bufoff) + ldsw + _i * 8192), 16, 0, 0); } while (0)
; #define PG8_LDA(dst, b, h) do { _Pragma("unroll") for (int m = 0; m < 4; ++m) _Pragma("unroll") for (int k = 0; k < 2; ++k) dst[m][k] = *(const LAS h16x8*)(lds + PG8_SA(b, h) + aoff + m * 2048 + k * 1024); } while (0)
; #define PG8_LDB(dst, b, h) do { _Pragma("unroll") for (int n = 0; n < 2; ++n) _Pragma("unroll") for (int k = 0; k < 2; ++k) dst[n][k] = *(const LAS h16x8*)(lds + PG8_SB(b, h) + boff + n * 2048 + k * 1024); } while (0)
; #define PG8_WAIT_V(n) asm volatile("s_waitcnt vmcnt(" #n ")" ::: "memory")
; #define PG8_WAIT_L(n) asm volatile("s_waitcnt lgkmcnt(" #n ")" ::: "memory")
; #define PG8_BAR __builtin_amdgcn_s_barrier()
; #define PG8_SCHED __builtin_amdgcn_sched_barrier(0)
; template <class Epi, class AMap>
; __device__ __forceinline__ void gemm_phase(LAS unsigned char* lds, const AMap am, const int lda, const h16* Bt, const int ldb, const int M, const int N, const int K, const Epi& E) {
;     ...
;         const bool has_next = S.next(ui + 1, nxt);
;         const char* nA = has_next ? am(nxt.pn) + (size_t)nxt.pm * tstepA : cA; const char* nB = has_next ? (const char*)Bt + (size_t)nxt.pn * tstepB : cB;
; #pragma unroll 1
;         for (int t = 0; t < nt; t += 2) {
;             const bool last = (t == nt - 2);
;             const char* a1 = cA + (size_t)(t + 1) * kstep;
;             const char* a2 = last ? nA : cA + (size_t)(t + 2) * kstep; const char* b2 = last ? nB : cB + (size_t)(t + 2) * kstep;
;             const char* a3 = a2 + kstep; const char* b3 = b2 + kstep;
;             PG8_LDB(B0, 0, 0); PG8_SCHED; PG8_LDA(At, 0, 0); PG8_STAGE(PG8_SA(1, 1), a1 + hstepA, voffA);
;             PG8_WAIT_L(8); PG8_BAR; PG8_WAIT_L(0); PG8_MMA(0, 0, At, B0); PG8_BAR; PG8_SCHED;
;             PG8_LDB(B1, 0, 1); PG8_STAGE(PG8_SB(0, 0), b2, voffB);
;             PG8_BAR; PG8_WAIT_L(0); PG8_MMA(0, 1, At, B1); PG8_BAR;
;             PG8_LDA(At, 0, 1); PG8_STAGE(PG8_SA(0, 0), a2, voffA);
;             PG8_BAR; PG8_WAIT_L(0); PG8_MMA(1, 0, At, B0); PG8_BAR; PG8_SCHED;
;             PG8_STAGE(PG8_SB(0, 1), b2 + hstepB, voffB);
;             PG8_WAIT_V(6); PG8_BAR; PG8_MMA(1, 1, At, B1); PG8_BAR;
.LBB0_798:
	s_ashr_i32 s43, s42, 31
	s_lshl_b64 s[20:21], s[42:43], 20
	s_add_u32 s64, s10, s20
	s_addc_u32 s65, s11, s21
	s_and_b64 s[0:1], s[0:1], exec
	s_cselect_b32 s29, s65, s41
	s_cselect_b32 s20, s64, s40
	s_add_u32 s0, s48, 0x80080
	s_addc_u32 s1, s49, 0
	s_add_u32 s21, s40, 0x100
	s_addc_u32 s35, s41, 0
	s_mov_b32 s43, -2
	s_add_u32 s40, s0, 0xfff80080
	s_addc_u32 s41, s1, -1
	s_add_i32 s45, 0, 0x10000
	v_add_u32_e32 v152, s45, v155
	ds_read_b128 v[130:133], v152
	ds_read_b128 v[134:137], v152 offset:1024
	ds_read_b128 v[148:151], v152 offset:2048
	ds_read_b128 v[158:161], v152 offset:3072
	s_cmp_eq_u32 s43, 28
	s_cselect_b32 s49, s47, s41
	s_cselect_b32 s48, s46, s40
	s_cselect_b32 s41, s29, s35
	s_cselect_b32 s40, s20, s21
	v_lshl_add_u64 v[152:153], s[0:1], 0, v[144:145]
	s_add_i32 m0, s23, 0xc000
	ds_read_b128 v[162:165], v157
	ds_read_b128 v[166:169], v157 offset:1024
	ds_read_b128 v[170:173], v157 offset:2048
	ds_read_b128 v[174:177], v157 offset:3072
	ds_read_b128 v[178:181], v157 offset:4096
	ds_read_b128 v[182:185], v157 offset:5120
	ds_read_b128 v[186:189], v157 offset:6144
	ds_read_b128 v[190:193], v157 offset:7168
	global_load_lds_dwordx4 v[152:153], off
	v_lshl_add_u64 v[152:153], s[0:1], 0, v[146:147]
	s_add_i32 m0, s23, 0xe000
	s_nop 0
	global_load_lds_dwordx4 v[152:153], off
	s_waitcnt lgkmcnt(11)
	s_add_i32 s60, 0, 0x14000
	v_add_u32_e32 v152, s60, v155
	s_add_i32 s45, s45, s72
	ds_read_b128 v[194:197], v152
	ds_read_b128 v[198:201], v152 offset:1024
	ds_read_b128 v[202:205], v152 offset:2048
	ds_read_b128 v[220:223], v152 offset:3072
	s_waitcnt vmcnt(8) lgkmcnt(0)
	s_barrier
	v_mfma_f32_16x16x32_f16 v[126:129], v[130:133], v[162:165], 0
	v_mfma_f32_16x16x32_f16 v[122:125], v[148:151], v[162:165], 0
	v_mfma_f32_16x16x32_f16 v[110:113], v[130:133], v[170:173], 0
	v_mfma_f32_16x16x32_f16 v[106:109], v[148:151], v[170:173], 0
	v_mfma_f32_16x16x32_f16 v[94:97], v[130:133], v[178:181], 0
	v_mfma_f32_16x16x32_f16 v[90:93], v[148:151], v[178:181], 0
	v_mfma_f32_16x16x32_f16 v[78:81], v[130:133], v[186:189], 0
	v_mfma_f32_16x16x32_f16 v[74:77], v[148:151], v[186:189], 0
	v_mfma_f32_16x16x32_f16 v[126:129], v[134:137], v[166:169], v[126:129]
	v_mfma_f32_16x16x32_f16 v[122:125], v[158:161], v[166:169], v[122:125]
	v_mfma_f32_16x16x32_f16 v[110:113], v[134:137], v[174:177], v[110:113]
	v_mfma_f32_16x16x32_f16 v[106:109], v[158:161], v[174:177], v[106:109]
	v_mfma_f32_16x16x32_f16 v[94:97], v[134:137], v[182:185], v[94:97]
	v_mfma_f32_16x16x32_f16 v[90:93], v[158:161], v[182:185], v[90:93]
	v_mfma_f32_16x16x32_f16 v[78:81], v[134:137], v[190:193], v[78:81]
	v_mfma_f32_16x16x32_f16 v[74:77], v[158:161], v[190:193], v[74:77]
	v_mfma_f32_16x16x32_f16 v[118:121], v[194:197], v[162:165], 0
	v_mfma_f32_16x16x32_f16 v[114:117], v[202:205], v[162:165], 0
	v_mfma_f32_16x16x32_f16 v[102:105], v[194:197], v[170:173], 0
	v_mfma_f32_16x16x32_f16 v[98:101], v[202:205], v[170:173], 0
	v_mfma_f32_16x16x32_f16 v[86:89], v[194:197], v[178:181], 0
	v_mfma_f32_16x16x32_f16 v[82:85], v[202:205], v[178:181], 0
	v_mfma_f32_16x16x32_f16 v[70:73], v[194:197], v[186:189], 0
	v_mfma_f32_16x16x32_f16 v[66:69], v[202:205], v[186:189], 0
	v_mfma_f32_16x16x32_f16 v[118:121], v[198:201], v[166:169], v[118:121]
	v_mfma_f32_16x16x32_f16 v[114:117], v[220:223], v[166:169], v[114:117]
	v_mfma_f32_16x16x32_f16 v[102:105], v[198:201], v[174:177], v[102:105]
	v_mfma_f32_16x16x32_f16 v[98:101], v[220:223], v[174:177], v[98:101]
	v_mfma_f32_16x16x32_f16 v[86:89], v[198:201], v[182:185], v[86:89]
	v_mfma_f32_16x16x32_f16 v[82:85], v[220:223], v[182:185], v[82:85]
	v_mfma_f32_16x16x32_f16 v[70:73], v[198:201], v[190:193], v[70:73]
	v_mfma_f32_16x16x32_f16 v[66:69], v[220:223], v[190:193], v[66:69]
	s_barrier
	v_lshl_add_u64 v[152:153], s[40:41], 0, v[0:1]
	s_mov_b32 m0, s45
	v_lshl_add_u64 v[206:207], s[40:41], 0, v[142:143]
	global_load_lds_dwordx4 v[152:153], off
	s_add_i32 m0, s45, 0x2000
	s_nop 0
	global_load_lds_dwordx4 v[206:207], off
	s_mov_b32 m0, s23
	v_lshl_add_u64 v[212:213], s[48:49], 0, v[138:139]
	ds_read_b128 v[162:165], v157 offset:16384
	ds_read_b128 v[166:169], v157 offset:17408
	ds_read_b128 v[170:173], v157 offset:18432
	ds_read_b128 v[174:177], v157 offset:19456
	ds_read_b128 v[178:181], v157 offset:20480
	ds_read_b128 v[182:185], v157 offset:21504
	ds_read_b128 v[186:189], v157 offset:22528
	ds_read_b128 v[190:193], v157 offset:23552
	global_load_lds_dwordx4 v[212:213], off
	v_lshl_add_u64 v[224:225], s[48:49], 0, v[140:141]
	s_mov_b32 m0, s27
	s_nop 0
	global_load_lds_dwordx4 v[224:225], off
	s_add_u32 s50, s40, 0x80000
	s_addc_u32 s51, s41, 0
	s_add_i32 s45, s60, s72
	v_lshl_add_u64 v[232:233], s[50:51], 0, v[0:1]
	s_mov_b32 m0, s45
	s_nop 0
	global_load_lds_dwordx4 v[232:233], off
	v_lshl_add_u64 v[232:233], s[50:51], 0, v[142:143]
	s_add_i32 m0, s45, 0x2000
	s_nop 0
	global_load_lds_dwordx4 v[232:233], off
	s_waitcnt vmcnt(8) lgkmcnt(0)
	s_barrier
; #define PG8_STAGE(bufoff, gbase, voff) do { _Pragma("unroll") for (int _i = 0; _i < 2; ++_i) \
;         __builtin_amdgcn_global_load_lds((const unsigned*)((const char*)(gbase) + (voff)[_i]), (LAS unsigned*)(lds + (bufoff) + ldsw + _i * 8192), 16, 0, 0); } while (0)
; #define PG8_LDA(dst, b, h) do { _Pragma("unroll") for (int m = 0; m < 4; ++m) _Pragma("unroll") for (int k = 0; k < 2; ++k) dst[m][k] = *(const LAS h16x8*)(lds + PG8_SA(b, h) + aoff + m * 2048 + k * 1024); } while (0)
; #define PG8_LDB(dst, b, h) do { _Pragma("unroll") for (int n = 0; n < 2; ++n) _Pragma("unroll") for (int k = 0; k < 2; ++k) dst[n][k] = *(const LAS h16x8*)(lds + PG8_SB(b, h) + boff + n * 2048 + k * 1024); } while (0)
; #define PG8_MMA(ai, bj, At, Bt_) do { __builtin_amdgcn_s_setprio(1); _Pragma("unroll") for (int m = 0; m < 4; ++m) _Pragma("unroll") for (int n = 0; n < 2; ++n) _Pragma("unroll") for (int k = 0; k < 2; ++k) \
;         acc[ai][bj][m][n] = __builtin_amdgcn_mfma_f32_16x16x32_f16(Bt_[n][k], At[m][k], acc[ai][bj][m][n], 0, 0, 0); __builtin_amdgcn_s_setprio(0); } while (0)
; #define PG8_WAIT_V(n) asm volatile("s_waitcnt vmcnt(" #n ")" ::: "memory")
; #define PG8_WAIT_L(n) asm volatile("s_waitcnt lgkmcnt(" #n ")" ::: "memory")
; #define PG8_BAR __builtin_amdgcn_s_barrier()
; #define PG8_SCHED __builtin_amdgcn_sched_barrier(0)
; template <class Epi, class AMap>
; __device__ __forceinline__ void gemm_phase(LAS unsigned char* lds, const AMap am, const int lda, const h16* Bt, const int ldb, const int M, const int N, const int K, const Epi& E) {
;     ...
;             PG8_BAR; PG8_WAIT_L(0); PG8_MMA(1, 0, At, B0); PG8_BAR; PG8_SCHED;
;             PG8_STAGE(PG8_SB(0, 1), b2 + hstepB, voffB);
;             PG8_WAIT_V(6); PG8_BAR; PG8_MMA(1, 1, At, B1); PG8_BAR;
;             PG8_LDB(B0, 1, 0); PG8_SCHED; PG8_LDA(At, 1, 0); PG8_STAGE(PG8_SA(0, 1), a2 + hstepA, voffA);
;             PG8_WAIT_L(8); PG8_BAR; PG8_WAIT_L(0); PG8_MMA(0, 0, At, B0); PG8_BAR; PG8_SCHED;
;             PG8_LDB(B1, 1, 1); PG8_STAGE(PG8_SB(1, 0), b3, voffB);
;             PG8_BAR; PG8_WAIT_L(0); PG8_MMA(0, 1, At, B1); PG8_BAR;
;             PG8_LDA(At, 1, 1); PG8_STAGE(PG8_SA(1, 0), a3, voffA);
;             PG8_BAR; PG8_WAIT_L(0); PG8_MMA(1, 0, At, B0); PG8_BAR; PG8_SCHED;
	v_mfma_f32_16x16x32_f16 v[62:65], v[130:133], v[162:165], 0
	v_mfma_f32_16x16x32_f16 v[58:61], v[148:151], v[162:165], 0
	v_mfma_f32_16x16x32_f16 v[46:49], v[130:133], v[170:173], 0
	v_mfma_f32_16x16x32_f16 v[42:45], v[148:151], v[170:173], 0
	v_mfma_f32_16x16x32_f16 v[30:33], v[130:133], v[178:181], 0
	v_mfma_f32_16x16x32_f16 v[26:29], v[148:151], v[178:181], 0
	v_mfma_f32_16x16x32_f16 v[14:17], v[130:133], v[186:189], 0
	v_mfma_f32_16x16x32_f16 v[10:13], v[148:151], v[186:189], 0
	v_mfma_f32_16x16x32_f16 v[62:65], v[134:137], v[166:169], v[62:65]
	v_mfma_f32_16x16x32_f16 v[58:61], v[158:161], v[166:169], v[58:61]
	v_mfma_f32_16x16x32_f16 v[46:49], v[134:137], v[174:177], v[46:49]
	v_mfma_f32_16x16x32_f16 v[42:45], v[158:161], v[174:177], v[42:45]
	v_mfma_f32_16x16x32_f16 v[30:33], v[134:137], v[182:185], v[30:33]
	v_mfma_f32_16x16x32_f16 v[26:29], v[158:161], v[182:185], v[26:29]
	v_mfma_f32_16x16x32_f16 v[14:17], v[134:137], v[190:193], v[14:17]
	v_mfma_f32_16x16x32_f16 v[10:13], v[158:161], v[190:193], v[10:13]
	v_mfma_f32_16x16x32_f16 v[54:57], v[194:197], v[162:165], 0
	v_mfma_f32_16x16x32_f16 v[50:53], v[202:205], v[162:165], 0
	v_mfma_f32_16x16x32_f16 v[38:41], v[194:197], v[170:173], 0
	v_mfma_f32_16x16x32_f16 v[34:37], v[202:205], v[170:173], 0
	v_mfma_f32_16x16x32_f16 v[22:25], v[194:197], v[178:181], 0
	v_mfma_f32_16x16x32_f16 v[18:21], v[202:205], v[178:181], 0
	v_mfma_f32_16x16x32_f16 v[6:9], v[194:197], v[186:189], 0
	v_mfma_f32_16x16x32_f16 v[2:5], v[202:205], v[186:189], 0
	v_mfma_f32_16x16x32_f16 v[54:57], v[198:201], v[166:169], v[54:57]
	v_mfma_f32_16x16x32_f16 v[50:53], v[220:223], v[166:169], v[50:53]
	v_mfma_f32_16x16x32_f16 v[38:41], v[198:201], v[174:177], v[38:41]
	v_mfma_f32_16x16x32_f16 v[34:37], v[220:223], v[174:177], v[34:37]
	v_mfma_f32_16x16x32_f16 v[22:25], v[198:201], v[182:185], v[22:25]
	v_mfma_f32_16x16x32_f16 v[18:21], v[220:223], v[182:185], v[18:21]
	v_mfma_f32_16x16x32_f16 v[6:9], v[198:201], v[190:193], v[6:9]
	v_mfma_f32_16x16x32_f16 v[2:5], v[220:223], v[190:193], v[2:5]
	s_barrier
	s_add_i32 s45, 0, 0x18000
	v_add_u32_e32 v234, s45, v155
	ds_read_b128 v[130:133], v234
	ds_read_b128 v[134:137], v234 offset:1024
	ds_read_b128 v[148:151], v234 offset:2048
	ds_read_b128 v[158:161], v234 offset:3072
	s_add_u32 s48, s48, 0x80000
	s_addc_u32 s49, s49, 0
	s_mov_b32 m0, s73
	v_lshl_add_u64 v[232:233], s[48:49], 0, v[138:139]
	ds_read_b128 v[162:165], v157 offset:32768
	ds_read_b128 v[166:169], v157 offset:33792
	ds_read_b128 v[170:173], v157 offset:34816
	ds_read_b128 v[174:177], v157 offset:35840
	ds_read_b128 v[178:181], v157 offset:36864
	ds_read_b128 v[182:185], v157 offset:37888
	ds_read_b128 v[186:189], v157 offset:38912
	ds_read_b128 v[190:193], v157 offset:39936
	global_load_lds_dwordx4 v[232:233], off
	v_lshl_add_u64 v[232:233], s[48:49], 0, v[140:141]
	s_mov_b32 m0, s74
	s_nop 0
	global_load_lds_dwordx4 v[232:233], off
	s_waitcnt lgkmcnt(11)
	s_add_i32 s48, 0, 0x1c000
	s_add_i32 s45, s45, s72
	v_add_u32_e32 v214, s48, v155
	v_lshl_add_u64 v[152:153], v[152:153], 0, s[92:93]
	s_mov_b32 m0, s45
	ds_read_b128 v[194:197], v214
	ds_read_b128 v[198:201], v214 offset:1024
	ds_read_b128 v[202:205], v214 offset:2048
	ds_read_b128 v[220:223], v214 offset:3072
	s_waitcnt vmcnt(8) lgkmcnt(0)
	s_barrier
	v_mfma_f32_16x16x32_f16 v[126:129], v[130:133], v[162:165], v[126:129]
	v_mfma_f32_16x16x32_f16 v[122:125], v[148:151], v[162:165], v[122:125]
	v_mfma_f32_16x16x32_f16 v[110:113], v[130:133], v[170:173], v[110:113]
	v_mfma_f32_16x16x32_f16 v[106:109], v[148:151], v[170:173], v[106:109]
	v_mfma_f32_16x16x32_f16 v[94:97], v[130:133], v[178:181], v[94:97]
	v_mfma_f32_16x16x32_f16 v[90:93], v[148:151], v[178:181], v[90:93]
	v_mfma_f32_16x16x32_f16 v[78:81], v[130:133], v[186:189], v[78:81]
	v_mfma_f32_16x16x32_f16 v[74:77], v[148:151], v[186:189], v[74:77]
	v_mfma_f32_16x16x32_f16 v[126:129], v[134:137], v[166:169], v[126:129]
	v_mfma_f32_16x16x32_f16 v[122:125], v[158:161], v[166:169], v[122:125]
	v_mfma_f32_16x16x32_f16 v[110:113], v[134:137], v[174:177], v[110:113]
	v_mfma_f32_16x16x32_f16 v[106:109], v[158:161], v[174:177], v[106:109]
	v_mfma_f32_16x16x32_f16 v[94:97], v[134:137], v[182:185], v[94:97]
	v_mfma_f32_16x16x32_f16 v[90:93], v[158:161], v[182:185], v[90:93]
	v_mfma_f32_16x16x32_f16 v[78:81], v[134:137], v[190:193], v[78:81]
	v_mfma_f32_16x16x32_f16 v[74:77], v[158:161], v[190:193], v[74:77]
	v_mfma_f32_16x16x32_f16 v[118:121], v[194:197], v[162:165], v[118:121]
	v_mfma_f32_16x16x32_f16 v[114:117], v[202:205], v[162:165], v[114:117]
	v_mfma_f32_16x16x32_f16 v[102:105], v[194:197], v[170:173], v[102:105]
	v_mfma_f32_16x16x32_f16 v[98:101], v[202:205], v[170:173], v[98:101]
	v_mfma_f32_16x16x32_f16 v[86:89], v[194:197], v[178:181], v[86:89]
	v_mfma_f32_16x16x32_f16 v[82:85], v[202:205], v[178:181], v[82:85]
	v_mfma_f32_16x16x32_f16 v[70:73], v[194:197], v[186:189], v[70:73]
	v_mfma_f32_16x16x32_f16 v[66:69], v[202:205], v[186:189], v[66:69]
	v_mfma_f32_16x16x32_f16 v[118:121], v[198:201], v[166:169], v[118:121]
	v_mfma_f32_16x16x32_f16 v[114:117], v[220:223], v[166:169], v[114:117]
	v_mfma_f32_16x16x32_f16 v[102:105], v[198:201], v[174:177], v[102:105]
	v_mfma_f32_16x16x32_f16 v[98:101], v[220:223], v[174:177], v[98:101]
	v_mfma_f32_16x16x32_f16 v[86:89], v[198:201], v[182:185], v[86:89]
	v_mfma_f32_16x16x32_f16 v[82:85], v[220:223], v[182:185], v[82:85]
	v_mfma_f32_16x16x32_f16 v[70:73], v[198:201], v[190:193], v[70:73]
	v_mfma_f32_16x16x32_f16 v[66:69], v[220:223], v[190:193], v[66:69]
	s_barrier
; #define PG8_STAGE(bufoff, gbase, voff) do { _Pragma("unroll") for (int _i = 0; _i < 2; ++_i) \
;         __builtin_amdgcn_global_load_lds((const unsigned*)((const char*)(gbase) + (voff)[_i]), (LAS unsigned*)(lds + (bufoff) + ldsw + _i * 8192), 16, 0, 0); } while (0)
; #define PG8_LDA(dst, b, h) do { _Pragma("unroll") for (int m = 0; m < 4; ++m) _Pragma("unroll") for (int k = 0; k < 2; ++k) dst[m][k] = *(const LAS h16x8*)(lds + PG8_SA(b, h) + aoff + m * 2048 + k * 1024); } while (0)
; #define PG8_LDB(dst, b, h) do { _Pragma("unroll") for (int n = 0; n < 2; ++n) _Pragma("unroll") for (int k = 0; k < 2; ++k) dst[n][k] = *(const LAS h16x8*)(lds + PG8_SB(b, h) + boff + n * 2048 + k * 1024); } while (0)
; #define PG8_MMA(ai, bj, At, Bt_) do { __builtin_amdgcn_s_setprio(1); _Pragma("unroll") for (int m = 0; m < 4; ++m) _Pragma("unroll") for (int n = 0; n < 2; ++n) _Pragma("unroll") for (int k = 0; k < 2; ++k) \
;         acc[ai][bj][m][n] = __builtin_amdgcn_mfma_f32_16x16x32_f16(Bt_[n][k], At[m][k], acc[ai][bj][m][n], 0, 0, 0); __builtin_amdgcn_s_setprio(0); } while (0)
; #define PG8_WAIT_V(n) asm volatile("s_waitcnt vmcnt(" #n ")" ::: "memory")
; #define PG8_WAIT_L(n) asm volatile("s_waitcnt lgkmcnt(" #n ")" ::: "memory")
; #define PG8_BAR __builtin_amdgcn_s_barrier()
; #define PG8_SCHED __builtin_amdgcn_sched_barrier(0)
; template <class Epi, class AMap>
; __device__ __forceinline__ void gemm_phase(LAS unsigned char* lds, const AMap am, const int lda, const h16* Bt, const int ldb, const int M, const int N, const int K, const Epi& E) {
;     ...
;             PG8_LDB(B0, 0, 0); PG8_SCHED; PG8_LDA(At, 0, 0); PG8_STAGE(PG8_SA(1, 1), a1 + hstepA, voffA);
;             PG8_WAIT_L(8); PG8_BAR; PG8_WAIT_L(0); PG8_MMA(0, 0, At, B0); PG8_BAR; PG8_SCHED;
;     ...
;             PG8_LDB(B1, 1, 1); PG8_STAGE(PG8_SB(1, 0), b3, voffB);
;             PG8_BAR; PG8_WAIT_L(0); PG8_MMA(0, 1, At, B1); PG8_BAR;
;             PG8_LDA(At, 1, 1); PG8_STAGE(PG8_SA(1, 0), a3, voffA);
;             PG8_BAR; PG8_WAIT_L(0); PG8_MMA(1, 0, At, B0); PG8_BAR; PG8_SCHED;
;             PG8_STAGE(PG8_SB(1, 1), b3 + hstepB, voffB);
;             PG8_WAIT_V(6); PG8_BAR; PG8_MMA(1, 1, At, B1); PG8_BAR;
;         }
	global_load_lds_dwordx4 v[152:153], off
	v_lshl_add_u64 v[152:153], v[206:207], 0, s[92:93]
	s_add_i32 m0, s45, 0x2000
	s_nop 0
	global_load_lds_dwordx4 v[152:153], off
	s_mov_b32 m0, s75
	v_lshl_add_u64 v[152:153], v[212:213], 0, s[92:93]
	ds_read_b128 v[162:165], v157 offset:49152
	ds_read_b128 v[166:169], v157 offset:50176
	ds_read_b128 v[170:173], v157 offset:51200
	ds_read_b128 v[174:177], v157 offset:52224
	ds_read_b128 v[178:181], v157 offset:53248
	ds_read_b128 v[182:185], v157 offset:54272
	ds_read_b128 v[186:189], v157 offset:55296
	ds_read_b128 v[190:193], v157 offset:56320
	global_load_lds_dwordx4 v[152:153], off
	v_lshl_add_u64 v[152:153], v[224:225], 0, s[92:93]
	s_mov_b32 m0, s76
	s_nop 0
	global_load_lds_dwordx4 v[152:153], off
	s_add_u32 s40, s40, 0x80080
	s_addc_u32 s41, s41, 0
	s_add_i32 s45, s48, s72
	v_lshl_add_u64 v[232:233], s[40:41], 0, v[0:1]
	s_mov_b32 m0, s45
	s_nop 0
	global_load_lds_dwordx4 v[232:233], off
	v_lshl_add_u64 v[232:233], s[40:41], 0, v[142:143]
	s_add_i32 m0, s45, 0x2000
	s_nop 0
	global_load_lds_dwordx4 v[232:233], off
	s_add_i32 s43, s43, 2
	s_add_u32 s0, s0, 0x100
	s_addc_u32 s1, s1, 0
	s_add_u32 s21, s21, 0x100
	s_addc_u32 s35, s35, 0
	s_cmp_gt_u32 s43, 29
	s_waitcnt vmcnt(8) lgkmcnt(0)
	s_barrier
	v_mfma_f32_16x16x32_f16 v[62:65], v[130:133], v[162:165], v[62:65]
	v_mfma_f32_16x16x32_f16 v[58:61], v[148:151], v[162:165], v[58:61]
	v_mfma_f32_16x16x32_f16 v[46:49], v[130:133], v[170:173], v[46:49]
	v_mfma_f32_16x16x32_f16 v[42:45], v[148:151], v[170:173], v[42:45]
	v_mfma_f32_16x16x32_f16 v[30:33], v[130:133], v[178:181], v[30:33]
	v_mfma_f32_16x16x32_f16 v[26:29], v[148:151], v[178:181], v[26:29]
	v_mfma_f32_16x16x32_f16 v[14:17], v[130:133], v[186:189], v[14:17]
	v_mfma_f32_16x16x32_f16 v[10:13], v[148:151], v[186:189], v[10:13]
	v_mfma_f32_16x16x32_f16 v[62:65], v[134:137], v[166:169], v[62:65]
	v_mfma_f32_16x16x32_f16 v[58:61], v[158:161], v[166:169], v[58:61]
	v_mfma_f32_16x16x32_f16 v[46:49], v[134:137], v[174:177], v[46:49]
	v_mfma_f32_16x16x32_f16 v[42:45], v[158:161], v[174:177], v[42:45]
	v_mfma_f32_16x16x32_f16 v[30:33], v[134:137], v[182:185], v[30:33]
	v_mfma_f32_16x16x32_f16 v[26:29], v[158:161], v[182:185], v[26:29]
	v_mfma_f32_16x16x32_f16 v[14:17], v[134:137], v[190:193], v[14:17]
	v_mfma_f32_16x16x32_f16 v[10:13], v[158:161], v[190:193], v[10:13]
	v_mfma_f32_16x16x32_f16 v[54:57], v[194:197], v[162:165], v[54:57]
	v_mfma_f32_16x16x32_f16 v[50:53], v[202:205], v[162:165], v[50:53]
	v_mfma_f32_16x16x32_f16 v[38:41], v[194:197], v[170:173], v[38:41]
	v_mfma_f32_16x16x32_f16 v[34:37], v[202:205], v[170:173], v[34:37]
	v_mfma_f32_16x16x32_f16 v[22:25], v[194:197], v[178:181], v[22:25]
	v_mfma_f32_16x16x32_f16 v[18:21], v[202:205], v[178:181], v[18:21]
	v_mfma_f32_16x16x32_f16 v[6:9], v[194:197], v[186:189], v[6:9]
	v_mfma_f32_16x16x32_f16 v[2:5], v[202:205], v[186:189], v[2:5]
	v_mfma_f32_16x16x32_f16 v[54:57], v[198:201], v[166:169], v[54:57]
	v_mfma_f32_16x16x32_f16 v[50:53], v[220:223], v[166:169], v[50:53]
	v_mfma_f32_16x16x32_f16 v[38:41], v[198:201], v[174:177], v[38:41]
	v_mfma_f32_16x16x32_f16 v[34:37], v[220:223], v[174:177], v[34:37]
	v_mfma_f32_16x16x32_f16 v[22:25], v[198:201], v[182:185], v[22:25]
	v_mfma_f32_16x16x32_f16 v[18:21], v[220:223], v[182:185], v[18:21]
	v_mfma_f32_16x16x32_f16 v[6:9], v[198:201], v[190:193], v[6:9]
	v_mfma_f32_16x16x32_f16 v[2:5], v[220:223], v[190:193], v[2:5]
	s_barrier
	s_cbranch_scc1 .Lg4x_799
.LBB0_799:
	s_add_u32 s40, s0, 0xfff80080
	s_addc_u32 s41, s1, -1
	s_add_i32 s45, 0, 0x10000
	v_add_u32_e32 v152, s45, v155
	ds_read_b128 v[130:133], v152
	ds_read_b128 v[134:137], v152 offset:1024
	ds_read_b128 v[148:151], v152 offset:2048
	ds_read_b128 v[158:161], v152 offset:3072
	s_cmp_eq_u32 s43, 28
	s_cselect_b32 s49, s47, s41
	s_cselect_b32 s48, s46, s40
	s_cselect_b32 s41, s29, s35
	s_cselect_b32 s40, s20, s21
	v_lshl_add_u64 v[152:153], s[0:1], 0, v[144:145]
	s_add_i32 m0, s23, 0xc000
	ds_read_b128 v[162:165], v157
	ds_read_b128 v[166:169], v157 offset:1024
	ds_read_b128 v[170:173], v157 offset:2048
	ds_read_b128 v[174:177], v157 offset:3072
	ds_read_b128 v[178:181], v157 offset:4096
	ds_read_b128 v[182:185], v157 offset:5120
	ds_read_b128 v[186:189], v157 offset:6144
	ds_read_b128 v[190:193], v157 offset:7168
	global_load_lds_dwordx4 v[152:153], off
	v_lshl_add_u64 v[152:153], s[0:1], 0, v[146:147]
	s_add_i32 m0, s23, 0xe000
	s_nop 0
	global_load_lds_dwordx4 v[152:153], off
	s_waitcnt lgkmcnt(11)
	s_add_i32 s60, 0, 0x14000
	v_add_u32_e32 v152, s60, v155
	s_add_i32 s45, s45, s72
	ds_read_b128 v[194:197], v152
	ds_read_b128 v[198:201], v152 offset:1024
	ds_read_b128 v[202:205], v152 offset:2048
	ds_read_b128 v[220:223], v152 offset:3072
	s_waitcnt vmcnt(8) lgkmcnt(0)
	s_barrier
; #define PG8_STAGE(bufoff, gbase, voff) do { _Pragma("unroll") for (int _i = 0; _i < 2; ++_i) \
;         __builtin_amdgcn_global_load_lds((const unsigned*)((const char*)(gbase) + (voff)[_i]), (LAS unsigned*)(lds + (bufoff) + ldsw + _i * 8192), 16, 0, 0); } while (0)
; #define PG8_LDA(dst, b, h) do { _Pragma("unroll") for (int m = 0; m < 4; ++m) _Pragma("unroll") for (int k = 0; k < 2; ++k) dst[m][k] = *(const LAS h16x8*)(lds + PG8_SA(b, h) + aoff + m * 2048 + k * 1024); } while (0)
; #define PG8_LDB(dst, b, h) do { _Pragma("unroll") for (int n = 0; n < 2; ++n) _Pragma("unroll") for (int k = 0; k < 2; ++k) dst[n][k] = *(const LAS h16x8*)(lds + PG8_SB(b, h) + boff + n * 2048 + k * 1024); } while (0)
; #define PG8_MMA(ai, bj, At, Bt_) do { __builtin_amdgcn_s_setprio(1); _Pragma("unroll") for (int m = 0; m < 4; ++m) _Pragma("unroll") for (int n = 0; n < 2; ++n) _Pragma("unroll") for (int k = 0; k < 2; ++k) \
;         acc[ai][bj][m][n] = __builtin_amdgcn_mfma_f32_16x16x32_f16(Bt_[n][k], At[m][k], acc[ai][bj][m][n], 0, 0, 0); __builtin_amdgcn_s_setprio(0); } while (0)
; #define PG8_WAIT_V(n) asm volatile("s_waitcnt vmcnt(" #n ")" ::: "memory")
; #define PG8_WAIT_L(n) asm volatile("s_waitcnt lgkmcnt(" #n ")" ::: "memory")
; #define PG8_BAR __builtin_amdgcn_s_barrier()
; #define PG8_SCHED __builtin_amdgcn_sched_barrier(0)
; template <class Epi, class AMap>
; __device__ __forceinline__ void gemm_phase(LAS unsigned char* lds, const AMap am, const int lda, const h16* Bt, const int ldb, const int M, const int N, const int K, const Epi& E) {
;     ...
;             PG8_WAIT_L(8); PG8_BAR; PG8_WAIT_L(0); PG8_MMA(0, 0, At, B0); PG8_BAR; PG8_SCHED;
;             PG8_LDB(B1, 0, 1); PG8_STAGE(PG8_SB(0, 0), b2, voffB);
;             PG8_BAR; PG8_WAIT_L(0); PG8_MMA(0, 1, At, B1); PG8_BAR;
;             PG8_LDA(At, 0, 1); PG8_STAGE(PG8_SA(0, 0), a2, voffA);
;             PG8_BAR; PG8_WAIT_L(0); PG8_MMA(1, 0, At, B0); PG8_BAR; PG8_SCHED;
;             PG8_STAGE(PG8_SB(0, 1), b2 + hstepB, voffB);
;             PG8_WAIT_V(6); PG8_BAR; PG8_MMA(1, 1, At, B1); PG8_BAR;
;             PG8_LDB(B0, 1, 0); PG8_SCHED; PG8_LDA(At, 1, 0); PG8_STAGE(PG8_SA(0, 1), a2 + hstepA, voffA);
;             PG8_WAIT_L(8); PG8_BAR; PG8_WAIT_L(0); PG8_MMA(0, 0, At, B0); PG8_BAR; PG8_SCHED;
	v_mfma_f32_16x16x32_f16 v[126:129], v[130:133], v[162:165], v[126:129]
	v_mfma_f32_16x16x32_f16 v[122:125], v[148:151], v[162:165], v[122:125]
	v_mfma_f32_16x16x32_f16 v[110:113], v[130:133], v[170:173], v[110:113]
	v_mfma_f32_16x16x32_f16 v[106:109], v[148:151], v[170:173], v[106:109]
	v_mfma_f32_16x16x32_f16 v[94:97], v[130:133], v[178:181], v[94:97]
	v_mfma_f32_16x16x32_f16 v[90:93], v[148:151], v[178:181], v[90:93]
	v_mfma_f32_16x16x32_f16 v[78:81], v[130:133], v[186:189], v[78:81]
	v_mfma_f32_16x16x32_f16 v[74:77], v[148:151], v[186:189], v[74:77]
	v_mfma_f32_16x16x32_f16 v[126:129], v[134:137], v[166:169], v[126:129]
	v_mfma_f32_16x16x32_f16 v[122:125], v[158:161], v[166:169], v[122:125]
	v_mfma_f32_16x16x32_f16 v[110:113], v[134:137], v[174:177], v[110:113]
	v_mfma_f32_16x16x32_f16 v[106:109], v[158:161], v[174:177], v[106:109]
	v_mfma_f32_16x16x32_f16 v[94:97], v[134:137], v[182:185], v[94:97]
	v_mfma_f32_16x16x32_f16 v[90:93], v[158:161], v[182:185], v[90:93]
	v_mfma_f32_16x16x32_f16 v[78:81], v[134:137], v[190:193], v[78:81]
	v_mfma_f32_16x16x32_f16 v[74:77], v[158:161], v[190:193], v[74:77]
	v_mfma_f32_16x16x32_f16 v[118:121], v[194:197], v[162:165], v[118:121]
	v_mfma_f32_16x16x32_f16 v[114:117], v[202:205], v[162:165], v[114:117]
	v_mfma_f32_16x16x32_f16 v[102:105], v[194:197], v[170:173], v[102:105]
	v_mfma_f32_16x16x32_f16 v[98:101], v[202:205], v[170:173], v[98:101]
	v_mfma_f32_16x16x32_f16 v[86:89], v[194:197], v[178:181], v[86:89]
	v_mfma_f32_16x16x32_f16 v[82:85], v[202:205], v[178:181], v[82:85]
	v_mfma_f32_16x16x32_f16 v[70:73], v[194:197], v[186:189], v[70:73]
	v_mfma_f32_16x16x32_f16 v[66:69], v[202:205], v[186:189], v[66:69]
	v_mfma_f32_16x16x32_f16 v[118:121], v[198:201], v[166:169], v[118:121]
	v_mfma_f32_16x16x32_f16 v[114:117], v[220:223], v[166:169], v[114:117]
	v_mfma_f32_16x16x32_f16 v[102:105], v[198:201], v[174:177], v[102:105]
	v_mfma_f32_16x16x32_f16 v[98:101], v[220:223], v[174:177], v[98:101]
	v_mfma_f32_16x16x32_f16 v[86:89], v[198:201], v[182:185], v[86:89]
	v_mfma_f32_16x16x32_f16 v[82:85], v[220:223], v[182:185], v[82:85]
	v_mfma_f32_16x16x32_f16 v[70:73], v[198:201], v[190:193], v[70:73]
	v_mfma_f32_16x16x32_f16 v[66:69], v[220:223], v[190:193], v[66:69]
	s_barrier
	v_lshl_add_u64 v[152:153], s[40:41], 0, v[0:1]
	s_mov_b32 m0, s45
	v_lshl_add_u64 v[206:207], s[40:41], 0, v[142:143]
	global_load_lds_dwordx4 v[152:153], off
	s_add_i32 m0, s45, 0x2000
	s_nop 0
	global_load_lds_dwordx4 v[206:207], off
	s_mov_b32 m0, s23
	v_lshl_add_u64 v[212:213], s[48:49], 0, v[138:139]
	ds_read_b128 v[162:165], v157 offset:16384
	ds_read_b128 v[166:169], v157 offset:17408
	ds_read_b128 v[170:173], v157 offset:18432
	ds_read_b128 v[174:177], v157 offset:19456
	ds_read_b128 v[178:181], v157 offset:20480
	ds_read_b128 v[182:185], v157 offset:21504
	ds_read_b128 v[186:189], v157 offset:22528
	ds_read_b128 v[190:193], v157 offset:23552
	global_load_lds_dwordx4 v[212:213], off
	v_lshl_add_u64 v[224:225], s[48:49], 0, v[140:141]
	s_mov_b32 m0, s27
	s_nop 0
	global_load_lds_dwordx4 v[224:225], off
	s_add_u32 s50, s40, 0x80000
	s_addc_u32 s51, s41, 0
	s_add_i32 s45, s60, s72
	v_lshl_add_u64 v[232:233], s[50:51], 0, v[0:1]
	s_mov_b32 m0, s45
	s_nop 0
	global_load_lds_dwordx4 v[232:233], off
	v_lshl_add_u64 v[232:233], s[50:51], 0, v[142:143]
	s_add_i32 m0, s45, 0x2000
	s_nop 0
	global_load_lds_dwordx4 v[232:233], off
	s_waitcnt vmcnt(8) lgkmcnt(0)
	s_barrier
	v_mfma_f32_16x16x32_f16 v[62:65], v[130:133], v[162:165], v[62:65]
	v_mfma_f32_16x16x32_f16 v[58:61], v[148:151], v[162:165], v[58:61]
	v_mfma_f32_16x16x32_f16 v[46:49], v[130:133], v[170:173], v[46:49]
	v_mfma_f32_16x16x32_f16 v[42:45], v[148:151], v[170:173], v[42:45]
	v_mfma_f32_16x16x32_f16 v[30:33], v[130:133], v[178:181], v[30:33]
	v_mfma_f32_16x16x32_f16 v[26:29], v[148:151], v[178:181], v[26:29]
	v_mfma_f32_16x16x32_f16 v[14:17], v[130:133], v[186:189], v[14:17]
	v_mfma_f32_16x16x32_f16 v[10:13], v[148:151], v[186:189], v[10:13]
	v_mfma_f32_16x16x32_f16 v[62:65], v[134:137], v[166:169], v[62:65]
	v_mfma_f32_16x16x32_f16 v[58:61], v[158:161], v[166:169], v[58:61]
	v_mfma_f32_16x16x32_f16 v[46:49], v[134:137], v[174:177], v[46:49]
	v_mfma_f32_16x16x32_f16 v[42:45], v[158:161], v[174:177], v[42:45]
	v_mfma_f32_16x16x32_f16 v[30:33], v[134:137], v[182:185], v[30:33]
	v_mfma_f32_16x16x32_f16 v[26:29], v[158:161], v[182:185], v[26:29]
	v_mfma_f32_16x16x32_f16 v[14:17], v[134:137], v[190:193], v[14:17]
	v_mfma_f32_16x16x32_f16 v[10:13], v[158:161], v[190:193], v[10:13]
	v_mfma_f32_16x16x32_f16 v[54:57], v[194:197], v[162:165], v[54:57]
	v_mfma_f32_16x16x32_f16 v[50:53], v[202:205], v[162:165], v[50:53]
	v_mfma_f32_16x16x32_f16 v[38:41], v[194:197], v[170:173], v[38:41]
	v_mfma_f32_16x16x32_f16 v[34:37], v[202:205], v[170:173], v[34:37]
	v_mfma_f32_16x16x32_f16 v[22:25], v[194:197], v[178:181], v[22:25]
	v_mfma_f32_16x16x32_f16 v[18:21], v[202:205], v[178:181], v[18:21]
	v_mfma_f32_16x16x32_f16 v[6:9], v[194:197], v[186:189], v[6:9]
	v_mfma_f32_16x16x32_f16 v[2:5], v[202:205], v[186:189], v[2:5]
	v_mfma_f32_16x16x32_f16 v[54:57], v[198:201], v[166:169], v[54:57]
	v_mfma_f32_16x16x32_f16 v[50:53], v[220:223], v[166:169], v[50:53]
	v_mfma_f32_16x16x32_f16 v[38:41], v[198:201], v[174:177], v[38:41]
	v_mfma_f32_16x16x32_f16 v[34:37], v[220:223], v[174:177], v[34:37]
	v_mfma_f32_16x16x32_f16 v[22:25], v[198:201], v[182:185], v[22:25]
	v_mfma_f32_16x16x32_f16 v[18:21], v[220:223], v[182:185], v[18:21]
	v_mfma_f32_16x16x32_f16 v[6:9], v[198:201], v[190:193], v[6:9]
	v_mfma_f32_16x16x32_f16 v[2:5], v[220:223], v[190:193], v[2:5]
	s_barrier
; #define PG8_STAGE(bufoff, gbase, voff) do { _Pragma("unroll") for (int _i = 0; _i < 2; ++_i) \
;         __builtin_amdgcn_global_load_lds((const unsigned*)((const char*)(gbase) + (voff)[_i]), (LAS unsigned*)(lds + (bufoff) + ldsw + _i * 8192), 16, 0, 0); } while (0)
; #define PG8_LDA(dst, b, h) do { _Pragma("unroll") for (int m = 0; m < 4; ++m) _Pragma("unroll") for (int k = 0; k < 2; ++k) dst[m][k] = *(const LAS h16x8*)(lds + PG8_SA(b, h) + aoff + m * 2048 + k * 1024); } while (0)
; #define PG8_LDB(dst, b, h) do { _Pragma("unroll") for (int n = 0; n < 2; ++n) _Pragma("unroll") for (int k = 0; k < 2; ++k) dst[n][k] = *(const LAS h16x8*)(lds + PG8_SB(b, h) + boff + n * 2048 + k * 1024); } while (0)
; #define PG8_MMA(ai, bj, At, Bt_) do { __builtin_amdgcn_s_setprio(1); _Pragma("unroll") for (int m = 0; m < 4; ++m) _Pragma("unroll") for (int n = 0; n < 2; ++n) _Pragma("unroll") for (int k = 0; k < 2; ++k) \
;         acc[ai][bj][m][n] = __builtin_amdgcn_mfma_f32_16x16x32_f16(Bt_[n][k], At[m][k], acc[ai][bj][m][n], 0, 0, 0); __builtin_amdgcn_s_setprio(0); } while (0)
; #define PG8_WAIT_V(n) asm volatile("s_waitcnt vmcnt(" #n ")" ::: "memory")
; #define PG8_WAIT_L(n) asm volatile("s_waitcnt lgkmcnt(" #n ")" ::: "memory")
; #define PG8_BAR __builtin_amdgcn_s_barrier()
; #define PG8_SCHED __builtin_amdgcn_sched_barrier(0)
; template <class Epi, class AMap>
; __device__ __forceinline__ void gemm_phase(LAS unsigned char* lds, const AMap am, const int lda, const h16* Bt, const int ldb, const int M, const int N, const int K, const Epi& E) {
;     ...
;             PG8_LDB(B0, 1, 0); PG8_SCHED; PG8_LDA(At, 1, 0); PG8_STAGE(PG8_SA(0, 1), a2 + hstepA, voffA);
;             PG8_WAIT_L(8); PG8_BAR; PG8_WAIT_L(0); PG8_MMA(0, 0, At, B0); PG8_BAR; PG8_SCHED;
;             PG8_LDB(B1, 1, 1); PG8_STAGE(PG8_SB(1, 0), b3, voffB);
;             PG8_BAR; PG8_WAIT_L(0); PG8_MMA(0, 1, At, B1); PG8_BAR;
;             PG8_LDA(At, 1, 1); PG8_STAGE(PG8_SA(1, 0), a3, voffA);
;             PG8_BAR; PG8_WAIT_L(0); PG8_MMA(1, 0, At, B0); PG8_BAR; PG8_SCHED;
;             PG8_STAGE(PG8_SB(1, 1), b3 + hstepB, voffB);
;             PG8_WAIT_V(6); PG8_BAR; PG8_MMA(1, 1, At, B1); PG8_BAR;
;         }
	s_add_i32 s45, 0, 0x18000
	v_add_u32_e32 v234, s45, v155
	ds_read_b128 v[130:133], v234
	ds_read_b128 v[134:137], v234 offset:1024
	ds_read_b128 v[148:151], v234 offset:2048
	ds_read_b128 v[158:161], v234 offset:3072
	s_add_u32 s48, s48, 0x80000
	s_addc_u32 s49, s49, 0
	s_mov_b32 m0, s73
	v_lshl_add_u64 v[232:233], s[48:49], 0, v[138:139]
	ds_read_b128 v[162:165], v157 offset:32768
	ds_read_b128 v[166:169], v157 offset:33792
	ds_read_b128 v[170:173], v157 offset:34816
	ds_read_b128 v[174:177], v157 offset:35840
	ds_read_b128 v[178:181], v157 offset:36864
	ds_read_b128 v[182:185], v157 offset:37888
	ds_read_b128 v[186:189], v157 offset:38912
	ds_read_b128 v[190:193], v157 offset:39936
	global_load_lds_dwordx4 v[232:233], off
	v_lshl_add_u64 v[232:233], s[48:49], 0, v[140:141]
	s_mov_b32 m0, s74
	s_nop 0
	global_load_lds_dwordx4 v[232:233], off
	s_waitcnt lgkmcnt(11)
	s_add_i32 s48, 0, 0x1c000
	s_add_i32 s45, s45, s72
	v_add_u32_e32 v214, s48, v155
	v_lshl_add_u64 v[152:153], v[152:153], 0, s[92:93]
	s_mov_b32 m0, s45
	ds_read_b128 v[194:197], v214
	ds_read_b128 v[198:201], v214 offset:1024
	ds_read_b128 v[202:205], v214 offset:2048
	ds_read_b128 v[220:223], v214 offset:3072
	s_waitcnt vmcnt(8) lgkmcnt(0)
	s_barrier
	v_mfma_f32_16x16x32_f16 v[126:129], v[130:133], v[162:165], v[126:129]
	v_mfma_f32_16x16x32_f16 v[122:125], v[148:151], v[162:165], v[122:125]
	v_mfma_f32_16x16x32_f16 v[110:113], v[130:133], v[170:173], v[110:113]
	v_mfma_f32_16x16x32_f16 v[106:109], v[148:151], v[170:173], v[106:109]
	v_mfma_f32_16x16x32_f16 v[94:97], v[130:133], v[178:181], v[94:97]
	v_mfma_f32_16x16x32_f16 v[90:93], v[148:151], v[178:181], v[90:93]
	v_mfma_f32_16x16x32_f16 v[78:81], v[130:133], v[186:189], v[78:81]
	v_mfma_f32_16x16x32_f16 v[74:77], v[148:151], v[186:189], v[74:77]
	v_mfma_f32_16x16x32_f16 v[126:129], v[134:137], v[166:169], v[126:129]
	v_mfma_f32_16x16x32_f16 v[122:125], v[158:161], v[166:169], v[122:125]
	v_mfma_f32_16x16x32_f16 v[110:113], v[134:137], v[174:177], v[110:113]
	v_mfma_f32_16x16x32_f16 v[106:109], v[158:161], v[174:177], v[106:109]
	v_mfma_f32_16x16x32_f16 v[94:97], v[134:137], v[182:185], v[94:97]
	v_mfma_f32_16x16x32_f16 v[90:93], v[158:161], v[182:185], v[90:93]
	v_mfma_f32_16x16x32_f16 v[78:81], v[134:137], v[190:193], v[78:81]
	v_mfma_f32_16x16x32_f16 v[74:77], v[158:161], v[190:193], v[74:77]
	v_mfma_f32_16x16x32_f16 v[118:121], v[194:197], v[162:165], v[118:121]
	v_mfma_f32_16x16x32_f16 v[114:117], v[202:205], v[162:165], v[114:117]
	v_mfma_f32_16x16x32_f16 v[102:105], v[194:197], v[170:173], v[102:105]
	v_mfma_f32_16x16x32_f16 v[98:101], v[202:205], v[170:173], v[98:101]
	v_mfma_f32_16x16x32_f16 v[86:89], v[194:197], v[178:181], v[86:89]
	v_mfma_f32_16x16x32_f16 v[82:85], v[202:205], v[178:181], v[82:85]
	v_mfma_f32_16x16x32_f16 v[70:73], v[194:197], v[186:189], v[70:73]
	v_mfma_f32_16x16x32_f16 v[66:69], v[202:205], v[186:189], v[66:69]
	v_mfma_f32_16x16x32_f16 v[118:121], v[198:201], v[166:169], v[118:121]
	v_mfma_f32_16x16x32_f16 v[114:117], v[220:223], v[166:169], v[114:117]
	v_mfma_f32_16x16x32_f16 v[102:105], v[198:201], v[174:177], v[102:105]
	v_mfma_f32_16x16x32_f16 v[98:101], v[220:223], v[174:177], v[98:101]
	v_mfma_f32_16x16x32_f16 v[86:89], v[198:201], v[182:185], v[86:89]
	v_mfma_f32_16x16x32_f16 v[82:85], v[220:223], v[182:185], v[82:85]
	v_mfma_f32_16x16x32_f16 v[70:73], v[198:201], v[190:193], v[70:73]
	v_mfma_f32_16x16x32_f16 v[66:69], v[220:223], v[190:193], v[66:69]
	s_barrier
	global_load_lds_dwordx4 v[152:153], off
	v_lshl_add_u64 v[152:153], v[206:207], 0, s[92:93]
	s_add_i32 m0, s45, 0x2000
	s_nop 0
	global_load_lds_dwordx4 v[152:153], off
	s_mov_b32 m0, s75
	v_lshl_add_u64 v[152:153], v[212:213], 0, s[92:93]
	ds_read_b128 v[162:165], v157 offset:49152
	ds_read_b128 v[166:169], v157 offset:50176
	ds_read_b128 v[170:173], v157 offset:51200
	ds_read_b128 v[174:177], v157 offset:52224
	ds_read_b128 v[178:181], v157 offset:53248
	ds_read_b128 v[182:185], v157 offset:54272
	ds_read_b128 v[186:189], v157 offset:55296
	ds_read_b128 v[190:193], v157 offset:56320
	global_load_lds_dwordx4 v[152:153], off
	v_lshl_add_u64 v[152:153], v[224:225], 0, s[92:93]
	s_mov_b32 m0, s76
	s_nop 0
	global_load_lds_dwordx4 v[152:153], off
	s_add_u32 s40, s40, 0x80080
	s_addc_u32 s41, s41, 0
	s_add_i32 s45, s48, s72
	v_lshl_add_u64 v[232:233], s[40:41], 0, v[0:1]
	s_mov_b32 m0, s45
	s_nop 0
	global_load_lds_dwordx4 v[232:233], off
	v_lshl_add_u64 v[232:233], s[40:41], 0, v[142:143]
	s_add_i32 m0, s45, 0x2000
	s_nop 0
	global_load_lds_dwordx4 v[232:233], off
	s_add_i32 s43, s43, 2
	s_add_u32 s0, s0, 0x100
	s_addc_u32 s1, s1, 0
	s_add_u32 s21, s21, 0x100
	s_addc_u32 s35, s35, 0
	s_cmp_gt_u32 s43, 29
	s_waitcnt vmcnt(8) lgkmcnt(0)
	s_barrier
	v_mfma_f32_16x16x32_f16 v[62:65], v[130:133], v[162:165], v[62:65]
	v_mfma_f32_16x16x32_f16 v[58:61], v[148:151], v[162:165], v[58:61]
	v_mfma_f32_16x16x32_f16 v[46:49], v[130:133], v[170:173], v[46:49]
	v_mfma_f32_16x16x32_f16 v[42:45], v[148:151], v[170:173], v[42:45]
	v_mfma_f32_16x16x32_f16 v[30:33], v[130:133], v[178:181], v[30:33]
	v_mfma_f32_16x16x32_f16 v[26:29], v[148:151], v[178:181], v[26:29]
	v_mfma_f32_16x16x32_f16 v[14:17], v[130:133], v[186:189], v[14:17]
	v_mfma_f32_16x16x32_f16 v[10:13], v[148:151], v[186:189], v[10:13]
	v_mfma_f32_16x16x32_f16 v[62:65], v[134:137], v[166:169], v[62:65]
	v_mfma_f32_16x16x32_f16 v[58:61], v[158:161], v[166:169], v[58:61]
	v_mfma_f32_16x16x32_f16 v[46:49], v[134:137], v[174:177], v[46:49]
	v_mfma_f32_16x16x32_f16 v[42:45], v[158:161], v[174:177], v[42:45]
	v_mfma_f32_16x16x32_f16 v[30:33], v[134:137], v[182:185], v[30:33]
	v_mfma_f32_16x16x32_f16 v[26:29], v[158:161], v[182:185], v[26:29]
	v_mfma_f32_16x16x32_f16 v[14:17], v[134:137], v[190:193], v[14:17]
	v_mfma_f32_16x16x32_f16 v[10:13], v[158:161], v[190:193], v[10:13]
	v_mfma_f32_16x16x32_f16 v[54:57], v[194:197], v[162:165], v[54:57]
	v_mfma_f32_16x16x32_f16 v[50:53], v[202:205], v[162:165], v[50:53]
	v_mfma_f32_16x16x32_f16 v[38:41], v[194:197], v[170:173], v[38:41]
	v_mfma_f32_16x16x32_f16 v[34:37], v[202:205], v[170:173], v[34:37]
	v_mfma_f32_16x16x32_f16 v[22:25], v[194:197], v[178:181], v[22:25]
	v_mfma_f32_16x16x32_f16 v[18:21], v[202:205], v[178:181], v[18:21]
	v_mfma_f32_16x16x32_f16 v[6:9], v[194:197], v[186:189], v[6:9]
	v_mfma_f32_16x16x32_f16 v[2:5], v[202:205], v[186:189], v[2:5]
	v_mfma_f32_16x16x32_f16 v[54:57], v[198:201], v[166:169], v[54:57]
	v_mfma_f32_16x16x32_f16 v[50:53], v[220:223], v[166:169], v[50:53]
	v_mfma_f32_16x16x32_f16 v[38:41], v[198:201], v[174:177], v[38:41]
	v_mfma_f32_16x16x32_f16 v[34:37], v[220:223], v[174:177], v[34:37]
	v_mfma_f32_16x16x32_f16 v[22:25], v[198:201], v[182:185], v[22:25]
	v_mfma_f32_16x16x32_f16 v[18:21], v[220:223], v[182:185], v[18:21]
	v_mfma_f32_16x16x32_f16 v[6:9], v[198:201], v[190:193], v[6:9]
	v_mfma_f32_16x16x32_f16 v[2:5], v[220:223], v[190:193], v[2:5]
	s_barrier
	s_cbranch_scc0 .LBB0_799
.Lg4x_799:
	s_cmpk_gt_u32 s71, 0xff
	s_cbranch_scc1 .Lgx8
	s_barrier
